# early2 with tail priority 2, plus partner wave raises priority before parking at the barrier and skips the redundant lgkmcnt(0) after it
# speedup vs baseline: 1.0124x; 1.0064x over previous
; #define PG8_STAGE(bufoff, gbase, voff) do { _Pragma("unroll") for (int _i = 0; _i < 2; ++_i) \
;         __builtin_amdgcn_global_load_lds((const unsigned*)((const char*)(gbase) + (voff)[_i]), (PG8_LAS unsigned*)(lds + (bufoff) + ldsw + _i * 8192), 16, 0, 0); } while (0)
; #define PG8_LDA(dst, b, h) do { _Pragma("unroll") for (int m = 0; m < 4; ++m) _Pragma("unroll") for (int k = 0; k < 2; ++k) dst[m][k] = *(const PG8_LAS bf16x8*)(lds + PG8_SA(b, h) + aoff + m * 2048 + k * 1024); } while (0)
; #define PG8_LDB(dst, b, h) do { _Pragma("unroll") for (int n = 0; n < 2; ++n) _Pragma("unroll") for (int k = 0; k < 2; ++k) dst[n][k] = *(const PG8_LAS bf16x8*)(lds + PG8_SB(b, h) + boff + n * 2048 + k * 1024); } while (0)
; #define PG8_MMA(ai, bj, At, Bt) do { __builtin_amdgcn_s_setprio(1); _Pragma("unroll") for (int m = 0; m < 4; ++m) _Pragma("unroll") for (int n = 0; n < 2; ++n) _Pragma("unroll") for (int k = 0; k < 2; ++k) \
;         acc[ai][bj][m][n] = __builtin_amdgcn_mfma_f32_16x16x32_bf16(Bt[n][k], At[m][k], acc[ai][bj][m][n], 0, 0, 0); __builtin_amdgcn_s_setprio(0); } while (0)
; #define PG8_WAIT_V(n) asm volatile("s_waitcnt vmcnt(" #n ")" ::: "memory")
; #define PG8_WAIT_L(n) asm volatile("s_waitcnt lgkmcnt(" #n ")" ::: "memory")
; #define PG8_BAR __builtin_amdgcn_s_barrier()
; template <class Epi, class Sched, bool ALIGN_EPI = false, bool SP2 = false>
; __device__ __forceinline__ void gemm_phase(PG8_LAS unsigned char* lds, const Gemm g, const Sched& S, const Epi& E) {
;     ...
;             const bool last = (t == nt - 2);
;             const char* a1 = cA + (size_t)(t + 1) * kstep;
;             const char* a2 = last ? nA : cA + (size_t)(t + 2) * kstep; const char* b2 = last ? nB : cB + (size_t)(t + 2) * kstep;
;             const char* a3 = a2 + kstep; const char* b3 = b2 + kstep;
;             if constexpr (SP2) {
;             PG8_LDB(B0, 0, 0); PG8_LDB(B1, 0, 1); PG8_SCHED; PG8_LDA(At, 0, 0); PG8_STAGE(PG8_SA(1, 1), a1 + hstep, voffA);
;             PG8_WAIT_V(8); PG8_WAIT_L(0); PG8_BAR; PG8_MMA(0, 0, At, B0); PG8_MMA(0, 1, At, B1); PG8_BAR; PG8_SCHED;
;             PG8_LDA(At, 0, 1); PG8_STAGE(PG8_SB(0, 0), b2, voffB); PG8_STAGE(PG8_SB(0, 1), b2 + hstep, voffB); PG8_STAGE(PG8_SA(0, 0), a2, voffA);
;             PG8_WAIT_V(8); PG8_WAIT_L(0); PG8_BAR; PG8_MMA(1, 0, At, B0); PG8_MMA(1, 1, At, B1); PG8_BAR; PG8_SCHED;
.LBB0_200:
	ds_read_b128 v[148:151], v164
	ds_read_b128 v[152:155], v164 offset:1024
	ds_read_b128 v[156:159], v164 offset:2048
	ds_read_b128 v[168:171], v164 offset:3072
	ds_read_b128 v[172:175], v165
	ds_read_b128 v[176:179], v165 offset:1024
	ds_read_b128 v[180:183], v165 offset:2048
	ds_read_b128 v[184:187], v165 offset:3072
	s_add_u32 s52, s70, 0xfff80080
	s_addc_u32 s53, s71, -1
	s_cmp_eq_u32 s93, 28
	s_cselect_b32 s75, s39, s53
	s_cselect_b32 s74, s69, s52
	s_cselect_b32 s73, s35, s92
	s_cselect_b32 s72, s90, s91
	v_lshl_add_u64 v[220:221], s[70:71], 0, v[138:139]
	s_add_i32 m0, s33, 0xc000
	ds_read_b128 v[188:191], v166
	ds_read_b128 v[192:195], v166 offset:1024
	ds_read_b128 v[196:199], v166 offset:2048
	ds_read_b128 v[200:203], v166 offset:3072
	ds_read_b128 v[204:207], v166 offset:4096
	ds_read_b128 v[208:211], v166 offset:5120
	ds_read_b128 v[212:215], v166 offset:6144
	ds_read_b128 v[216:219], v166 offset:7168
	global_load_lds_dwordx4 v[220:221], off
	v_lshl_add_u64 v[220:221], s[70:71], 0, v[140:141]
	s_add_i32 m0, s33, 0xe000
	s_nop 0
	global_load_lds_dwordx4 v[220:221], off
	s_waitcnt vmcnt(8)
	s_waitcnt lgkmcnt(0)
	s_setprio 1
	s_barrier
	v_mfma_f32_16x16x32_bf16 v[124:127], v[148:151], v[188:191], v[124:127]
	v_mfma_f32_16x16x32_bf16 v[120:123], v[156:159], v[188:191], v[120:123]
	v_mfma_f32_16x16x32_bf16 v[116:119], v[148:151], v[196:199], v[116:119]
	v_mfma_f32_16x16x32_bf16 v[108:111], v[156:159], v[196:199], v[108:111]
	v_mfma_f32_16x16x32_bf16 v[100:103], v[148:151], v[204:207], v[100:103]
	v_mfma_f32_16x16x32_bf16 v[92:95], v[156:159], v[204:207], v[92:95]
	v_mfma_f32_16x16x32_bf16 v[84:87], v[148:151], v[212:215], v[84:87]
	v_mfma_f32_16x16x32_bf16 v[76:79], v[156:159], v[212:215], v[76:79]
	v_mfma_f32_16x16x32_bf16 v[124:127], v[152:155], v[192:195], v[124:127]
	v_mfma_f32_16x16x32_bf16 v[120:123], v[168:171], v[192:195], v[120:123]
	v_mfma_f32_16x16x32_bf16 v[116:119], v[152:155], v[200:203], v[116:119]
	v_mfma_f32_16x16x32_bf16 v[108:111], v[168:171], v[200:203], v[108:111]
	v_mfma_f32_16x16x32_bf16 v[100:103], v[152:155], v[208:211], v[100:103]
	v_mfma_f32_16x16x32_bf16 v[92:95], v[168:171], v[208:211], v[92:95]
	v_mfma_f32_16x16x32_bf16 v[84:87], v[152:155], v[216:219], v[84:87]
	v_mfma_f32_16x16x32_bf16 v[76:79], v[168:171], v[216:219], v[76:79]
	s_setprio 0
	s_setprio 1
	v_mfma_f32_16x16x32_bf16 v[112:115], v[172:175], v[188:191], v[112:115]
	v_mfma_f32_16x16x32_bf16 v[104:107], v[180:183], v[188:191], v[104:107]
	v_mfma_f32_16x16x32_bf16 v[96:99], v[172:175], v[196:199], v[96:99]
	v_mfma_f32_16x16x32_bf16 v[88:91], v[180:183], v[196:199], v[88:91]
	v_mfma_f32_16x16x32_bf16 v[80:83], v[172:175], v[204:207], v[80:83]
	v_mfma_f32_16x16x32_bf16 v[72:75], v[180:183], v[204:207], v[72:75]
	v_mfma_f32_16x16x32_bf16 v[68:71], v[172:175], v[212:215], v[68:71]
	v_mfma_f32_16x16x32_bf16 v[64:67], v[180:183], v[212:215], v[64:67]
	v_mfma_f32_16x16x32_bf16 v[112:115], v[176:179], v[192:195], v[112:115]
	v_mfma_f32_16x16x32_bf16 v[104:107], v[184:187], v[192:195], v[104:107]
	v_mfma_f32_16x16x32_bf16 v[96:99], v[176:179], v[200:203], v[96:99]
	v_mfma_f32_16x16x32_bf16 v[88:91], v[184:187], v[200:203], v[88:91]
	v_mfma_f32_16x16x32_bf16 v[80:83], v[176:179], v[208:211], v[80:83]
	v_mfma_f32_16x16x32_bf16 v[72:75], v[184:187], v[208:211], v[72:75]
	s_setprio 2
	s_barrier
	v_mfma_f32_16x16x32_bf16 v[68:71], v[176:179], v[216:219], v[68:71]
	v_mfma_f32_16x16x32_bf16 v[64:67], v[184:187], v[216:219], v[64:67]
	s_setprio 0
	s_add_i32 s52, s84, s3
	v_lshl_add_u64 v[220:221], s[72:73], 0, v[132:133]
	s_mov_b32 m0, s52
	ds_read_b128 v[188:191], v166 offset:16384
	ds_read_b128 v[192:195], v166 offset:17408
	ds_read_b128 v[196:199], v166 offset:18432
	ds_read_b128 v[200:203], v166 offset:19456
	ds_read_b128 v[204:207], v166 offset:20480
	ds_read_b128 v[208:211], v166 offset:21504
	ds_read_b128 v[212:215], v166 offset:22528
	ds_read_b128 v[216:219], v166 offset:23552
	global_load_lds_dwordx4 v[220:221], off
	s_add_i32 m0, s52, 0x2000
	s_add_u32 s96, s72, 0x80000
	v_lshl_add_u64 v[222:223], s[72:73], 0, v[128:129]
	s_addc_u32 s97, s73, 0
	s_add_i32 s52, s85, s3
	global_load_lds_dwordx4 v[222:223], off
	v_lshl_add_u64 v[224:225], s[96:97], 0, v[132:133]
	s_mov_b32 m0, s52
	v_lshl_add_u64 v[226:227], s[74:75], 0, v[130:131]
	global_load_lds_dwordx4 v[224:225], off
	v_lshl_add_u64 v[224:225], s[96:97], 0, v[128:129]
	s_add_i32 m0, s52, 0x2000
	s_nop 0
	global_load_lds_dwordx4 v[224:225], off
	v_lshl_add_u64 v[224:225], s[74:75], 0, v[134:135]
	s_mov_b32 m0, s33
	s_nop 0
	global_load_lds_dwordx4 v[224:225], off
	s_mov_b32 m0, s76
	s_nop 0
	global_load_lds_dwordx4 v[226:227], off
	s_waitcnt vmcnt(8)
	s_waitcnt lgkmcnt(0)
	s_setprio 1
	s_barrier
; #define PG8_STAGE(bufoff, gbase, voff) do { _Pragma("unroll") for (int _i = 0; _i < 2; ++_i) \
;         __builtin_amdgcn_global_load_lds((const unsigned*)((const char*)(gbase) + (voff)[_i]), (PG8_LAS unsigned*)(lds + (bufoff) + ldsw + _i * 8192), 16, 0, 0); } while (0)
; #define PG8_LDA(dst, b, h) do { _Pragma("unroll") for (int m = 0; m < 4; ++m) _Pragma("unroll") for (int k = 0; k < 2; ++k) dst[m][k] = *(const PG8_LAS bf16x8*)(lds + PG8_SA(b, h) + aoff + m * 2048 + k * 1024); } while (0)
; #define PG8_LDB(dst, b, h) do { _Pragma("unroll") for (int n = 0; n < 2; ++n) _Pragma("unroll") for (int k = 0; k < 2; ++k) dst[n][k] = *(const PG8_LAS bf16x8*)(lds + PG8_SB(b, h) + boff + n * 2048 + k * 1024); } while (0)
; #define PG8_MMA(ai, bj, At, Bt) do { __builtin_amdgcn_s_setprio(1); _Pragma("unroll") for (int m = 0; m < 4; ++m) _Pragma("unroll") for (int n = 0; n < 2; ++n) _Pragma("unroll") for (int k = 0; k < 2; ++k) \
;         acc[ai][bj][m][n] = __builtin_amdgcn_mfma_f32_16x16x32_bf16(Bt[n][k], At[m][k], acc[ai][bj][m][n], 0, 0, 0); __builtin_amdgcn_s_setprio(0); } while (0)
; #define PG8_WAIT_V(n) asm volatile("s_waitcnt vmcnt(" #n ")" ::: "memory")
; #define PG8_WAIT_L(n) asm volatile("s_waitcnt lgkmcnt(" #n ")" ::: "memory")
; #define PG8_BAR __builtin_amdgcn_s_barrier()
; #define PG8_SCHED __builtin_amdgcn_sched_barrier(0)
; template <class Epi, class Sched, bool ALIGN_EPI = false, bool SP2 = false>
; __device__ __forceinline__ void gemm_phase(PG8_LAS unsigned char* lds, const Gemm g, const Sched& S, const Epi& E) {
;     ...
;             PG8_WAIT_V(8); PG8_WAIT_L(0); PG8_BAR; PG8_MMA(1, 0, At, B0); PG8_MMA(1, 1, At, B1); PG8_BAR; PG8_SCHED;
;             PG8_LDB(B0, 1, 0); PG8_LDB(B1, 1, 1); PG8_SCHED; PG8_LDA(At, 1, 0); PG8_STAGE(PG8_SA(0, 1), a2 + hstep, voffA);
;             PG8_WAIT_V(8); PG8_WAIT_L(0); PG8_BAR; PG8_MMA(0, 0, At, B0); PG8_MMA(0, 1, At, B1); PG8_BAR; PG8_SCHED;
	v_mfma_f32_16x16x32_bf16 v[60:63], v[148:151], v[188:191], v[60:63]
	v_mfma_f32_16x16x32_bf16 v[56:59], v[156:159], v[188:191], v[56:59]
	v_mfma_f32_16x16x32_bf16 v[52:55], v[148:151], v[196:199], v[52:55]
	v_mfma_f32_16x16x32_bf16 v[44:47], v[156:159], v[196:199], v[44:47]
	v_mfma_f32_16x16x32_bf16 v[36:39], v[148:151], v[204:207], v[36:39]
	v_mfma_f32_16x16x32_bf16 v[28:31], v[156:159], v[204:207], v[28:31]
	v_mfma_f32_16x16x32_bf16 v[20:23], v[148:151], v[212:215], v[20:23]
	v_mfma_f32_16x16x32_bf16 v[12:15], v[156:159], v[212:215], v[12:15]
	v_mfma_f32_16x16x32_bf16 v[60:63], v[152:155], v[192:195], v[60:63]
	v_mfma_f32_16x16x32_bf16 v[56:59], v[168:171], v[192:195], v[56:59]
	v_mfma_f32_16x16x32_bf16 v[52:55], v[152:155], v[200:203], v[52:55]
	v_mfma_f32_16x16x32_bf16 v[44:47], v[168:171], v[200:203], v[44:47]
	v_mfma_f32_16x16x32_bf16 v[36:39], v[152:155], v[208:211], v[36:39]
	v_mfma_f32_16x16x32_bf16 v[28:31], v[168:171], v[208:211], v[28:31]
	v_mfma_f32_16x16x32_bf16 v[20:23], v[152:155], v[216:219], v[20:23]
	v_mfma_f32_16x16x32_bf16 v[12:15], v[168:171], v[216:219], v[12:15]
	s_setprio 0
	s_setprio 1
	v_mfma_f32_16x16x32_bf16 v[48:51], v[172:175], v[188:191], v[48:51]
	v_mfma_f32_16x16x32_bf16 v[40:43], v[180:183], v[188:191], v[40:43]
	v_mfma_f32_16x16x32_bf16 v[32:35], v[172:175], v[196:199], v[32:35]
	v_mfma_f32_16x16x32_bf16 v[24:27], v[180:183], v[196:199], v[24:27]
	v_mfma_f32_16x16x32_bf16 v[16:19], v[172:175], v[204:207], v[16:19]
	v_mfma_f32_16x16x32_bf16 v[8:11], v[180:183], v[204:207], v[8:11]
	v_mfma_f32_16x16x32_bf16 v[4:7], v[172:175], v[212:215], v[4:7]
	v_mfma_f32_16x16x32_bf16 v[0:3], v[180:183], v[212:215], v[0:3]
	v_mfma_f32_16x16x32_bf16 v[48:51], v[176:179], v[192:195], v[48:51]
	v_mfma_f32_16x16x32_bf16 v[40:43], v[184:187], v[192:195], v[40:43]
	v_mfma_f32_16x16x32_bf16 v[32:35], v[176:179], v[200:203], v[32:35]
	v_mfma_f32_16x16x32_bf16 v[24:27], v[184:187], v[200:203], v[24:27]
	v_mfma_f32_16x16x32_bf16 v[16:19], v[176:179], v[208:211], v[16:19]
	v_mfma_f32_16x16x32_bf16 v[8:11], v[184:187], v[208:211], v[8:11]
	s_setprio 2
	s_barrier
	v_mfma_f32_16x16x32_bf16 v[4:7], v[176:179], v[216:219], v[4:7]
	v_mfma_f32_16x16x32_bf16 v[0:3], v[184:187], v[216:219], v[0:3]
	s_setprio 0
	s_add_i32 s52, 0, 0x18000
	v_add_u32_e32 v136, s52, v161
	s_add_i32 s53, 0, 0x1c000
	ds_read_b128 v[148:151], v136
	ds_read_b128 v[152:155], v136 offset:1024
	ds_read_b128 v[156:159], v136 offset:2048
	ds_read_b128 v[168:171], v136 offset:3072
	v_add_u32_e32 v136, s53, v161
	ds_read_b128 v[172:175], v136
	ds_read_b128 v[176:179], v136 offset:1024
	ds_read_b128 v[180:183], v136 offset:2048
	ds_read_b128 v[184:187], v136 offset:3072
	s_add_u32 s74, s74, 0x80000
	s_addc_u32 s75, s75, 0
	s_mov_b32 m0, s77
	v_lshl_add_u64 v[228:229], s[74:75], 0, v[134:135]
	ds_read_b128 v[188:191], v166 offset:32768
	ds_read_b128 v[192:195], v166 offset:33792
	ds_read_b128 v[196:199], v166 offset:34816
	ds_read_b128 v[200:203], v166 offset:35840
	ds_read_b128 v[204:207], v166 offset:36864
	ds_read_b128 v[208:211], v166 offset:37888
	ds_read_b128 v[212:215], v166 offset:38912
	ds_read_b128 v[216:219], v166 offset:39936
	global_load_lds_dwordx4 v[228:229], off
	v_lshl_add_u64 v[228:229], s[74:75], 0, v[130:131]
	s_mov_b32 m0, s78
	s_nop 0
	global_load_lds_dwordx4 v[228:229], off
	s_waitcnt vmcnt(8)
	s_waitcnt lgkmcnt(0)
	s_setprio 1
	s_barrier
	v_mfma_f32_16x16x32_bf16 v[124:127], v[148:151], v[188:191], v[124:127]
	v_mfma_f32_16x16x32_bf16 v[120:123], v[156:159], v[188:191], v[120:123]
	v_mfma_f32_16x16x32_bf16 v[116:119], v[148:151], v[196:199], v[116:119]
	v_mfma_f32_16x16x32_bf16 v[108:111], v[156:159], v[196:199], v[108:111]
	v_mfma_f32_16x16x32_bf16 v[100:103], v[148:151], v[204:207], v[100:103]
	v_mfma_f32_16x16x32_bf16 v[92:95], v[156:159], v[204:207], v[92:95]
	v_mfma_f32_16x16x32_bf16 v[84:87], v[148:151], v[212:215], v[84:87]
	v_mfma_f32_16x16x32_bf16 v[76:79], v[156:159], v[212:215], v[76:79]
	v_mfma_f32_16x16x32_bf16 v[124:127], v[152:155], v[192:195], v[124:127]
	v_mfma_f32_16x16x32_bf16 v[120:123], v[168:171], v[192:195], v[120:123]
	v_mfma_f32_16x16x32_bf16 v[116:119], v[152:155], v[200:203], v[116:119]
	v_mfma_f32_16x16x32_bf16 v[108:111], v[168:171], v[200:203], v[108:111]
	v_mfma_f32_16x16x32_bf16 v[100:103], v[152:155], v[208:211], v[100:103]
	v_mfma_f32_16x16x32_bf16 v[92:95], v[168:171], v[208:211], v[92:95]
	v_mfma_f32_16x16x32_bf16 v[84:87], v[152:155], v[216:219], v[84:87]
	v_mfma_f32_16x16x32_bf16 v[76:79], v[168:171], v[216:219], v[76:79]
	s_setprio 0
	s_setprio 1
	v_mfma_f32_16x16x32_bf16 v[112:115], v[172:175], v[188:191], v[112:115]
	v_mfma_f32_16x16x32_bf16 v[104:107], v[180:183], v[188:191], v[104:107]
	v_mfma_f32_16x16x32_bf16 v[96:99], v[172:175], v[196:199], v[96:99]
	v_mfma_f32_16x16x32_bf16 v[88:91], v[180:183], v[196:199], v[88:91]
	v_mfma_f32_16x16x32_bf16 v[80:83], v[172:175], v[204:207], v[80:83]
	v_mfma_f32_16x16x32_bf16 v[72:75], v[180:183], v[204:207], v[72:75]
	v_mfma_f32_16x16x32_bf16 v[68:71], v[172:175], v[212:215], v[68:71]
	v_mfma_f32_16x16x32_bf16 v[64:67], v[180:183], v[212:215], v[64:67]
	v_mfma_f32_16x16x32_bf16 v[112:115], v[176:179], v[192:195], v[112:115]
	v_mfma_f32_16x16x32_bf16 v[104:107], v[184:187], v[192:195], v[104:107]
	v_mfma_f32_16x16x32_bf16 v[96:99], v[176:179], v[200:203], v[96:99]
	v_mfma_f32_16x16x32_bf16 v[88:91], v[184:187], v[200:203], v[88:91]
	v_mfma_f32_16x16x32_bf16 v[80:83], v[176:179], v[208:211], v[80:83]
	v_mfma_f32_16x16x32_bf16 v[72:75], v[184:187], v[208:211], v[72:75]
	s_setprio 2
	s_barrier
; #define PG8_STAGE(bufoff, gbase, voff) do { _Pragma("unroll") for (int _i = 0; _i < 2; ++_i) \
;         __builtin_amdgcn_global_load_lds((const unsigned*)((const char*)(gbase) + (voff)[_i]), (PG8_LAS unsigned*)(lds + (bufoff) + ldsw + _i * 8192), 16, 0, 0); } while (0)
; #define PG8_LDA(dst, b, h) do { _Pragma("unroll") for (int m = 0; m < 4; ++m) _Pragma("unroll") for (int k = 0; k < 2; ++k) dst[m][k] = *(const PG8_LAS bf16x8*)(lds + PG8_SA(b, h) + aoff + m * 2048 + k * 1024); } while (0)
; #define PG8_MMA(ai, bj, At, Bt) do { __builtin_amdgcn_s_setprio(1); _Pragma("unroll") for (int m = 0; m < 4; ++m) _Pragma("unroll") for (int n = 0; n < 2; ++n) _Pragma("unroll") for (int k = 0; k < 2; ++k) \
;         acc[ai][bj][m][n] = __builtin_amdgcn_mfma_f32_16x16x32_bf16(Bt[n][k], At[m][k], acc[ai][bj][m][n], 0, 0, 0); __builtin_amdgcn_s_setprio(0); } while (0)
; #define PG8_WAIT_V(n) asm volatile("s_waitcnt vmcnt(" #n ")" ::: "memory")
; #define PG8_WAIT_L(n) asm volatile("s_waitcnt lgkmcnt(" #n ")" ::: "memory")
; #define PG8_BAR __builtin_amdgcn_s_barrier()
; #define PG8_SCHED __builtin_amdgcn_sched_barrier(0)
; template <class Epi, class Sched, bool ALIGN_EPI = false, bool SP2 = false>
; __device__ __forceinline__ void gemm_phase(PG8_LAS unsigned char* lds, const Gemm g, const Sched& S, const Epi& E) {
;     ...
;             PG8_WAIT_V(8); PG8_WAIT_L(0); PG8_BAR; PG8_MMA(0, 0, At, B0); PG8_MMA(0, 1, At, B1); PG8_BAR; PG8_SCHED;
;             PG8_LDA(At, 1, 1); PG8_STAGE(PG8_SB(1, 0), b3, voffB); PG8_STAGE(PG8_SB(1, 1), b3 + hstep, voffB); PG8_STAGE(PG8_SA(1, 0), a3, voffA);
;             PG8_WAIT_V(8); PG8_WAIT_L(0); PG8_BAR; PG8_MMA(1, 0, At, B0); PG8_MMA(1, 1, At, B1); PG8_BAR; PG8_SCHED;
;     ...
;         if constexpr (ALIGN_EPI) { if (wr == 0) PG8_BAR; }
	v_mfma_f32_16x16x32_bf16 v[68:71], v[176:179], v[216:219], v[68:71]
	v_mfma_f32_16x16x32_bf16 v[64:67], v[184:187], v[216:219], v[64:67]
	s_setprio 0
	s_add_i32 s52, s52, s3
	v_lshl_add_u64 v[220:221], v[220:221], 0, s[12:13]
	s_mov_b32 m0, s52
	ds_read_b128 v[188:191], v166 offset:49152
	ds_read_b128 v[192:195], v166 offset:50176
	ds_read_b128 v[196:199], v166 offset:51200
	ds_read_b128 v[200:203], v166 offset:52224
	ds_read_b128 v[204:207], v166 offset:53248
	ds_read_b128 v[208:211], v166 offset:54272
	ds_read_b128 v[212:215], v166 offset:55296
	ds_read_b128 v[216:219], v166 offset:56320
	global_load_lds_dwordx4 v[220:221], off
	s_add_i32 m0, s52, 0x2000
	s_add_u32 s72, s72, 0x80080
	v_lshl_add_u64 v[220:221], v[222:223], 0, s[12:13]
	s_addc_u32 s73, s73, 0
	s_add_i32 s52, s53, s3
	global_load_lds_dwordx4 v[220:221], off
	v_lshl_add_u64 v[220:221], s[72:73], 0, v[132:133]
	s_mov_b32 m0, s52
	s_nop 0
	global_load_lds_dwordx4 v[220:221], off
	v_lshl_add_u64 v[220:221], s[72:73], 0, v[128:129]
	s_add_i32 m0, s52, 0x2000
	s_nop 0
	global_load_lds_dwordx4 v[220:221], off
	v_lshl_add_u64 v[220:221], v[224:225], 0, s[12:13]
	s_mov_b32 m0, s80
	s_nop 0
	global_load_lds_dwordx4 v[220:221], off
	v_lshl_add_u64 v[220:221], v[226:227], 0, s[12:13]
	s_mov_b32 m0, s81
	s_nop 0
	global_load_lds_dwordx4 v[220:221], off
	s_waitcnt vmcnt(8)
	s_waitcnt lgkmcnt(0)
	s_setprio 1
	s_barrier
	v_mfma_f32_16x16x32_bf16 v[60:63], v[148:151], v[188:191], v[60:63]
	v_mfma_f32_16x16x32_bf16 v[56:59], v[156:159], v[188:191], v[56:59]
	v_mfma_f32_16x16x32_bf16 v[52:55], v[148:151], v[196:199], v[52:55]
	v_mfma_f32_16x16x32_bf16 v[44:47], v[156:159], v[196:199], v[44:47]
	v_mfma_f32_16x16x32_bf16 v[36:39], v[148:151], v[204:207], v[36:39]
	v_mfma_f32_16x16x32_bf16 v[28:31], v[156:159], v[204:207], v[28:31]
	v_mfma_f32_16x16x32_bf16 v[20:23], v[148:151], v[212:215], v[20:23]
	v_mfma_f32_16x16x32_bf16 v[12:15], v[156:159], v[212:215], v[12:15]
	v_mfma_f32_16x16x32_bf16 v[60:63], v[152:155], v[192:195], v[60:63]
	v_mfma_f32_16x16x32_bf16 v[56:59], v[168:171], v[192:195], v[56:59]
	v_mfma_f32_16x16x32_bf16 v[52:55], v[152:155], v[200:203], v[52:55]
	v_mfma_f32_16x16x32_bf16 v[44:47], v[168:171], v[200:203], v[44:47]
	v_mfma_f32_16x16x32_bf16 v[36:39], v[152:155], v[208:211], v[36:39]
	v_mfma_f32_16x16x32_bf16 v[28:31], v[168:171], v[208:211], v[28:31]
	v_mfma_f32_16x16x32_bf16 v[20:23], v[152:155], v[216:219], v[20:23]
	v_mfma_f32_16x16x32_bf16 v[12:15], v[168:171], v[216:219], v[12:15]
	s_setprio 0
	s_setprio 1
	v_mfma_f32_16x16x32_bf16 v[48:51], v[172:175], v[188:191], v[48:51]
	v_mfma_f32_16x16x32_bf16 v[40:43], v[180:183], v[188:191], v[40:43]
	v_mfma_f32_16x16x32_bf16 v[32:35], v[172:175], v[196:199], v[32:35]
	v_mfma_f32_16x16x32_bf16 v[24:27], v[180:183], v[196:199], v[24:27]
	v_mfma_f32_16x16x32_bf16 v[16:19], v[172:175], v[204:207], v[16:19]
	v_mfma_f32_16x16x32_bf16 v[8:11], v[180:183], v[204:207], v[8:11]
	v_mfma_f32_16x16x32_bf16 v[4:7], v[172:175], v[212:215], v[4:7]
	v_mfma_f32_16x16x32_bf16 v[0:3], v[180:183], v[212:215], v[0:3]
	v_mfma_f32_16x16x32_bf16 v[48:51], v[176:179], v[192:195], v[48:51]
	v_mfma_f32_16x16x32_bf16 v[40:43], v[184:187], v[192:195], v[40:43]
	v_mfma_f32_16x16x32_bf16 v[32:35], v[176:179], v[200:203], v[32:35]
	v_mfma_f32_16x16x32_bf16 v[24:27], v[184:187], v[200:203], v[24:27]
	v_mfma_f32_16x16x32_bf16 v[16:19], v[176:179], v[208:211], v[16:19]
	v_mfma_f32_16x16x32_bf16 v[8:11], v[184:187], v[208:211], v[8:11]
	s_setprio 2
	s_barrier
	v_mfma_f32_16x16x32_bf16 v[4:7], v[176:179], v[216:219], v[4:7]
	v_mfma_f32_16x16x32_bf16 v[0:3], v[184:187], v[216:219], v[0:3]
	s_setprio 0
	s_add_i32 s93, s93, 2
	s_add_u32 s70, s70, 0x100
	s_addc_u32 s71, s71, 0
	s_add_u32 s91, s91, 0x100
	s_addc_u32 s92, s92, 0
	s_cmp_gt_u32 s93, 29
	s_cbranch_scc0 .LBB0_200
	s_and_b64 vcc, exec, s[14:15]
	s_cbranch_vccz .LBB0_203
	s_barrier

; #define PG8_STAGE(bufoff, gbase, voff) do { _Pragma("unroll") for (int _i = 0; _i < 2; ++_i) \
;         __builtin_amdgcn_global_load_lds((const unsigned*)((const char*)(gbase) + (voff)[_i]), (PG8_LAS unsigned*)(lds + (bufoff) + ldsw + _i * 8192), 16, 0, 0); } while (0)
; #define PG8_LDA(dst, b, h) do { _Pragma("unroll") for (int m = 0; m < 4; ++m) _Pragma("unroll") for (int k = 0; k < 2; ++k) dst[m][k] = *(const PG8_LAS bf16x8*)(lds + PG8_SA(b, h) + aoff + m * 2048 + k * 1024); } while (0)
; #define PG8_LDB(dst, b, h) do { _Pragma("unroll") for (int n = 0; n < 2; ++n) _Pragma("unroll") for (int k = 0; k < 2; ++k) dst[n][k] = *(const PG8_LAS bf16x8*)(lds + PG8_SB(b, h) + boff + n * 2048 + k * 1024); } while (0)
; #define PG8_MMA(ai, bj, At, Bt) do { __builtin_amdgcn_s_setprio(1); _Pragma("unroll") for (int m = 0; m < 4; ++m) _Pragma("unroll") for (int n = 0; n < 2; ++n) _Pragma("unroll") for (int k = 0; k < 2; ++k) \
;         acc[ai][bj][m][n] = __builtin_amdgcn_mfma_f32_16x16x32_bf16(Bt[n][k], At[m][k], acc[ai][bj][m][n], 0, 0, 0); __builtin_amdgcn_s_setprio(0); } while (0)
; #define PG8_WAIT_V(n) asm volatile("s_waitcnt vmcnt(" #n ")" ::: "memory")
; #define PG8_WAIT_L(n) asm volatile("s_waitcnt lgkmcnt(" #n ")" ::: "memory")
; #define PG8_BAR __builtin_amdgcn_s_barrier()
; template <class Epi, class Sched, bool ALIGN_EPI = false, bool SP2 = false>
; __device__ __forceinline__ void gemm_phase(PG8_LAS unsigned char* lds, const Gemm g, const Sched& S, const Epi& E) {
;     ...
;             const bool last = (t == nt - 2);
;             const char* a1 = cA + (size_t)(t + 1) * kstep;
;             const char* a2 = last ? nA : cA + (size_t)(t + 2) * kstep; const char* b2 = last ? nB : cB + (size_t)(t + 2) * kstep;
;             const char* a3 = a2 + kstep; const char* b3 = b2 + kstep;
;             if constexpr (SP2) {
;             PG8_LDB(B0, 0, 0); PG8_LDB(B1, 0, 1); PG8_SCHED; PG8_LDA(At, 0, 0); PG8_STAGE(PG8_SA(1, 1), a1 + hstep, voffA);
;             PG8_WAIT_V(8); PG8_WAIT_L(0); PG8_BAR; PG8_MMA(0, 0, At, B0); PG8_MMA(0, 1, At, B1); PG8_BAR; PG8_SCHED;
;             PG8_LDA(At, 0, 1); PG8_STAGE(PG8_SB(0, 0), b2, voffB); PG8_STAGE(PG8_SB(0, 1), b2 + hstep, voffB); PG8_STAGE(PG8_SA(0, 0), a2, voffA);
;             PG8_WAIT_V(8); PG8_WAIT_L(0); PG8_BAR; PG8_MMA(1, 0, At, B0); PG8_MMA(1, 1, At, B1); PG8_BAR; PG8_SCHED;
.LBB0_374:
	ds_read_b128 v[128:131], v230
	ds_read_b128 v[132:135], v230 offset:1024
	ds_read_b128 v[158:161], v230 offset:2048
	ds_read_b128 v[162:165], v230 offset:3072
	ds_read_b128 v[166:169], v231
	ds_read_b128 v[170:173], v231 offset:1024
	ds_read_b128 v[174:177], v231 offset:2048
	ds_read_b128 v[178:181], v231 offset:3072
	s_add_u32 s52, s76, 0xfff80080
	s_addc_u32 s53, s77, -1
	s_cmp_eq_u32 vcc_hi, 28
	s_cselect_b32 s81, s11, s53
	s_cselect_b32 s80, s55, s52
	s_cselect_b32 s79, s51, vcc_lo
	s_cselect_b32 s78, s73, s75
	v_lshl_add_u64 v[214:215], s[76:77], 0, v[150:151]
	s_add_i32 m0, s28, 0xc000
	ds_read_b128 v[182:185], v232
	ds_read_b128 v[186:189], v232 offset:1024
	ds_read_b128 v[190:193], v232 offset:2048
	ds_read_b128 v[194:197], v232 offset:3072
	ds_read_b128 v[198:201], v232 offset:4096
	ds_read_b128 v[202:205], v232 offset:5120
	ds_read_b128 v[206:209], v232 offset:6144
	ds_read_b128 v[210:213], v232 offset:7168
	global_load_lds_dwordx4 v[214:215], off
	v_lshl_add_u64 v[214:215], s[76:77], 0, v[152:153]
	s_add_i32 m0, s28, 0xe000
	s_nop 0
	global_load_lds_dwordx4 v[214:215], off
	s_waitcnt vmcnt(8)
	s_waitcnt lgkmcnt(0)
	s_setprio 1
	s_barrier
	v_mfma_f32_16x16x32_bf16 v[124:127], v[128:131], v[182:185], v[124:127]
	v_mfma_f32_16x16x32_bf16 v[120:123], v[158:161], v[182:185], v[120:123]
	v_mfma_f32_16x16x32_bf16 v[116:119], v[128:131], v[190:193], v[116:119]
	v_mfma_f32_16x16x32_bf16 v[112:115], v[158:161], v[190:193], v[112:115]
	v_mfma_f32_16x16x32_bf16 v[108:111], v[128:131], v[198:201], v[108:111]
	v_mfma_f32_16x16x32_bf16 v[104:107], v[158:161], v[198:201], v[104:107]
	v_mfma_f32_16x16x32_bf16 v[100:103], v[128:131], v[206:209], v[100:103]
	v_mfma_f32_16x16x32_bf16 v[96:99], v[158:161], v[206:209], v[96:99]
	v_mfma_f32_16x16x32_bf16 v[124:127], v[132:135], v[186:189], v[124:127]
	v_mfma_f32_16x16x32_bf16 v[120:123], v[162:165], v[186:189], v[120:123]
	v_mfma_f32_16x16x32_bf16 v[116:119], v[132:135], v[194:197], v[116:119]
	v_mfma_f32_16x16x32_bf16 v[112:115], v[162:165], v[194:197], v[112:115]
	v_mfma_f32_16x16x32_bf16 v[108:111], v[132:135], v[202:205], v[108:111]
	v_mfma_f32_16x16x32_bf16 v[104:107], v[162:165], v[202:205], v[104:107]
	v_mfma_f32_16x16x32_bf16 v[100:103], v[132:135], v[210:213], v[100:103]
	v_mfma_f32_16x16x32_bf16 v[96:99], v[162:165], v[210:213], v[96:99]
	s_setprio 0
	s_setprio 1
	v_mfma_f32_16x16x32_bf16 v[60:63], v[166:169], v[182:185], v[60:63]
	v_mfma_f32_16x16x32_bf16 v[56:59], v[174:177], v[182:185], v[56:59]
	v_mfma_f32_16x16x32_bf16 v[52:55], v[166:169], v[190:193], v[52:55]
	v_mfma_f32_16x16x32_bf16 v[48:51], v[174:177], v[190:193], v[48:51]
	v_mfma_f32_16x16x32_bf16 v[44:47], v[166:169], v[198:201], v[44:47]
	v_mfma_f32_16x16x32_bf16 v[40:43], v[174:177], v[198:201], v[40:43]
	v_mfma_f32_16x16x32_bf16 v[36:39], v[166:169], v[206:209], v[36:39]
	v_mfma_f32_16x16x32_bf16 v[32:35], v[174:177], v[206:209], v[32:35]
	v_mfma_f32_16x16x32_bf16 v[60:63], v[170:173], v[186:189], v[60:63]
	v_mfma_f32_16x16x32_bf16 v[56:59], v[178:181], v[186:189], v[56:59]
	v_mfma_f32_16x16x32_bf16 v[52:55], v[170:173], v[194:197], v[52:55]
	v_mfma_f32_16x16x32_bf16 v[48:51], v[178:181], v[194:197], v[48:51]
	v_mfma_f32_16x16x32_bf16 v[44:47], v[170:173], v[202:205], v[44:47]
	v_mfma_f32_16x16x32_bf16 v[40:43], v[178:181], v[202:205], v[40:43]
	s_setprio 2
	s_barrier
	v_mfma_f32_16x16x32_bf16 v[36:39], v[170:173], v[210:213], v[36:39]
	v_mfma_f32_16x16x32_bf16 v[32:35], v[178:181], v[210:213], v[32:35]
	s_setprio 0
	s_add_i32 s52, s93, s3
	v_lshl_add_u64 v[214:215], s[78:79], 0, v[138:139]
	s_mov_b32 m0, s52
	ds_read_b128 v[182:185], v232 offset:16384
	ds_read_b128 v[186:189], v232 offset:17408
	ds_read_b128 v[190:193], v232 offset:18432
	ds_read_b128 v[194:197], v232 offset:19456
	ds_read_b128 v[198:201], v232 offset:20480
	ds_read_b128 v[202:205], v232 offset:21504
	ds_read_b128 v[206:209], v232 offset:22528
	ds_read_b128 v[210:213], v232 offset:23552
	global_load_lds_dwordx4 v[214:215], off
	s_add_i32 m0, s52, 0x2000
	s_add_u32 s52, s78, 0x80000
	v_lshl_add_u64 v[216:217], s[78:79], 0, v[142:143]
	s_addc_u32 s53, s79, 0
	s_add_i32 s56, s10, s3
	global_load_lds_dwordx4 v[216:217], off
	v_lshl_add_u64 v[218:219], s[52:53], 0, v[138:139]
	s_mov_b32 m0, s56
	v_lshl_add_u64 v[220:221], s[80:81], 0, v[140:141]
	global_load_lds_dwordx4 v[218:219], off
	v_lshl_add_u64 v[218:219], s[52:53], 0, v[142:143]
	s_add_i32 m0, s56, 0x2000
	s_nop 0
	global_load_lds_dwordx4 v[218:219], off
	v_lshl_add_u64 v[218:219], s[80:81], 0, v[136:137]
	s_mov_b32 m0, s28
	s_nop 0
	global_load_lds_dwordx4 v[218:219], off
	s_mov_b32 m0, s29
	s_nop 0
	global_load_lds_dwordx4 v[220:221], off
	s_waitcnt vmcnt(8)
	s_waitcnt lgkmcnt(0)
	s_setprio 1
	s_barrier
; #define PG8_STAGE(bufoff, gbase, voff) do { _Pragma("unroll") for (int _i = 0; _i < 2; ++_i) \
;         __builtin_amdgcn_global_load_lds((const unsigned*)((const char*)(gbase) + (voff)[_i]), (PG8_LAS unsigned*)(lds + (bufoff) + ldsw + _i * 8192), 16, 0, 0); } while (0)
; #define PG8_LDA(dst, b, h) do { _Pragma("unroll") for (int m = 0; m < 4; ++m) _Pragma("unroll") for (int k = 0; k < 2; ++k) dst[m][k] = *(const PG8_LAS bf16x8*)(lds + PG8_SA(b, h) + aoff + m * 2048 + k * 1024); } while (0)
; #define PG8_LDB(dst, b, h) do { _Pragma("unroll") for (int n = 0; n < 2; ++n) _Pragma("unroll") for (int k = 0; k < 2; ++k) dst[n][k] = *(const PG8_LAS bf16x8*)(lds + PG8_SB(b, h) + boff + n * 2048 + k * 1024); } while (0)
; #define PG8_MMA(ai, bj, At, Bt) do { __builtin_amdgcn_s_setprio(1); _Pragma("unroll") for (int m = 0; m < 4; ++m) _Pragma("unroll") for (int n = 0; n < 2; ++n) _Pragma("unroll") for (int k = 0; k < 2; ++k) \
;         acc[ai][bj][m][n] = __builtin_amdgcn_mfma_f32_16x16x32_bf16(Bt[n][k], At[m][k], acc[ai][bj][m][n], 0, 0, 0); __builtin_amdgcn_s_setprio(0); } while (0)
; #define PG8_WAIT_V(n) asm volatile("s_waitcnt vmcnt(" #n ")" ::: "memory")
; #define PG8_WAIT_L(n) asm volatile("s_waitcnt lgkmcnt(" #n ")" ::: "memory")
; #define PG8_BAR __builtin_amdgcn_s_barrier()
; #define PG8_SCHED __builtin_amdgcn_sched_barrier(0)
; template <class Epi, class Sched, bool ALIGN_EPI = false, bool SP2 = false>
; __device__ __forceinline__ void gemm_phase(PG8_LAS unsigned char* lds, const Gemm g, const Sched& S, const Epi& E) {
;     ...
;             PG8_WAIT_V(8); PG8_WAIT_L(0); PG8_BAR; PG8_MMA(1, 0, At, B0); PG8_MMA(1, 1, At, B1); PG8_BAR; PG8_SCHED;
;             PG8_LDB(B0, 1, 0); PG8_LDB(B1, 1, 1); PG8_SCHED; PG8_LDA(At, 1, 0); PG8_STAGE(PG8_SA(0, 1), a2 + hstep, voffA);
;             PG8_WAIT_V(8); PG8_WAIT_L(0); PG8_BAR; PG8_MMA(0, 0, At, B0); PG8_MMA(0, 1, At, B1); PG8_BAR; PG8_SCHED;
	v_mfma_f32_16x16x32_bf16 v[92:95], v[128:131], v[182:185], v[92:95]
	v_mfma_f32_16x16x32_bf16 v[88:91], v[158:161], v[182:185], v[88:91]
	v_mfma_f32_16x16x32_bf16 v[84:87], v[128:131], v[190:193], v[84:87]
	v_mfma_f32_16x16x32_bf16 v[80:83], v[158:161], v[190:193], v[80:83]
	v_mfma_f32_16x16x32_bf16 v[76:79], v[128:131], v[198:201], v[76:79]
	v_mfma_f32_16x16x32_bf16 v[72:75], v[158:161], v[198:201], v[72:75]
	v_mfma_f32_16x16x32_bf16 v[68:71], v[128:131], v[206:209], v[68:71]
	v_mfma_f32_16x16x32_bf16 v[64:67], v[158:161], v[206:209], v[64:67]
	v_mfma_f32_16x16x32_bf16 v[92:95], v[132:135], v[186:189], v[92:95]
	v_mfma_f32_16x16x32_bf16 v[88:91], v[162:165], v[186:189], v[88:91]
	v_mfma_f32_16x16x32_bf16 v[84:87], v[132:135], v[194:197], v[84:87]
	v_mfma_f32_16x16x32_bf16 v[80:83], v[162:165], v[194:197], v[80:83]
	v_mfma_f32_16x16x32_bf16 v[76:79], v[132:135], v[202:205], v[76:79]
	v_mfma_f32_16x16x32_bf16 v[72:75], v[162:165], v[202:205], v[72:75]
	v_mfma_f32_16x16x32_bf16 v[68:71], v[132:135], v[210:213], v[68:71]
	v_mfma_f32_16x16x32_bf16 v[64:67], v[162:165], v[210:213], v[64:67]
	s_setprio 0
	s_setprio 1
	v_mfma_f32_16x16x32_bf16 v[28:31], v[166:169], v[182:185], v[28:31]
	v_mfma_f32_16x16x32_bf16 v[24:27], v[174:177], v[182:185], v[24:27]
	v_mfma_f32_16x16x32_bf16 v[20:23], v[166:169], v[190:193], v[20:23]
	v_mfma_f32_16x16x32_bf16 v[16:19], v[174:177], v[190:193], v[16:19]
	v_mfma_f32_16x16x32_bf16 v[12:15], v[166:169], v[198:201], v[12:15]
	v_mfma_f32_16x16x32_bf16 v[8:11], v[174:177], v[198:201], v[8:11]
	v_mfma_f32_16x16x32_bf16 v[4:7], v[166:169], v[206:209], v[4:7]
	v_mfma_f32_16x16x32_bf16 v[0:3], v[174:177], v[206:209], v[0:3]
	v_mfma_f32_16x16x32_bf16 v[28:31], v[170:173], v[186:189], v[28:31]
	v_mfma_f32_16x16x32_bf16 v[24:27], v[178:181], v[186:189], v[24:27]
	v_mfma_f32_16x16x32_bf16 v[20:23], v[170:173], v[194:197], v[20:23]
	v_mfma_f32_16x16x32_bf16 v[16:19], v[178:181], v[194:197], v[16:19]
	v_mfma_f32_16x16x32_bf16 v[12:15], v[170:173], v[202:205], v[12:15]
	v_mfma_f32_16x16x32_bf16 v[8:11], v[178:181], v[202:205], v[8:11]
	s_setprio 2
	s_barrier
	v_mfma_f32_16x16x32_bf16 v[4:7], v[170:173], v[210:213], v[4:7]
	v_mfma_f32_16x16x32_bf16 v[0:3], v[178:181], v[210:213], v[0:3]
	s_setprio 0
	s_add_i32 s56, 0, 0x18000
	s_add_i32 s57, 0, 0x1c000
	v_add_u32_e32 v162, s56, v228
	v_add_u32_e32 v178, s57, v228
	ds_read_b128 v[128:131], v162
	ds_read_b128 v[132:135], v162 offset:1024
	ds_read_b128 v[158:161], v162 offset:2048
	ds_read_b128 v[162:165], v162 offset:3072
	ds_read_b128 v[166:169], v178
	ds_read_b128 v[170:173], v178 offset:1024
	ds_read_b128 v[174:177], v178 offset:2048
	ds_read_b128 v[178:181], v178 offset:3072
	s_add_u32 s52, s80, 0x80000
	s_addc_u32 s53, s81, 0
	s_mov_b32 m0, s33
	v_lshl_add_u64 v[234:235], s[52:53], 0, v[136:137]
	ds_read_b128 v[182:185], v232 offset:32768
	ds_read_b128 v[186:189], v232 offset:33792
	ds_read_b128 v[190:193], v232 offset:34816
	ds_read_b128 v[194:197], v232 offset:35840
	ds_read_b128 v[198:201], v232 offset:36864
	ds_read_b128 v[202:205], v232 offset:37888
	ds_read_b128 v[206:209], v232 offset:38912
	ds_read_b128 v[210:213], v232 offset:39936
	global_load_lds_dwordx4 v[234:235], off
	v_lshl_add_u64 v[234:235], s[52:53], 0, v[140:141]
	s_mov_b32 m0, s38
	s_nop 0
	global_load_lds_dwordx4 v[234:235], off
	s_waitcnt vmcnt(8)
	s_waitcnt lgkmcnt(0)
	s_setprio 1
	s_barrier
	v_mfma_f32_16x16x32_bf16 v[124:127], v[128:131], v[182:185], v[124:127]
	v_mfma_f32_16x16x32_bf16 v[120:123], v[158:161], v[182:185], v[120:123]
	v_mfma_f32_16x16x32_bf16 v[116:119], v[128:131], v[190:193], v[116:119]
	v_mfma_f32_16x16x32_bf16 v[112:115], v[158:161], v[190:193], v[112:115]
	v_mfma_f32_16x16x32_bf16 v[108:111], v[128:131], v[198:201], v[108:111]
	v_mfma_f32_16x16x32_bf16 v[104:107], v[158:161], v[198:201], v[104:107]
	v_mfma_f32_16x16x32_bf16 v[100:103], v[128:131], v[206:209], v[100:103]
	v_mfma_f32_16x16x32_bf16 v[96:99], v[158:161], v[206:209], v[96:99]
	v_mfma_f32_16x16x32_bf16 v[124:127], v[132:135], v[186:189], v[124:127]
	v_mfma_f32_16x16x32_bf16 v[120:123], v[162:165], v[186:189], v[120:123]
	v_mfma_f32_16x16x32_bf16 v[116:119], v[132:135], v[194:197], v[116:119]
	v_mfma_f32_16x16x32_bf16 v[112:115], v[162:165], v[194:197], v[112:115]
	v_mfma_f32_16x16x32_bf16 v[108:111], v[132:135], v[202:205], v[108:111]
	v_mfma_f32_16x16x32_bf16 v[104:107], v[162:165], v[202:205], v[104:107]
	v_mfma_f32_16x16x32_bf16 v[100:103], v[132:135], v[210:213], v[100:103]
	v_mfma_f32_16x16x32_bf16 v[96:99], v[162:165], v[210:213], v[96:99]
	s_setprio 0
	s_setprio 1
	v_mfma_f32_16x16x32_bf16 v[60:63], v[166:169], v[182:185], v[60:63]
	v_mfma_f32_16x16x32_bf16 v[56:59], v[174:177], v[182:185], v[56:59]
	v_mfma_f32_16x16x32_bf16 v[52:55], v[166:169], v[190:193], v[52:55]
	v_mfma_f32_16x16x32_bf16 v[48:51], v[174:177], v[190:193], v[48:51]
	v_mfma_f32_16x16x32_bf16 v[44:47], v[166:169], v[198:201], v[44:47]
	v_mfma_f32_16x16x32_bf16 v[40:43], v[174:177], v[198:201], v[40:43]
	v_mfma_f32_16x16x32_bf16 v[36:39], v[166:169], v[206:209], v[36:39]
	v_mfma_f32_16x16x32_bf16 v[32:35], v[174:177], v[206:209], v[32:35]
	v_mfma_f32_16x16x32_bf16 v[60:63], v[170:173], v[186:189], v[60:63]
	v_mfma_f32_16x16x32_bf16 v[56:59], v[178:181], v[186:189], v[56:59]
	v_mfma_f32_16x16x32_bf16 v[52:55], v[170:173], v[194:197], v[52:55]
	v_mfma_f32_16x16x32_bf16 v[48:51], v[178:181], v[194:197], v[48:51]
	v_mfma_f32_16x16x32_bf16 v[44:47], v[170:173], v[202:205], v[44:47]
	v_mfma_f32_16x16x32_bf16 v[40:43], v[178:181], v[202:205], v[40:43]
	s_setprio 2
	s_barrier
; #define PG8_STAGE(bufoff, gbase, voff) do { _Pragma("unroll") for (int _i = 0; _i < 2; ++_i) \
;         __builtin_amdgcn_global_load_lds((const unsigned*)((const char*)(gbase) + (voff)[_i]), (PG8_LAS unsigned*)(lds + (bufoff) + ldsw + _i * 8192), 16, 0, 0); } while (0)
; #define PG8_LDA(dst, b, h) do { _Pragma("unroll") for (int m = 0; m < 4; ++m) _Pragma("unroll") for (int k = 0; k < 2; ++k) dst[m][k] = *(const PG8_LAS bf16x8*)(lds + PG8_SA(b, h) + aoff + m * 2048 + k * 1024); } while (0)
; #define PG8_MMA(ai, bj, At, Bt) do { __builtin_amdgcn_s_setprio(1); _Pragma("unroll") for (int m = 0; m < 4; ++m) _Pragma("unroll") for (int n = 0; n < 2; ++n) _Pragma("unroll") for (int k = 0; k < 2; ++k) \
;         acc[ai][bj][m][n] = __builtin_amdgcn_mfma_f32_16x16x32_bf16(Bt[n][k], At[m][k], acc[ai][bj][m][n], 0, 0, 0); __builtin_amdgcn_s_setprio(0); } while (0)
; #define PG8_WAIT_V(n) asm volatile("s_waitcnt vmcnt(" #n ")" ::: "memory")
; #define PG8_WAIT_L(n) asm volatile("s_waitcnt lgkmcnt(" #n ")" ::: "memory")
; #define PG8_BAR __builtin_amdgcn_s_barrier()
; #define PG8_SCHED __builtin_amdgcn_sched_barrier(0)
; template <class Epi, class Sched, bool ALIGN_EPI = false, bool SP2 = false>
; __device__ __forceinline__ void gemm_phase(PG8_LAS unsigned char* lds, const Gemm g, const Sched& S, const Epi& E) {
;     ...
;             PG8_WAIT_V(8); PG8_WAIT_L(0); PG8_BAR; PG8_MMA(0, 0, At, B0); PG8_MMA(0, 1, At, B1); PG8_BAR; PG8_SCHED;
;             PG8_LDA(At, 1, 1); PG8_STAGE(PG8_SB(1, 0), b3, voffB); PG8_STAGE(PG8_SB(1, 1), b3 + hstep, voffB); PG8_STAGE(PG8_SA(1, 0), a3, voffA);
;             PG8_WAIT_V(8); PG8_WAIT_L(0); PG8_BAR; PG8_MMA(1, 0, At, B0); PG8_MMA(1, 1, At, B1); PG8_BAR; PG8_SCHED;
;     ...
;         if constexpr (ALIGN_EPI) { if (wr == 0) PG8_BAR; }
	v_mfma_f32_16x16x32_bf16 v[36:39], v[170:173], v[210:213], v[36:39]
	v_mfma_f32_16x16x32_bf16 v[32:35], v[178:181], v[210:213], v[32:35]
	s_setprio 0
	s_add_i32 s52, s56, s3
	v_lshl_add_u64 v[214:215], v[214:215], 0, s[14:15]
	s_mov_b32 m0, s52
	ds_read_b128 v[182:185], v232 offset:49152
	ds_read_b128 v[186:189], v232 offset:50176
	ds_read_b128 v[190:193], v232 offset:51200
	ds_read_b128 v[194:197], v232 offset:52224
	ds_read_b128 v[198:201], v232 offset:53248
	ds_read_b128 v[202:205], v232 offset:54272
	ds_read_b128 v[206:209], v232 offset:55296
	ds_read_b128 v[210:213], v232 offset:56320
	global_load_lds_dwordx4 v[214:215], off
	s_add_i32 m0, s52, 0x2000
	s_add_u32 s52, s78, 0x80080
	v_lshl_add_u64 v[214:215], v[216:217], 0, s[14:15]
	s_addc_u32 s53, s79, 0
	s_add_i32 s56, s57, s3
	global_load_lds_dwordx4 v[214:215], off
	v_lshl_add_u64 v[214:215], s[52:53], 0, v[138:139]
	s_mov_b32 m0, s56
	s_nop 0
	global_load_lds_dwordx4 v[214:215], off
	v_lshl_add_u64 v[214:215], s[52:53], 0, v[142:143]
	s_add_i32 m0, s56, 0x2000
	s_nop 0
	global_load_lds_dwordx4 v[214:215], off
	v_lshl_add_u64 v[214:215], v[218:219], 0, s[14:15]
	s_mov_b32 m0, s88
	s_nop 0
	global_load_lds_dwordx4 v[214:215], off
	v_lshl_add_u64 v[214:215], v[220:221], 0, s[14:15]
	s_mov_b32 m0, s89
	s_nop 0
	global_load_lds_dwordx4 v[214:215], off
	s_waitcnt vmcnt(8)
	s_waitcnt lgkmcnt(0)
	s_setprio 1
	s_barrier
	v_mfma_f32_16x16x32_bf16 v[92:95], v[128:131], v[182:185], v[92:95]
	v_mfma_f32_16x16x32_bf16 v[88:91], v[158:161], v[182:185], v[88:91]
	v_mfma_f32_16x16x32_bf16 v[84:87], v[128:131], v[190:193], v[84:87]
	v_mfma_f32_16x16x32_bf16 v[80:83], v[158:161], v[190:193], v[80:83]
	v_mfma_f32_16x16x32_bf16 v[76:79], v[128:131], v[198:201], v[76:79]
	v_mfma_f32_16x16x32_bf16 v[72:75], v[158:161], v[198:201], v[72:75]
	v_mfma_f32_16x16x32_bf16 v[68:71], v[128:131], v[206:209], v[68:71]
	v_mfma_f32_16x16x32_bf16 v[64:67], v[158:161], v[206:209], v[64:67]
	v_mfma_f32_16x16x32_bf16 v[92:95], v[132:135], v[186:189], v[92:95]
	v_mfma_f32_16x16x32_bf16 v[88:91], v[162:165], v[186:189], v[88:91]
	v_mfma_f32_16x16x32_bf16 v[84:87], v[132:135], v[194:197], v[84:87]
	v_mfma_f32_16x16x32_bf16 v[80:83], v[162:165], v[194:197], v[80:83]
	v_mfma_f32_16x16x32_bf16 v[76:79], v[132:135], v[202:205], v[76:79]
	v_mfma_f32_16x16x32_bf16 v[72:75], v[162:165], v[202:205], v[72:75]
	v_mfma_f32_16x16x32_bf16 v[68:71], v[132:135], v[210:213], v[68:71]
	v_mfma_f32_16x16x32_bf16 v[64:67], v[162:165], v[210:213], v[64:67]
	s_setprio 0
	s_setprio 1
	v_mfma_f32_16x16x32_bf16 v[28:31], v[166:169], v[182:185], v[28:31]
	v_mfma_f32_16x16x32_bf16 v[24:27], v[174:177], v[182:185], v[24:27]
	v_mfma_f32_16x16x32_bf16 v[20:23], v[166:169], v[190:193], v[20:23]
	v_mfma_f32_16x16x32_bf16 v[16:19], v[174:177], v[190:193], v[16:19]
	v_mfma_f32_16x16x32_bf16 v[12:15], v[166:169], v[198:201], v[12:15]
	v_mfma_f32_16x16x32_bf16 v[8:11], v[174:177], v[198:201], v[8:11]
	v_mfma_f32_16x16x32_bf16 v[4:7], v[166:169], v[206:209], v[4:7]
	v_mfma_f32_16x16x32_bf16 v[0:3], v[174:177], v[206:209], v[0:3]
	v_mfma_f32_16x16x32_bf16 v[28:31], v[170:173], v[186:189], v[28:31]
	v_mfma_f32_16x16x32_bf16 v[24:27], v[178:181], v[186:189], v[24:27]
	v_mfma_f32_16x16x32_bf16 v[20:23], v[170:173], v[194:197], v[20:23]
	v_mfma_f32_16x16x32_bf16 v[16:19], v[178:181], v[194:197], v[16:19]
	v_mfma_f32_16x16x32_bf16 v[12:15], v[170:173], v[202:205], v[12:15]
	v_mfma_f32_16x16x32_bf16 v[8:11], v[178:181], v[202:205], v[8:11]
	s_setprio 2
	s_barrier
	v_mfma_f32_16x16x32_bf16 v[4:7], v[170:173], v[210:213], v[4:7]
	v_mfma_f32_16x16x32_bf16 v[0:3], v[178:181], v[210:213], v[0:3]
	s_setprio 0
	s_add_i32 vcc_hi, vcc_hi, 2
	s_add_u32 s76, s76, 0x100
	s_addc_u32 s77, s77, 0
	s_add_u32 s75, s75, 0x100
	s_addc_u32 vcc_lo, vcc_lo, 0
	s_cmp_gt_u32 vcc_hi, 29
	s_cbranch_scc0 .LBB0_374
	s_and_b64 vcc, exec, s[48:49]
	s_cbranch_vccz .LBB0_377
	s_barrier

; #define PG8_STAGE(bufoff, gbase, voff) do { _Pragma("unroll") for (int _i = 0; _i < 2; ++_i) \
;         __builtin_amdgcn_global_load_lds((const unsigned*)((const char*)(gbase) + (voff)[_i]), (PG8_LAS unsigned*)(lds + (bufoff) + ldsw + _i * 8192), 16, 0, 0); } while (0)
; #define PG8_LDA(dst, b, h) do { _Pragma("unroll") for (int m = 0; m < 4; ++m) _Pragma("unroll") for (int k = 0; k < 2; ++k) dst[m][k] = *(const PG8_LAS bf16x8*)(lds + PG8_SA(b, h) + aoff + m * 2048 + k * 1024); } while (0)
; #define PG8_LDB(dst, b, h) do { _Pragma("unroll") for (int n = 0; n < 2; ++n) _Pragma("unroll") for (int k = 0; k < 2; ++k) dst[n][k] = *(const PG8_LAS bf16x8*)(lds + PG8_SB(b, h) + boff + n * 2048 + k * 1024); } while (0)
; #define PG8_MMA(ai, bj, At, Bt) do { __builtin_amdgcn_s_setprio(1); _Pragma("unroll") for (int m = 0; m < 4; ++m) _Pragma("unroll") for (int n = 0; n < 2; ++n) _Pragma("unroll") for (int k = 0; k < 2; ++k) \
;         acc[ai][bj][m][n] = __builtin_amdgcn_mfma_f32_16x16x32_bf16(Bt[n][k], At[m][k], acc[ai][bj][m][n], 0, 0, 0); __builtin_amdgcn_s_setprio(0); } while (0)
; #define PG8_WAIT_V(n) asm volatile("s_waitcnt vmcnt(" #n ")" ::: "memory")
; #define PG8_WAIT_L(n) asm volatile("s_waitcnt lgkmcnt(" #n ")" ::: "memory")
; #define PG8_BAR __builtin_amdgcn_s_barrier()
; #define PG8_SCHED __builtin_amdgcn_sched_barrier(0)
; template <class Epi, class Sched, bool ALIGN_EPI = false, bool SP2 = false>
; __device__ __forceinline__ void gemm_phase(PG8_LAS unsigned char* lds, const Gemm g, const Sched& S, const Epi& E) {
;     ...
;         for (int t = 0; t < nt; t += 2) {
;             const bool last = (t == nt - 2);
;             const char* a1 = cA + (size_t)(t + 1) * kstep;
;             const char* a2 = last ? nA : cA + (size_t)(t + 2) * kstep; const char* b2 = last ? nB : cB + (size_t)(t + 2) * kstep;
;             const char* a3 = a2 + kstep; const char* b3 = b2 + kstep;
;             if constexpr (SP2) {
;             PG8_LDB(B0, 0, 0); PG8_LDB(B1, 0, 1); PG8_SCHED; PG8_LDA(At, 0, 0); PG8_STAGE(PG8_SA(1, 1), a1 + hstep, voffA);
;             PG8_WAIT_V(8); PG8_WAIT_L(0); PG8_BAR; PG8_MMA(0, 0, At, B0); PG8_MMA(0, 1, At, B1); PG8_BAR; PG8_SCHED;
;             PG8_LDA(At, 0, 1); PG8_STAGE(PG8_SB(0, 0), b2, voffB); PG8_STAGE(PG8_SB(0, 1), b2 + hstep, voffB); PG8_STAGE(PG8_SA(0, 0), a2, voffA);
.LBB0_410:
	ds_read_b128 v[166:169], v145
	ds_read_b128 v[170:173], v145 offset:1024
	ds_read_b128 v[174:177], v145 offset:2048
	ds_read_b128 v[178:181], v145 offset:3072
	ds_read_b128 v[182:185], v149
	ds_read_b128 v[186:189], v149 offset:1024
	ds_read_b128 v[190:193], v149 offset:2048
	ds_read_b128 v[194:197], v149 offset:3072
	s_add_u32 s52, s74, 0xfff80080
	s_addc_u32 s53, s75, -1
	s_cmp_eq_u32 s51, 4
	s_cselect_b32 s79, s55, s53
	s_cselect_b32 s78, s54, s52
	s_cselect_b32 s77, s69, s49
	s_cselect_b32 s76, s68, s37
	s_mov_b32 m0, s80
	v_lshl_add_u64 v[230:231], s[74:75], 0, v[160:161]
	ds_read_b128 v[198:201], v164
	ds_read_b128 v[202:205], v164 offset:1024
	ds_read_b128 v[206:209], v164 offset:2048
	ds_read_b128 v[210:213], v164 offset:3072
	ds_read_b128 v[214:217], v164 offset:4096
	ds_read_b128 v[218:221], v164 offset:5120
	ds_read_b128 v[222:225], v164 offset:6144
	ds_read_b128 v[226:229], v164 offset:7168
	global_load_lds_dwordx4 v[230:231], off
	v_lshl_add_u64 v[230:231], s[74:75], 0, v[162:163]
	s_mov_b32 m0, s81
	s_nop 0
	global_load_lds_dwordx4 v[230:231], off
	s_waitcnt vmcnt(8)
	s_waitcnt lgkmcnt(0)
	s_setprio 1
	s_barrier
	v_mfma_f32_16x16x32_bf16 v[124:127], v[166:169], v[198:201], v[124:127]
	v_mfma_f32_16x16x32_bf16 v[120:123], v[174:177], v[198:201], v[120:123]
	v_mfma_f32_16x16x32_bf16 v[116:119], v[166:169], v[206:209], v[116:119]
	v_mfma_f32_16x16x32_bf16 v[108:111], v[174:177], v[206:209], v[108:111]
	v_mfma_f32_16x16x32_bf16 v[100:103], v[166:169], v[214:217], v[100:103]
	v_mfma_f32_16x16x32_bf16 v[92:95], v[174:177], v[214:217], v[92:95]
	v_mfma_f32_16x16x32_bf16 v[84:87], v[166:169], v[222:225], v[84:87]
	v_mfma_f32_16x16x32_bf16 v[76:79], v[174:177], v[222:225], v[76:79]
	v_mfma_f32_16x16x32_bf16 v[124:127], v[170:173], v[202:205], v[124:127]
	v_mfma_f32_16x16x32_bf16 v[120:123], v[178:181], v[202:205], v[120:123]
	v_mfma_f32_16x16x32_bf16 v[116:119], v[170:173], v[210:213], v[116:119]
	v_mfma_f32_16x16x32_bf16 v[108:111], v[178:181], v[210:213], v[108:111]
	v_mfma_f32_16x16x32_bf16 v[100:103], v[170:173], v[218:221], v[100:103]
	v_mfma_f32_16x16x32_bf16 v[92:95], v[178:181], v[218:221], v[92:95]
	v_mfma_f32_16x16x32_bf16 v[84:87], v[170:173], v[226:229], v[84:87]
	v_mfma_f32_16x16x32_bf16 v[76:79], v[178:181], v[226:229], v[76:79]
	s_setprio 0
	s_setprio 1
	v_mfma_f32_16x16x32_bf16 v[112:115], v[182:185], v[198:201], v[112:115]
	v_mfma_f32_16x16x32_bf16 v[104:107], v[190:193], v[198:201], v[104:107]
	v_mfma_f32_16x16x32_bf16 v[96:99], v[182:185], v[206:209], v[96:99]
	v_mfma_f32_16x16x32_bf16 v[88:91], v[190:193], v[206:209], v[88:91]
	v_mfma_f32_16x16x32_bf16 v[80:83], v[182:185], v[214:217], v[80:83]
	v_mfma_f32_16x16x32_bf16 v[72:75], v[190:193], v[214:217], v[72:75]
	v_mfma_f32_16x16x32_bf16 v[68:71], v[182:185], v[222:225], v[68:71]
	v_mfma_f32_16x16x32_bf16 v[64:67], v[190:193], v[222:225], v[64:67]
	v_mfma_f32_16x16x32_bf16 v[112:115], v[186:189], v[202:205], v[112:115]
	v_mfma_f32_16x16x32_bf16 v[104:107], v[194:197], v[202:205], v[104:107]
	v_mfma_f32_16x16x32_bf16 v[96:99], v[186:189], v[210:213], v[96:99]
	v_mfma_f32_16x16x32_bf16 v[88:91], v[194:197], v[210:213], v[88:91]
	v_mfma_f32_16x16x32_bf16 v[80:83], v[186:189], v[218:221], v[80:83]
	v_mfma_f32_16x16x32_bf16 v[72:75], v[194:197], v[218:221], v[72:75]
	s_setprio 2
	s_barrier
	v_mfma_f32_16x16x32_bf16 v[68:71], v[186:189], v[226:229], v[68:71]
	v_mfma_f32_16x16x32_bf16 v[64:67], v[194:197], v[226:229], v[64:67]
	s_setprio 0
	s_mov_b32 m0, s84
	v_lshl_add_u64 v[230:231], s[76:77], 0, v[138:139]
	s_add_u32 s52, s76, 0x80000
	ds_read_b128 v[198:201], v164 offset:16384
	ds_read_b128 v[202:205], v164 offset:17408
	ds_read_b128 v[206:209], v164 offset:18432
	ds_read_b128 v[210:213], v164 offset:19456
	ds_read_b128 v[214:217], v164 offset:20480
	ds_read_b128 v[218:221], v164 offset:21504
	ds_read_b128 v[222:225], v164 offset:22528
	ds_read_b128 v[226:229], v164 offset:23552
	global_load_lds_dwordx4 v[230:231], off
	v_lshl_add_u64 v[232:233], s[76:77], 0, v[142:143]
	s_mov_b32 m0, s85
	s_addc_u32 s53, s77, 0
	global_load_lds_dwordx4 v[232:233], off
	v_lshl_add_u64 v[234:235], s[52:53], 0, v[138:139]
	s_mov_b32 m0, s86
	v_lshl_add_u64 v[236:237], s[78:79], 0, v[140:141]
	global_load_lds_dwordx4 v[234:235], off
	v_lshl_add_u64 v[234:235], s[52:53], 0, v[142:143]
	s_mov_b32 m0, s87
	s_nop 0
	global_load_lds_dwordx4 v[234:235], off
	v_lshl_add_u64 v[234:235], s[78:79], 0, v[136:137]
	s_mov_b32 m0, s10
	s_nop 0
	global_load_lds_dwordx4 v[234:235], off
	s_mov_b32 m0, s11
	s_nop 0
	global_load_lds_dwordx4 v[236:237], off
	s_waitcnt vmcnt(8)
	s_waitcnt lgkmcnt(0)
	s_setprio 1
	s_barrier
; #define PG8_STAGE(bufoff, gbase, voff) do { _Pragma("unroll") for (int _i = 0; _i < 2; ++_i) \
;         __builtin_amdgcn_global_load_lds((const unsigned*)((const char*)(gbase) + (voff)[_i]), (PG8_LAS unsigned*)(lds + (bufoff) + ldsw + _i * 8192), 16, 0, 0); } while (0)
; #define PG8_LDA(dst, b, h) do { _Pragma("unroll") for (int m = 0; m < 4; ++m) _Pragma("unroll") for (int k = 0; k < 2; ++k) dst[m][k] = *(const PG8_LAS bf16x8*)(lds + PG8_SA(b, h) + aoff + m * 2048 + k * 1024); } while (0)
; #define PG8_LDB(dst, b, h) do { _Pragma("unroll") for (int n = 0; n < 2; ++n) _Pragma("unroll") for (int k = 0; k < 2; ++k) dst[n][k] = *(const PG8_LAS bf16x8*)(lds + PG8_SB(b, h) + boff + n * 2048 + k * 1024); } while (0)
; #define PG8_MMA(ai, bj, At, Bt) do { __builtin_amdgcn_s_setprio(1); _Pragma("unroll") for (int m = 0; m < 4; ++m) _Pragma("unroll") for (int n = 0; n < 2; ++n) _Pragma("unroll") for (int k = 0; k < 2; ++k) \
;         acc[ai][bj][m][n] = __builtin_amdgcn_mfma_f32_16x16x32_bf16(Bt[n][k], At[m][k], acc[ai][bj][m][n], 0, 0, 0); __builtin_amdgcn_s_setprio(0); } while (0)
; #define PG8_WAIT_V(n) asm volatile("s_waitcnt vmcnt(" #n ")" ::: "memory")
; #define PG8_WAIT_L(n) asm volatile("s_waitcnt lgkmcnt(" #n ")" ::: "memory")
; #define PG8_BAR __builtin_amdgcn_s_barrier()
; #define PG8_SCHED __builtin_amdgcn_sched_barrier(0)
; template <class Epi, class Sched, bool ALIGN_EPI = false, bool SP2 = false>
; __device__ __forceinline__ void gemm_phase(PG8_LAS unsigned char* lds, const Gemm g, const Sched& S, const Epi& E) {
;     ...
;             PG8_WAIT_V(8); PG8_WAIT_L(0); PG8_BAR; PG8_MMA(1, 0, At, B0); PG8_MMA(1, 1, At, B1); PG8_BAR; PG8_SCHED;
;             PG8_LDB(B0, 1, 0); PG8_LDB(B1, 1, 1); PG8_SCHED; PG8_LDA(At, 1, 0); PG8_STAGE(PG8_SA(0, 1), a2 + hstep, voffA);
;             PG8_WAIT_V(8); PG8_WAIT_L(0); PG8_BAR; PG8_MMA(0, 0, At, B0); PG8_MMA(0, 1, At, B1); PG8_BAR; PG8_SCHED;
	v_mfma_f32_16x16x32_bf16 v[60:63], v[166:169], v[198:201], v[60:63]
	v_mfma_f32_16x16x32_bf16 v[56:59], v[174:177], v[198:201], v[56:59]
	v_mfma_f32_16x16x32_bf16 v[52:55], v[166:169], v[206:209], v[52:55]
	v_mfma_f32_16x16x32_bf16 v[44:47], v[174:177], v[206:209], v[44:47]
	v_mfma_f32_16x16x32_bf16 v[36:39], v[166:169], v[214:217], v[36:39]
	v_mfma_f32_16x16x32_bf16 v[28:31], v[174:177], v[214:217], v[28:31]
	v_mfma_f32_16x16x32_bf16 v[20:23], v[166:169], v[222:225], v[20:23]
	v_mfma_f32_16x16x32_bf16 v[12:15], v[174:177], v[222:225], v[12:15]
	v_mfma_f32_16x16x32_bf16 v[60:63], v[170:173], v[202:205], v[60:63]
	v_mfma_f32_16x16x32_bf16 v[56:59], v[178:181], v[202:205], v[56:59]
	v_mfma_f32_16x16x32_bf16 v[52:55], v[170:173], v[210:213], v[52:55]
	v_mfma_f32_16x16x32_bf16 v[44:47], v[178:181], v[210:213], v[44:47]
	v_mfma_f32_16x16x32_bf16 v[36:39], v[170:173], v[218:221], v[36:39]
	v_mfma_f32_16x16x32_bf16 v[28:31], v[178:181], v[218:221], v[28:31]
	v_mfma_f32_16x16x32_bf16 v[20:23], v[170:173], v[226:229], v[20:23]
	v_mfma_f32_16x16x32_bf16 v[12:15], v[178:181], v[226:229], v[12:15]
	s_setprio 0
	s_setprio 1
	v_mfma_f32_16x16x32_bf16 v[48:51], v[182:185], v[198:201], v[48:51]
	v_mfma_f32_16x16x32_bf16 v[40:43], v[190:193], v[198:201], v[40:43]
	v_mfma_f32_16x16x32_bf16 v[32:35], v[182:185], v[206:209], v[32:35]
	v_mfma_f32_16x16x32_bf16 v[24:27], v[190:193], v[206:209], v[24:27]
	v_mfma_f32_16x16x32_bf16 v[16:19], v[182:185], v[214:217], v[16:19]
	v_mfma_f32_16x16x32_bf16 v[8:11], v[190:193], v[214:217], v[8:11]
	v_mfma_f32_16x16x32_bf16 v[4:7], v[182:185], v[222:225], v[4:7]
	v_mfma_f32_16x16x32_bf16 v[0:3], v[190:193], v[222:225], v[0:3]
	v_mfma_f32_16x16x32_bf16 v[48:51], v[186:189], v[202:205], v[48:51]
	v_mfma_f32_16x16x32_bf16 v[40:43], v[194:197], v[202:205], v[40:43]
	v_mfma_f32_16x16x32_bf16 v[32:35], v[186:189], v[210:213], v[32:35]
	v_mfma_f32_16x16x32_bf16 v[24:27], v[194:197], v[210:213], v[24:27]
	v_mfma_f32_16x16x32_bf16 v[16:19], v[186:189], v[218:221], v[16:19]
	v_mfma_f32_16x16x32_bf16 v[8:11], v[194:197], v[218:221], v[8:11]
	s_setprio 2
	s_barrier
	v_mfma_f32_16x16x32_bf16 v[4:7], v[186:189], v[226:229], v[4:7]
	v_mfma_f32_16x16x32_bf16 v[0:3], v[194:197], v[226:229], v[0:3]
	s_setprio 0
	ds_read_b128 v[166:169], v148
	ds_read_b128 v[170:173], v148 offset:1024
	ds_read_b128 v[174:177], v148 offset:2048
	ds_read_b128 v[178:181], v148 offset:3072
	ds_read_b128 v[182:185], v165
	ds_read_b128 v[186:189], v165 offset:1024
	ds_read_b128 v[190:193], v165 offset:2048
	ds_read_b128 v[194:197], v165 offset:3072
	s_add_u32 s52, s78, 0x80000
	s_addc_u32 s53, s79, 0
	s_mov_b32 m0, s28
	v_lshl_add_u64 v[238:239], s[52:53], 0, v[136:137]
	ds_read_b128 v[198:201], v164 offset:32768
	ds_read_b128 v[202:205], v164 offset:33792
	ds_read_b128 v[206:209], v164 offset:34816
	ds_read_b128 v[210:213], v164 offset:35840
	ds_read_b128 v[214:217], v164 offset:36864
	ds_read_b128 v[218:221], v164 offset:37888
	ds_read_b128 v[222:225], v164 offset:38912
	ds_read_b128 v[226:229], v164 offset:39936
	global_load_lds_dwordx4 v[238:239], off
	v_lshl_add_u64 v[238:239], s[52:53], 0, v[140:141]
	s_mov_b32 m0, s29
	s_nop 0
	global_load_lds_dwordx4 v[238:239], off
	s_waitcnt vmcnt(8)
	s_waitcnt lgkmcnt(0)
	s_setprio 1
	s_barrier
	v_mfma_f32_16x16x32_bf16 v[124:127], v[166:169], v[198:201], v[124:127]
	v_mfma_f32_16x16x32_bf16 v[120:123], v[174:177], v[198:201], v[120:123]
	v_mfma_f32_16x16x32_bf16 v[116:119], v[166:169], v[206:209], v[116:119]
	v_mfma_f32_16x16x32_bf16 v[108:111], v[174:177], v[206:209], v[108:111]
	v_mfma_f32_16x16x32_bf16 v[100:103], v[166:169], v[214:217], v[100:103]
	v_mfma_f32_16x16x32_bf16 v[92:95], v[174:177], v[214:217], v[92:95]
	v_mfma_f32_16x16x32_bf16 v[84:87], v[166:169], v[222:225], v[84:87]
	v_mfma_f32_16x16x32_bf16 v[76:79], v[174:177], v[222:225], v[76:79]
	v_mfma_f32_16x16x32_bf16 v[124:127], v[170:173], v[202:205], v[124:127]
	v_mfma_f32_16x16x32_bf16 v[120:123], v[178:181], v[202:205], v[120:123]
	v_mfma_f32_16x16x32_bf16 v[116:119], v[170:173], v[210:213], v[116:119]
	v_mfma_f32_16x16x32_bf16 v[108:111], v[178:181], v[210:213], v[108:111]
	v_mfma_f32_16x16x32_bf16 v[100:103], v[170:173], v[218:221], v[100:103]
	v_mfma_f32_16x16x32_bf16 v[92:95], v[178:181], v[218:221], v[92:95]
	v_mfma_f32_16x16x32_bf16 v[84:87], v[170:173], v[226:229], v[84:87]
	v_mfma_f32_16x16x32_bf16 v[76:79], v[178:181], v[226:229], v[76:79]
	s_setprio 0
	s_setprio 1
	v_mfma_f32_16x16x32_bf16 v[112:115], v[182:185], v[198:201], v[112:115]
	v_mfma_f32_16x16x32_bf16 v[104:107], v[190:193], v[198:201], v[104:107]
	v_mfma_f32_16x16x32_bf16 v[96:99], v[182:185], v[206:209], v[96:99]
	v_mfma_f32_16x16x32_bf16 v[88:91], v[190:193], v[206:209], v[88:91]
	v_mfma_f32_16x16x32_bf16 v[80:83], v[182:185], v[214:217], v[80:83]
	v_mfma_f32_16x16x32_bf16 v[72:75], v[190:193], v[214:217], v[72:75]
	v_mfma_f32_16x16x32_bf16 v[68:71], v[182:185], v[222:225], v[68:71]
	v_mfma_f32_16x16x32_bf16 v[64:67], v[190:193], v[222:225], v[64:67]
	v_mfma_f32_16x16x32_bf16 v[112:115], v[186:189], v[202:205], v[112:115]
	v_mfma_f32_16x16x32_bf16 v[104:107], v[194:197], v[202:205], v[104:107]
	v_mfma_f32_16x16x32_bf16 v[96:99], v[186:189], v[210:213], v[96:99]
	v_mfma_f32_16x16x32_bf16 v[88:91], v[194:197], v[210:213], v[88:91]
	v_mfma_f32_16x16x32_bf16 v[80:83], v[186:189], v[218:221], v[80:83]
	v_mfma_f32_16x16x32_bf16 v[72:75], v[194:197], v[218:221], v[72:75]
	s_setprio 2
	s_barrier
; #define PG8_STAGE(bufoff, gbase, voff) do { _Pragma("unroll") for (int _i = 0; _i < 2; ++_i) \
;         __builtin_amdgcn_global_load_lds((const unsigned*)((const char*)(gbase) + (voff)[_i]), (PG8_LAS unsigned*)(lds + (bufoff) + ldsw + _i * 8192), 16, 0, 0); } while (0)
; #define PG8_LDA(dst, b, h) do { _Pragma("unroll") for (int m = 0; m < 4; ++m) _Pragma("unroll") for (int k = 0; k < 2; ++k) dst[m][k] = *(const PG8_LAS bf16x8*)(lds + PG8_SA(b, h) + aoff + m * 2048 + k * 1024); } while (0)
; #define PG8_MMA(ai, bj, At, Bt) do { __builtin_amdgcn_s_setprio(1); _Pragma("unroll") for (int m = 0; m < 4; ++m) _Pragma("unroll") for (int n = 0; n < 2; ++n) _Pragma("unroll") for (int k = 0; k < 2; ++k) \
;         acc[ai][bj][m][n] = __builtin_amdgcn_mfma_f32_16x16x32_bf16(Bt[n][k], At[m][k], acc[ai][bj][m][n], 0, 0, 0); __builtin_amdgcn_s_setprio(0); } while (0)
; #define PG8_WAIT_V(n) asm volatile("s_waitcnt vmcnt(" #n ")" ::: "memory")
; #define PG8_WAIT_L(n) asm volatile("s_waitcnt lgkmcnt(" #n ")" ::: "memory")
; #define PG8_BAR __builtin_amdgcn_s_barrier()
; #define PG8_SCHED __builtin_amdgcn_sched_barrier(0)
; template <class Epi, class Sched, bool ALIGN_EPI = false, bool SP2 = false>
; __device__ __forceinline__ void gemm_phase(PG8_LAS unsigned char* lds, const Gemm g, const Sched& S, const Epi& E) {
;     ...
;             PG8_WAIT_V(8); PG8_WAIT_L(0); PG8_BAR; PG8_MMA(0, 0, At, B0); PG8_MMA(0, 1, At, B1); PG8_BAR; PG8_SCHED;
;             PG8_LDA(At, 1, 1); PG8_STAGE(PG8_SB(1, 0), b3, voffB); PG8_STAGE(PG8_SB(1, 1), b3 + hstep, voffB); PG8_STAGE(PG8_SA(1, 0), a3, voffA);
;             PG8_WAIT_V(8); PG8_WAIT_L(0); PG8_BAR; PG8_MMA(1, 0, At, B0); PG8_MMA(1, 1, At, B1); PG8_BAR; PG8_SCHED;
;     ...
;         if constexpr (ALIGN_EPI) { if (wr == 0) PG8_BAR; }
	v_mfma_f32_16x16x32_bf16 v[68:71], v[186:189], v[226:229], v[68:71]
	v_mfma_f32_16x16x32_bf16 v[64:67], v[194:197], v[226:229], v[64:67]
	s_setprio 0
	s_mov_b32 m0, s89
	v_lshl_add_u64 v[230:231], v[230:231], 0, s[12:13]
	ds_read_b128 v[198:201], v164 offset:49152
	ds_read_b128 v[202:205], v164 offset:50176
	ds_read_b128 v[206:209], v164 offset:51200
	ds_read_b128 v[210:213], v164 offset:52224
	ds_read_b128 v[214:217], v164 offset:53248
	ds_read_b128 v[218:221], v164 offset:54272
	ds_read_b128 v[222:225], v164 offset:55296
	ds_read_b128 v[226:229], v164 offset:56320
	global_load_lds_dwordx4 v[230:231], off
	s_add_i32 m0, s89, 0x2000
	s_add_u32 s52, s76, 0x80080
	v_lshl_add_u64 v[230:231], v[232:233], 0, s[12:13]
	s_addc_u32 s53, s77, 0
	s_add_i32 s56, s88, s3
	global_load_lds_dwordx4 v[230:231], off
	v_lshl_add_u64 v[230:231], s[52:53], 0, v[138:139]
	s_mov_b32 m0, s56
	s_nop 0
	global_load_lds_dwordx4 v[230:231], off
	v_lshl_add_u64 v[230:231], s[52:53], 0, v[142:143]
	s_add_i32 m0, s56, 0x2000
	s_nop 0
	global_load_lds_dwordx4 v[230:231], off
	v_lshl_add_u64 v[230:231], v[234:235], 0, s[12:13]
	s_mov_b32 m0, s38
	s_nop 0
	global_load_lds_dwordx4 v[230:231], off
	v_lshl_add_u64 v[230:231], v[236:237], 0, s[12:13]
	s_mov_b32 m0, s39
	s_nop 0
	global_load_lds_dwordx4 v[230:231], off
	s_waitcnt vmcnt(8)
	s_waitcnt lgkmcnt(0)
	s_setprio 1
	s_barrier
	v_mfma_f32_16x16x32_bf16 v[60:63], v[166:169], v[198:201], v[60:63]
	v_mfma_f32_16x16x32_bf16 v[56:59], v[174:177], v[198:201], v[56:59]
	v_mfma_f32_16x16x32_bf16 v[52:55], v[166:169], v[206:209], v[52:55]
	v_mfma_f32_16x16x32_bf16 v[44:47], v[174:177], v[206:209], v[44:47]
	v_mfma_f32_16x16x32_bf16 v[36:39], v[166:169], v[214:217], v[36:39]
	v_mfma_f32_16x16x32_bf16 v[28:31], v[174:177], v[214:217], v[28:31]
	v_mfma_f32_16x16x32_bf16 v[20:23], v[166:169], v[222:225], v[20:23]
	v_mfma_f32_16x16x32_bf16 v[12:15], v[174:177], v[222:225], v[12:15]
	v_mfma_f32_16x16x32_bf16 v[60:63], v[170:173], v[202:205], v[60:63]
	v_mfma_f32_16x16x32_bf16 v[56:59], v[178:181], v[202:205], v[56:59]
	v_mfma_f32_16x16x32_bf16 v[52:55], v[170:173], v[210:213], v[52:55]
	v_mfma_f32_16x16x32_bf16 v[44:47], v[178:181], v[210:213], v[44:47]
	v_mfma_f32_16x16x32_bf16 v[36:39], v[170:173], v[218:221], v[36:39]
	v_mfma_f32_16x16x32_bf16 v[28:31], v[178:181], v[218:221], v[28:31]
	v_mfma_f32_16x16x32_bf16 v[20:23], v[170:173], v[226:229], v[20:23]
	v_mfma_f32_16x16x32_bf16 v[12:15], v[178:181], v[226:229], v[12:15]
	s_setprio 0
	s_setprio 1
	v_mfma_f32_16x16x32_bf16 v[48:51], v[182:185], v[198:201], v[48:51]
	v_mfma_f32_16x16x32_bf16 v[40:43], v[190:193], v[198:201], v[40:43]
	v_mfma_f32_16x16x32_bf16 v[32:35], v[182:185], v[206:209], v[32:35]
	v_mfma_f32_16x16x32_bf16 v[24:27], v[190:193], v[206:209], v[24:27]
	v_mfma_f32_16x16x32_bf16 v[16:19], v[182:185], v[214:217], v[16:19]
	v_mfma_f32_16x16x32_bf16 v[8:11], v[190:193], v[214:217], v[8:11]
	v_mfma_f32_16x16x32_bf16 v[4:7], v[182:185], v[222:225], v[4:7]
	v_mfma_f32_16x16x32_bf16 v[0:3], v[190:193], v[222:225], v[0:3]
	v_mfma_f32_16x16x32_bf16 v[48:51], v[186:189], v[202:205], v[48:51]
	v_mfma_f32_16x16x32_bf16 v[40:43], v[194:197], v[202:205], v[40:43]
	v_mfma_f32_16x16x32_bf16 v[32:35], v[186:189], v[210:213], v[32:35]
	v_mfma_f32_16x16x32_bf16 v[24:27], v[194:197], v[210:213], v[24:27]
	v_mfma_f32_16x16x32_bf16 v[16:19], v[186:189], v[218:221], v[16:19]
	v_mfma_f32_16x16x32_bf16 v[8:11], v[194:197], v[218:221], v[8:11]
	s_setprio 2
	s_barrier
	v_mfma_f32_16x16x32_bf16 v[4:7], v[186:189], v[226:229], v[4:7]
	v_mfma_f32_16x16x32_bf16 v[0:3], v[194:197], v[226:229], v[0:3]
	s_setprio 0
	s_add_i32 s51, s51, 2
	s_add_u32 s74, s74, 0x100
	s_addc_u32 s75, s75, 0
	s_add_u32 s37, s37, 0x100
	s_addc_u32 s49, s49, 0
	s_cmp_gt_u32 s51, 5
	s_cbranch_scc0 .LBB0_410
	s_and_b64 vcc, exec, s[14:15]
	s_cbranch_vccz .LBB0_413
	s_barrier

; #define PG8_STAGE(bufoff, gbase, voff) do { _Pragma("unroll") for (int _i = 0; _i < 2; ++_i) \
;         __builtin_amdgcn_global_load_lds((const unsigned*)((const char*)(gbase) + (voff)[_i]), (PG8_LAS unsigned*)(lds + (bufoff) + ldsw + _i * 8192), 16, 0, 0); } while (0)
; #define PG8_LDA(dst, b, h) do { _Pragma("unroll") for (int m = 0; m < 4; ++m) _Pragma("unroll") for (int k = 0; k < 2; ++k) dst[m][k] = *(const PG8_LAS bf16x8*)(lds + PG8_SA(b, h) + aoff + m * 2048 + k * 1024); } while (0)
; #define PG8_LDB(dst, b, h) do { _Pragma("unroll") for (int n = 0; n < 2; ++n) _Pragma("unroll") for (int k = 0; k < 2; ++k) dst[n][k] = *(const PG8_LAS bf16x8*)(lds + PG8_SB(b, h) + boff + n * 2048 + k * 1024); } while (0)
; #define PG8_MMA(ai, bj, At, Bt) do { __builtin_amdgcn_s_setprio(1); _Pragma("unroll") for (int m = 0; m < 4; ++m) _Pragma("unroll") for (int n = 0; n < 2; ++n) _Pragma("unroll") for (int k = 0; k < 2; ++k) \
;         acc[ai][bj][m][n] = __builtin_amdgcn_mfma_f32_16x16x32_bf16(Bt[n][k], At[m][k], acc[ai][bj][m][n], 0, 0, 0); __builtin_amdgcn_s_setprio(0); } while (0)
; #define PG8_WAIT_V(n) asm volatile("s_waitcnt vmcnt(" #n ")" ::: "memory")
; #define PG8_WAIT_L(n) asm volatile("s_waitcnt lgkmcnt(" #n ")" ::: "memory")
; #define PG8_BAR __builtin_amdgcn_s_barrier()
; #define PG8_SCHED __builtin_amdgcn_sched_barrier(0)
; template <class Epi, class Sched, bool ALIGN_EPI = false, bool SP2 = false>
; __device__ __forceinline__ void gemm_phase(PG8_LAS unsigned char* lds, const Gemm g, const Sched& S, const Epi& E) {
;     ...
;         for (int t = 0; t < nt; t += 2) {
;             const bool last = (t == nt - 2);
;             const char* a1 = cA + (size_t)(t + 1) * kstep;
;             const char* a2 = last ? nA : cA + (size_t)(t + 2) * kstep; const char* b2 = last ? nB : cB + (size_t)(t + 2) * kstep;
;             const char* a3 = a2 + kstep; const char* b3 = b2 + kstep;
;             if constexpr (SP2) {
;             PG8_LDB(B0, 0, 0); PG8_LDB(B1, 0, 1); PG8_SCHED; PG8_LDA(At, 0, 0); PG8_STAGE(PG8_SA(1, 1), a1 + hstep, voffA);
;             PG8_WAIT_V(8); PG8_WAIT_L(0); PG8_BAR; PG8_MMA(0, 0, At, B0); PG8_MMA(0, 1, At, B1); PG8_BAR; PG8_SCHED;
;             PG8_LDA(At, 0, 1); PG8_STAGE(PG8_SB(0, 0), b2, voffB); PG8_STAGE(PG8_SB(0, 1), b2 + hstep, voffB); PG8_STAGE(PG8_SA(0, 0), a2, voffA);
.LBB0_545:
	ds_read_b128 v[112:115], v174
	ds_read_b128 v[116:119], v174 offset:1024
	ds_read_b128 v[120:123], v174 offset:2048
	ds_read_b128 v[124:127], v174 offset:3072
	ds_read_b128 v[164:167], v175
	ds_read_b128 v[168:171], v175 offset:1024
	ds_read_b128 v[178:181], v175 offset:2048
	ds_read_b128 v[182:185], v175 offset:3072
	s_add_u32 s52, s68, 0xfff80080
	s_addc_u32 s53, s69, -1
	s_cmp_eq_u32 s88, 28
	s_cselect_b32 s73, s41, s53
	s_cselect_b32 s72, s84, s52
	s_cselect_b32 s71, s37, s87
	s_cselect_b32 s70, s85, s86
	v_lshl_add_u64 v[218:219], s[68:69], 0, v[156:157]
	s_add_i32 m0, s39, 0xc000
	ds_read_b128 v[186:189], v176
	ds_read_b128 v[190:193], v176 offset:1024
	ds_read_b128 v[194:197], v176 offset:2048
	ds_read_b128 v[198:201], v176 offset:3072
	ds_read_b128 v[202:205], v176 offset:4096
	ds_read_b128 v[206:209], v176 offset:5120
	ds_read_b128 v[210:213], v176 offset:6144
	ds_read_b128 v[214:217], v176 offset:7168
	global_load_lds_dwordx4 v[218:219], off
	v_lshl_add_u64 v[218:219], s[68:69], 0, v[158:159]
	s_add_i32 m0, s39, 0xe000
	s_nop 0
	global_load_lds_dwordx4 v[218:219], off
	s_waitcnt vmcnt(8)
	s_waitcnt lgkmcnt(0)
	s_setprio 1
	s_barrier
	v_mfma_f32_16x16x32_bf16 v[140:143], v[112:115], v[186:189], v[140:143]
	v_mfma_f32_16x16x32_bf16 v[136:139], v[120:123], v[186:189], v[136:139]
	v_mfma_f32_16x16x32_bf16 v[108:111], v[112:115], v[194:197], v[108:111]
	v_mfma_f32_16x16x32_bf16 v[104:107], v[120:123], v[194:197], v[104:107]
	v_mfma_f32_16x16x32_bf16 v[92:95], v[112:115], v[202:205], v[92:95]
	v_mfma_f32_16x16x32_bf16 v[88:91], v[120:123], v[202:205], v[88:91]
	v_mfma_f32_16x16x32_bf16 v[76:79], v[112:115], v[210:213], v[76:79]
	v_mfma_f32_16x16x32_bf16 v[72:75], v[120:123], v[210:213], v[72:75]
	v_mfma_f32_16x16x32_bf16 v[140:143], v[116:119], v[190:193], v[140:143]
	v_mfma_f32_16x16x32_bf16 v[136:139], v[124:127], v[190:193], v[136:139]
	v_mfma_f32_16x16x32_bf16 v[108:111], v[116:119], v[198:201], v[108:111]
	v_mfma_f32_16x16x32_bf16 v[104:107], v[124:127], v[198:201], v[104:107]
	v_mfma_f32_16x16x32_bf16 v[92:95], v[116:119], v[206:209], v[92:95]
	v_mfma_f32_16x16x32_bf16 v[88:91], v[124:127], v[206:209], v[88:91]
	v_mfma_f32_16x16x32_bf16 v[76:79], v[116:119], v[214:217], v[76:79]
	v_mfma_f32_16x16x32_bf16 v[72:75], v[124:127], v[214:217], v[72:75]
	s_setprio 0
	s_setprio 1
	v_mfma_f32_16x16x32_bf16 v[132:135], v[164:167], v[186:189], v[132:135]
	v_mfma_f32_16x16x32_bf16 v[128:131], v[178:181], v[186:189], v[128:131]
	v_mfma_f32_16x16x32_bf16 v[100:103], v[164:167], v[194:197], v[100:103]
	v_mfma_f32_16x16x32_bf16 v[96:99], v[178:181], v[194:197], v[96:99]
	v_mfma_f32_16x16x32_bf16 v[84:87], v[164:167], v[202:205], v[84:87]
	v_mfma_f32_16x16x32_bf16 v[80:83], v[178:181], v[202:205], v[80:83]
	v_mfma_f32_16x16x32_bf16 v[68:71], v[164:167], v[210:213], v[68:71]
	v_mfma_f32_16x16x32_bf16 v[64:67], v[178:181], v[210:213], v[64:67]
	v_mfma_f32_16x16x32_bf16 v[132:135], v[168:171], v[190:193], v[132:135]
	v_mfma_f32_16x16x32_bf16 v[128:131], v[182:185], v[190:193], v[128:131]
	v_mfma_f32_16x16x32_bf16 v[100:103], v[168:171], v[198:201], v[100:103]
	v_mfma_f32_16x16x32_bf16 v[96:99], v[182:185], v[198:201], v[96:99]
	v_mfma_f32_16x16x32_bf16 v[84:87], v[168:171], v[206:209], v[84:87]
	v_mfma_f32_16x16x32_bf16 v[80:83], v[182:185], v[206:209], v[80:83]
	s_setprio 2
	s_barrier
	v_mfma_f32_16x16x32_bf16 v[68:71], v[168:171], v[214:217], v[68:71]
	v_mfma_f32_16x16x32_bf16 v[64:67], v[182:185], v[214:217], v[64:67]
	s_setprio 0
	s_add_i32 s52, s81, s29
	v_lshl_add_u64 v[218:219], s[70:71], 0, v[152:153]
	s_mov_b32 m0, s52
	ds_read_b128 v[186:189], v176 offset:16384
	ds_read_b128 v[190:193], v176 offset:17408
	ds_read_b128 v[194:197], v176 offset:18432
	ds_read_b128 v[198:201], v176 offset:19456
	ds_read_b128 v[202:205], v176 offset:20480
	ds_read_b128 v[206:209], v176 offset:21504
	ds_read_b128 v[210:213], v176 offset:22528
	ds_read_b128 v[214:217], v176 offset:23552
	global_load_lds_dwordx4 v[218:219], off
	s_add_i32 m0, s52, 0x2000
	s_add_u32 s52, s70, 0x80000
	v_lshl_add_u64 v[220:221], s[70:71], 0, v[148:149]
	s_addc_u32 s53, s71, 0
	s_add_i32 s56, s82, s29
	global_load_lds_dwordx4 v[220:221], off
	v_lshl_add_u64 v[222:223], s[52:53], 0, v[152:153]
	s_mov_b32 m0, s56
	v_lshl_add_u64 v[224:225], s[72:73], 0, v[150:151]
	global_load_lds_dwordx4 v[222:223], off
	v_lshl_add_u64 v[222:223], s[52:53], 0, v[148:149]
	s_add_i32 m0, s56, 0x2000
	s_nop 0
	global_load_lds_dwordx4 v[222:223], off
	v_lshl_add_u64 v[222:223], s[72:73], 0, v[154:155]
	s_mov_b32 m0, s39
	s_nop 0
	global_load_lds_dwordx4 v[222:223], off
	s_mov_b32 m0, s55
	s_nop 0
	global_load_lds_dwordx4 v[224:225], off
	s_waitcnt vmcnt(8)
	s_waitcnt lgkmcnt(0)
	s_setprio 1
	s_barrier
; #define PG8_STAGE(bufoff, gbase, voff) do { _Pragma("unroll") for (int _i = 0; _i < 2; ++_i) \
;         __builtin_amdgcn_global_load_lds((const unsigned*)((const char*)(gbase) + (voff)[_i]), (PG8_LAS unsigned*)(lds + (bufoff) + ldsw + _i * 8192), 16, 0, 0); } while (0)
; #define PG8_LDA(dst, b, h) do { _Pragma("unroll") for (int m = 0; m < 4; ++m) _Pragma("unroll") for (int k = 0; k < 2; ++k) dst[m][k] = *(const PG8_LAS bf16x8*)(lds + PG8_SA(b, h) + aoff + m * 2048 + k * 1024); } while (0)
; #define PG8_LDB(dst, b, h) do { _Pragma("unroll") for (int n = 0; n < 2; ++n) _Pragma("unroll") for (int k = 0; k < 2; ++k) dst[n][k] = *(const PG8_LAS bf16x8*)(lds + PG8_SB(b, h) + boff + n * 2048 + k * 1024); } while (0)
; #define PG8_MMA(ai, bj, At, Bt) do { __builtin_amdgcn_s_setprio(1); _Pragma("unroll") for (int m = 0; m < 4; ++m) _Pragma("unroll") for (int n = 0; n < 2; ++n) _Pragma("unroll") for (int k = 0; k < 2; ++k) \
;         acc[ai][bj][m][n] = __builtin_amdgcn_mfma_f32_16x16x32_bf16(Bt[n][k], At[m][k], acc[ai][bj][m][n], 0, 0, 0); __builtin_amdgcn_s_setprio(0); } while (0)
; #define PG8_WAIT_V(n) asm volatile("s_waitcnt vmcnt(" #n ")" ::: "memory")
; #define PG8_WAIT_L(n) asm volatile("s_waitcnt lgkmcnt(" #n ")" ::: "memory")
; #define PG8_BAR __builtin_amdgcn_s_barrier()
; #define PG8_SCHED __builtin_amdgcn_sched_barrier(0)
; template <class Epi, class Sched, bool ALIGN_EPI = false, bool SP2 = false>
; __device__ __forceinline__ void gemm_phase(PG8_LAS unsigned char* lds, const Gemm g, const Sched& S, const Epi& E) {
;     ...
;             PG8_WAIT_V(8); PG8_WAIT_L(0); PG8_BAR; PG8_MMA(1, 0, At, B0); PG8_MMA(1, 1, At, B1); PG8_BAR; PG8_SCHED;
;             PG8_LDB(B0, 1, 0); PG8_LDB(B1, 1, 1); PG8_SCHED; PG8_LDA(At, 1, 0); PG8_STAGE(PG8_SA(0, 1), a2 + hstep, voffA);
;             PG8_WAIT_V(8); PG8_WAIT_L(0); PG8_BAR; PG8_MMA(0, 0, At, B0); PG8_MMA(0, 1, At, B1); PG8_BAR; PG8_SCHED;
	v_mfma_f32_16x16x32_bf16 v[60:63], v[112:115], v[186:189], v[60:63]
	v_mfma_f32_16x16x32_bf16 v[56:59], v[120:123], v[186:189], v[56:59]
	v_mfma_f32_16x16x32_bf16 v[44:47], v[112:115], v[194:197], v[44:47]
	v_mfma_f32_16x16x32_bf16 v[40:43], v[120:123], v[194:197], v[40:43]
	v_mfma_f32_16x16x32_bf16 v[28:31], v[112:115], v[202:205], v[28:31]
	v_mfma_f32_16x16x32_bf16 v[24:27], v[120:123], v[202:205], v[24:27]
	v_mfma_f32_16x16x32_bf16 v[12:15], v[112:115], v[210:213], v[12:15]
	v_mfma_f32_16x16x32_bf16 v[8:11], v[120:123], v[210:213], v[8:11]
	v_mfma_f32_16x16x32_bf16 v[60:63], v[116:119], v[190:193], v[60:63]
	v_mfma_f32_16x16x32_bf16 v[56:59], v[124:127], v[190:193], v[56:59]
	v_mfma_f32_16x16x32_bf16 v[44:47], v[116:119], v[198:201], v[44:47]
	v_mfma_f32_16x16x32_bf16 v[40:43], v[124:127], v[198:201], v[40:43]
	v_mfma_f32_16x16x32_bf16 v[28:31], v[116:119], v[206:209], v[28:31]
	v_mfma_f32_16x16x32_bf16 v[24:27], v[124:127], v[206:209], v[24:27]
	v_mfma_f32_16x16x32_bf16 v[12:15], v[116:119], v[214:217], v[12:15]
	v_mfma_f32_16x16x32_bf16 v[8:11], v[124:127], v[214:217], v[8:11]
	s_setprio 0
	s_setprio 1
	v_mfma_f32_16x16x32_bf16 v[52:55], v[164:167], v[186:189], v[52:55]
	v_mfma_f32_16x16x32_bf16 v[48:51], v[178:181], v[186:189], v[48:51]
	v_mfma_f32_16x16x32_bf16 v[36:39], v[164:167], v[194:197], v[36:39]
	v_mfma_f32_16x16x32_bf16 v[32:35], v[178:181], v[194:197], v[32:35]
	v_mfma_f32_16x16x32_bf16 v[20:23], v[164:167], v[202:205], v[20:23]
	v_mfma_f32_16x16x32_bf16 v[16:19], v[178:181], v[202:205], v[16:19]
	v_mfma_f32_16x16x32_bf16 v[4:7], v[164:167], v[210:213], v[4:7]
	v_mfma_f32_16x16x32_bf16 v[0:3], v[178:181], v[210:213], v[0:3]
	v_mfma_f32_16x16x32_bf16 v[52:55], v[168:171], v[190:193], v[52:55]
	v_mfma_f32_16x16x32_bf16 v[48:51], v[182:185], v[190:193], v[48:51]
	v_mfma_f32_16x16x32_bf16 v[36:39], v[168:171], v[198:201], v[36:39]
	v_mfma_f32_16x16x32_bf16 v[32:35], v[182:185], v[198:201], v[32:35]
	v_mfma_f32_16x16x32_bf16 v[20:23], v[168:171], v[206:209], v[20:23]
	v_mfma_f32_16x16x32_bf16 v[16:19], v[182:185], v[206:209], v[16:19]
	s_setprio 2
	s_barrier
	v_mfma_f32_16x16x32_bf16 v[4:7], v[168:171], v[214:217], v[4:7]
	v_mfma_f32_16x16x32_bf16 v[0:3], v[182:185], v[214:217], v[0:3]
	s_setprio 0
	s_add_i32 s56, 0, 0x18000
	s_add_i32 s57, 0, 0x1c000
	v_add_u32_e32 v124, s56, v172
	v_add_u32_e32 v177, s57, v172
	ds_read_b128 v[112:115], v124
	ds_read_b128 v[116:119], v124 offset:1024
	ds_read_b128 v[120:123], v124 offset:2048
	ds_read_b128 v[124:127], v124 offset:3072
	ds_read_b128 v[164:167], v177
	ds_read_b128 v[168:171], v177 offset:1024
	ds_read_b128 v[178:181], v177 offset:2048
	ds_read_b128 v[182:185], v177 offset:3072
	s_add_u32 s52, s72, 0x80000
	s_addc_u32 s53, s73, 0
	s_mov_b32 m0, s74
	v_lshl_add_u64 v[226:227], s[52:53], 0, v[154:155]
	ds_read_b128 v[186:189], v176 offset:32768
	ds_read_b128 v[190:193], v176 offset:33792
	ds_read_b128 v[194:197], v176 offset:34816
	ds_read_b128 v[198:201], v176 offset:35840
	ds_read_b128 v[202:205], v176 offset:36864
	ds_read_b128 v[206:209], v176 offset:37888
	ds_read_b128 v[210:213], v176 offset:38912
	ds_read_b128 v[214:217], v176 offset:39936
	global_load_lds_dwordx4 v[226:227], off
	v_lshl_add_u64 v[226:227], s[52:53], 0, v[150:151]
	s_mov_b32 m0, s75
	s_nop 0
	global_load_lds_dwordx4 v[226:227], off
	s_waitcnt vmcnt(8)
	s_waitcnt lgkmcnt(0)
	s_setprio 1
	s_barrier
	v_mfma_f32_16x16x32_bf16 v[140:143], v[112:115], v[186:189], v[140:143]
	v_mfma_f32_16x16x32_bf16 v[136:139], v[120:123], v[186:189], v[136:139]
	v_mfma_f32_16x16x32_bf16 v[108:111], v[112:115], v[194:197], v[108:111]
	v_mfma_f32_16x16x32_bf16 v[104:107], v[120:123], v[194:197], v[104:107]
	v_mfma_f32_16x16x32_bf16 v[92:95], v[112:115], v[202:205], v[92:95]
	v_mfma_f32_16x16x32_bf16 v[88:91], v[120:123], v[202:205], v[88:91]
	v_mfma_f32_16x16x32_bf16 v[76:79], v[112:115], v[210:213], v[76:79]
	v_mfma_f32_16x16x32_bf16 v[72:75], v[120:123], v[210:213], v[72:75]
	v_mfma_f32_16x16x32_bf16 v[140:143], v[116:119], v[190:193], v[140:143]
	v_mfma_f32_16x16x32_bf16 v[136:139], v[124:127], v[190:193], v[136:139]
	v_mfma_f32_16x16x32_bf16 v[108:111], v[116:119], v[198:201], v[108:111]
	v_mfma_f32_16x16x32_bf16 v[104:107], v[124:127], v[198:201], v[104:107]
	v_mfma_f32_16x16x32_bf16 v[92:95], v[116:119], v[206:209], v[92:95]
	v_mfma_f32_16x16x32_bf16 v[88:91], v[124:127], v[206:209], v[88:91]
	v_mfma_f32_16x16x32_bf16 v[76:79], v[116:119], v[214:217], v[76:79]
	v_mfma_f32_16x16x32_bf16 v[72:75], v[124:127], v[214:217], v[72:75]
	s_setprio 0
	s_setprio 1
	v_mfma_f32_16x16x32_bf16 v[132:135], v[164:167], v[186:189], v[132:135]
	v_mfma_f32_16x16x32_bf16 v[128:131], v[178:181], v[186:189], v[128:131]
	v_mfma_f32_16x16x32_bf16 v[100:103], v[164:167], v[194:197], v[100:103]
	v_mfma_f32_16x16x32_bf16 v[96:99], v[178:181], v[194:197], v[96:99]
	v_mfma_f32_16x16x32_bf16 v[84:87], v[164:167], v[202:205], v[84:87]
	v_mfma_f32_16x16x32_bf16 v[80:83], v[178:181], v[202:205], v[80:83]
	v_mfma_f32_16x16x32_bf16 v[68:71], v[164:167], v[210:213], v[68:71]
	v_mfma_f32_16x16x32_bf16 v[64:67], v[178:181], v[210:213], v[64:67]
	v_mfma_f32_16x16x32_bf16 v[132:135], v[168:171], v[190:193], v[132:135]
	v_mfma_f32_16x16x32_bf16 v[128:131], v[182:185], v[190:193], v[128:131]
	v_mfma_f32_16x16x32_bf16 v[100:103], v[168:171], v[198:201], v[100:103]
	v_mfma_f32_16x16x32_bf16 v[96:99], v[182:185], v[198:201], v[96:99]
	v_mfma_f32_16x16x32_bf16 v[84:87], v[168:171], v[206:209], v[84:87]
	v_mfma_f32_16x16x32_bf16 v[80:83], v[182:185], v[206:209], v[80:83]
	s_setprio 2
	s_barrier
; #define PG8_STAGE(bufoff, gbase, voff) do { _Pragma("unroll") for (int _i = 0; _i < 2; ++_i) \
;         __builtin_amdgcn_global_load_lds((const unsigned*)((const char*)(gbase) + (voff)[_i]), (PG8_LAS unsigned*)(lds + (bufoff) + ldsw + _i * 8192), 16, 0, 0); } while (0)
; #define PG8_LDA(dst, b, h) do { _Pragma("unroll") for (int m = 0; m < 4; ++m) _Pragma("unroll") for (int k = 0; k < 2; ++k) dst[m][k] = *(const PG8_LAS bf16x8*)(lds + PG8_SA(b, h) + aoff + m * 2048 + k * 1024); } while (0)
; #define PG8_MMA(ai, bj, At, Bt) do { __builtin_amdgcn_s_setprio(1); _Pragma("unroll") for (int m = 0; m < 4; ++m) _Pragma("unroll") for (int n = 0; n < 2; ++n) _Pragma("unroll") for (int k = 0; k < 2; ++k) \
;         acc[ai][bj][m][n] = __builtin_amdgcn_mfma_f32_16x16x32_bf16(Bt[n][k], At[m][k], acc[ai][bj][m][n], 0, 0, 0); __builtin_amdgcn_s_setprio(0); } while (0)
; #define PG8_WAIT_V(n) asm volatile("s_waitcnt vmcnt(" #n ")" ::: "memory")
; #define PG8_WAIT_L(n) asm volatile("s_waitcnt lgkmcnt(" #n ")" ::: "memory")
; #define PG8_BAR __builtin_amdgcn_s_barrier()
; #define PG8_SCHED __builtin_amdgcn_sched_barrier(0)
; template <class Epi, class Sched, bool ALIGN_EPI = false, bool SP2 = false>
; __device__ __forceinline__ void gemm_phase(PG8_LAS unsigned char* lds, const Gemm g, const Sched& S, const Epi& E) {
;     ...
;             PG8_WAIT_V(8); PG8_WAIT_L(0); PG8_BAR; PG8_MMA(0, 0, At, B0); PG8_MMA(0, 1, At, B1); PG8_BAR; PG8_SCHED;
;             PG8_LDA(At, 1, 1); PG8_STAGE(PG8_SB(1, 0), b3, voffB); PG8_STAGE(PG8_SB(1, 1), b3 + hstep, voffB); PG8_STAGE(PG8_SA(1, 0), a3, voffA);
;             PG8_WAIT_V(8); PG8_WAIT_L(0); PG8_BAR; PG8_MMA(1, 0, At, B0); PG8_MMA(1, 1, At, B1); PG8_BAR; PG8_SCHED;
;     ...
;         if constexpr (ALIGN_EPI) { if (wr == 0) PG8_BAR; }
	v_mfma_f32_16x16x32_bf16 v[68:71], v[168:171], v[214:217], v[68:71]
	v_mfma_f32_16x16x32_bf16 v[64:67], v[182:185], v[214:217], v[64:67]
	s_setprio 0
	s_add_i32 s52, s56, s29
	v_lshl_add_u64 v[218:219], v[218:219], 0, s[12:13]
	s_mov_b32 m0, s52
	ds_read_b128 v[186:189], v176 offset:49152
	ds_read_b128 v[190:193], v176 offset:50176
	ds_read_b128 v[194:197], v176 offset:51200
	ds_read_b128 v[198:201], v176 offset:52224
	ds_read_b128 v[202:205], v176 offset:53248
	ds_read_b128 v[206:209], v176 offset:54272
	ds_read_b128 v[210:213], v176 offset:55296
	ds_read_b128 v[214:217], v176 offset:56320
	global_load_lds_dwordx4 v[218:219], off
	s_add_i32 m0, s52, 0x2000
	s_add_u32 s52, s70, 0x80080
	v_lshl_add_u64 v[218:219], v[220:221], 0, s[12:13]
	s_addc_u32 s53, s71, 0
	s_add_i32 s56, s57, s29
	global_load_lds_dwordx4 v[218:219], off
	v_lshl_add_u64 v[218:219], s[52:53], 0, v[152:153]
	s_mov_b32 m0, s56
	s_nop 0
	global_load_lds_dwordx4 v[218:219], off
	v_lshl_add_u64 v[218:219], s[52:53], 0, v[148:149]
	s_add_i32 m0, s56, 0x2000
	s_nop 0
	global_load_lds_dwordx4 v[218:219], off
	v_lshl_add_u64 v[218:219], v[222:223], 0, s[12:13]
	s_mov_b32 m0, s77
	s_nop 0
	global_load_lds_dwordx4 v[218:219], off
	v_lshl_add_u64 v[218:219], v[224:225], 0, s[12:13]
	s_mov_b32 m0, s78
	s_nop 0
	global_load_lds_dwordx4 v[218:219], off
	s_waitcnt vmcnt(8)
	s_waitcnt lgkmcnt(0)
	s_setprio 1
	s_barrier
	v_mfma_f32_16x16x32_bf16 v[60:63], v[112:115], v[186:189], v[60:63]
	v_mfma_f32_16x16x32_bf16 v[56:59], v[120:123], v[186:189], v[56:59]
	v_mfma_f32_16x16x32_bf16 v[44:47], v[112:115], v[194:197], v[44:47]
	v_mfma_f32_16x16x32_bf16 v[40:43], v[120:123], v[194:197], v[40:43]
	v_mfma_f32_16x16x32_bf16 v[28:31], v[112:115], v[202:205], v[28:31]
	v_mfma_f32_16x16x32_bf16 v[24:27], v[120:123], v[202:205], v[24:27]
	v_mfma_f32_16x16x32_bf16 v[12:15], v[112:115], v[210:213], v[12:15]
	v_mfma_f32_16x16x32_bf16 v[8:11], v[120:123], v[210:213], v[8:11]
	v_mfma_f32_16x16x32_bf16 v[60:63], v[116:119], v[190:193], v[60:63]
	v_mfma_f32_16x16x32_bf16 v[56:59], v[124:127], v[190:193], v[56:59]
	v_mfma_f32_16x16x32_bf16 v[44:47], v[116:119], v[198:201], v[44:47]
	v_mfma_f32_16x16x32_bf16 v[40:43], v[124:127], v[198:201], v[40:43]
	v_mfma_f32_16x16x32_bf16 v[28:31], v[116:119], v[206:209], v[28:31]
	v_mfma_f32_16x16x32_bf16 v[24:27], v[124:127], v[206:209], v[24:27]
	v_mfma_f32_16x16x32_bf16 v[12:15], v[116:119], v[214:217], v[12:15]
	v_mfma_f32_16x16x32_bf16 v[8:11], v[124:127], v[214:217], v[8:11]
	s_setprio 0
	s_setprio 1
	v_mfma_f32_16x16x32_bf16 v[52:55], v[164:167], v[186:189], v[52:55]
	v_mfma_f32_16x16x32_bf16 v[48:51], v[178:181], v[186:189], v[48:51]
	v_mfma_f32_16x16x32_bf16 v[36:39], v[164:167], v[194:197], v[36:39]
	v_mfma_f32_16x16x32_bf16 v[32:35], v[178:181], v[194:197], v[32:35]
	v_mfma_f32_16x16x32_bf16 v[20:23], v[164:167], v[202:205], v[20:23]
	v_mfma_f32_16x16x32_bf16 v[16:19], v[178:181], v[202:205], v[16:19]
	v_mfma_f32_16x16x32_bf16 v[4:7], v[164:167], v[210:213], v[4:7]
	v_mfma_f32_16x16x32_bf16 v[0:3], v[178:181], v[210:213], v[0:3]
	v_mfma_f32_16x16x32_bf16 v[52:55], v[168:171], v[190:193], v[52:55]
	v_mfma_f32_16x16x32_bf16 v[48:51], v[182:185], v[190:193], v[48:51]
	v_mfma_f32_16x16x32_bf16 v[36:39], v[168:171], v[198:201], v[36:39]
	v_mfma_f32_16x16x32_bf16 v[32:35], v[182:185], v[198:201], v[32:35]
	v_mfma_f32_16x16x32_bf16 v[20:23], v[168:171], v[206:209], v[20:23]
	v_mfma_f32_16x16x32_bf16 v[16:19], v[182:185], v[206:209], v[16:19]
	s_setprio 2
	s_barrier
	v_mfma_f32_16x16x32_bf16 v[4:7], v[168:171], v[214:217], v[4:7]
	v_mfma_f32_16x16x32_bf16 v[0:3], v[182:185], v[214:217], v[0:3]
	s_setprio 0
	s_add_i32 s88, s88, 2
	s_add_u32 s68, s68, 0x100
	s_addc_u32 s69, s69, 0
	s_add_u32 s86, s86, 0x100
	s_addc_u32 s87, s87, 0
	s_cmp_gt_u32 s88, 29
	s_cbranch_scc0 .LBB0_545
	s_and_b64 vcc, exec, s[14:15]
	s_cbranch_vccz .LBB0_548
	s_barrier

; #define PG8_STAGE(bufoff, gbase, voff) do { _Pragma("unroll") for (int _i = 0; _i < 2; ++_i) \
;         __builtin_amdgcn_global_load_lds((const unsigned*)((const char*)(gbase) + (voff)[_i]), (PG8_LAS unsigned*)(lds + (bufoff) + ldsw + _i * 8192), 16, 0, 0); } while (0)
; #define PG8_LDA(dst, b, h) do { _Pragma("unroll") for (int m = 0; m < 4; ++m) _Pragma("unroll") for (int k = 0; k < 2; ++k) dst[m][k] = *(const PG8_LAS bf16x8*)(lds + PG8_SA(b, h) + aoff + m * 2048 + k * 1024); } while (0)
; #define PG8_LDB(dst, b, h) do { _Pragma("unroll") for (int n = 0; n < 2; ++n) _Pragma("unroll") for (int k = 0; k < 2; ++k) dst[n][k] = *(const PG8_LAS bf16x8*)(lds + PG8_SB(b, h) + boff + n * 2048 + k * 1024); } while (0)
; #define PG8_MMA(ai, bj, At, Bt) do { __builtin_amdgcn_s_setprio(1); _Pragma("unroll") for (int m = 0; m < 4; ++m) _Pragma("unroll") for (int n = 0; n < 2; ++n) _Pragma("unroll") for (int k = 0; k < 2; ++k) \
;         acc[ai][bj][m][n] = __builtin_amdgcn_mfma_f32_16x16x32_bf16(Bt[n][k], At[m][k], acc[ai][bj][m][n], 0, 0, 0); __builtin_amdgcn_s_setprio(0); } while (0)
; #define PG8_WAIT_V(n) asm volatile("s_waitcnt vmcnt(" #n ")" ::: "memory")
; #define PG8_WAIT_L(n) asm volatile("s_waitcnt lgkmcnt(" #n ")" ::: "memory")
; #define PG8_BAR __builtin_amdgcn_s_barrier()
; #define PG8_SCHED __builtin_amdgcn_sched_barrier(0)
; template <class Epi, class Sched, bool ALIGN_EPI = false, bool SP2 = false>
; __device__ __forceinline__ void gemm_phase(PG8_LAS unsigned char* lds, const Gemm g, const Sched& S, const Epi& E) {
;     ...
;         for (int t = 0; t < nt; t += 2) {
;             const bool last = (t == nt - 2);
;             const char* a1 = cA + (size_t)(t + 1) * kstep;
;             const char* a2 = last ? nA : cA + (size_t)(t + 2) * kstep; const char* b2 = last ? nB : cB + (size_t)(t + 2) * kstep;
;             const char* a3 = a2 + kstep; const char* b3 = b2 + kstep;
;             if constexpr (SP2) {
;             PG8_LDB(B0, 0, 0); PG8_LDB(B1, 0, 1); PG8_SCHED; PG8_LDA(At, 0, 0); PG8_STAGE(PG8_SA(1, 1), a1 + hstep, voffA);
;             PG8_WAIT_V(8); PG8_WAIT_L(0); PG8_BAR; PG8_MMA(0, 0, At, B0); PG8_MMA(0, 1, At, B1); PG8_BAR; PG8_SCHED;
;             PG8_LDA(At, 0, 1); PG8_STAGE(PG8_SB(0, 0), b2, voffB); PG8_STAGE(PG8_SB(0, 1), b2 + hstep, voffB); PG8_STAGE(PG8_SA(0, 0), a2, voffA);
.LBB0_624:
	ds_read_b128 v[128:131], v214
	ds_read_b128 v[132:135], v214 offset:1024
	ds_read_b128 v[158:161], v214 offset:2048
	ds_read_b128 v[162:165], v214 offset:3072
	ds_read_b128 v[166:169], v215
	ds_read_b128 v[170:173], v215 offset:1024
	ds_read_b128 v[174:177], v215 offset:2048
	ds_read_b128 v[178:181], v215 offset:3072
	s_add_u32 s52, s74, 0xffe00080
	s_addc_u32 s53, s75, -1
	s_cmpk_eq_i32 vcc_hi, 0x7c
	s_cselect_b32 s79, s51, s53
	s_cselect_b32 s78, s71, s52
	s_cselect_b32 s77, s49, vcc_lo
	s_cselect_b32 s76, s73, s93
	v_lshl_add_u64 v[226:227], s[74:75], 0, v[150:151]
	s_add_i32 m0, s83, 0xc000
	ds_read_b128 v[182:185], v216
	ds_read_b128 v[186:189], v216 offset:1024
	ds_read_b128 v[190:193], v216 offset:2048
	ds_read_b128 v[194:197], v216 offset:3072
	ds_read_b128 v[198:201], v216 offset:4096
	ds_read_b128 v[202:205], v216 offset:5120
	ds_read_b128 v[218:221], v216 offset:6144
	ds_read_b128 v[222:225], v216 offset:7168
	global_load_lds_dwordx4 v[226:227], off
	v_lshl_add_u64 v[226:227], s[74:75], 0, v[152:153]
	s_add_i32 m0, s83, 0xe000
	s_nop 0
	global_load_lds_dwordx4 v[226:227], off
	s_waitcnt vmcnt(8)
	s_waitcnt lgkmcnt(0)
	s_setprio 1
	s_barrier
	v_mfma_f32_16x16x32_bf16 v[124:127], v[128:131], v[182:185], v[124:127]
	v_mfma_f32_16x16x32_bf16 v[120:123], v[158:161], v[182:185], v[120:123]
	v_mfma_f32_16x16x32_bf16 v[116:119], v[128:131], v[190:193], v[116:119]
	v_mfma_f32_16x16x32_bf16 v[112:115], v[158:161], v[190:193], v[112:115]
	v_mfma_f32_16x16x32_bf16 v[108:111], v[128:131], v[198:201], v[108:111]
	v_mfma_f32_16x16x32_bf16 v[104:107], v[158:161], v[198:201], v[104:107]
	v_mfma_f32_16x16x32_bf16 v[100:103], v[128:131], v[218:221], v[100:103]
	v_mfma_f32_16x16x32_bf16 v[96:99], v[158:161], v[218:221], v[96:99]
	v_mfma_f32_16x16x32_bf16 v[124:127], v[132:135], v[186:189], v[124:127]
	v_mfma_f32_16x16x32_bf16 v[120:123], v[162:165], v[186:189], v[120:123]
	v_mfma_f32_16x16x32_bf16 v[116:119], v[132:135], v[194:197], v[116:119]
	v_mfma_f32_16x16x32_bf16 v[112:115], v[162:165], v[194:197], v[112:115]
	v_mfma_f32_16x16x32_bf16 v[108:111], v[132:135], v[202:205], v[108:111]
	v_mfma_f32_16x16x32_bf16 v[104:107], v[162:165], v[202:205], v[104:107]
	v_mfma_f32_16x16x32_bf16 v[100:103], v[132:135], v[222:225], v[100:103]
	v_mfma_f32_16x16x32_bf16 v[96:99], v[162:165], v[222:225], v[96:99]
	s_setprio 0
	s_setprio 1
	v_mfma_f32_16x16x32_bf16 v[60:63], v[166:169], v[182:185], v[60:63]
	v_mfma_f32_16x16x32_bf16 v[56:59], v[174:177], v[182:185], v[56:59]
	v_mfma_f32_16x16x32_bf16 v[52:55], v[166:169], v[190:193], v[52:55]
	v_mfma_f32_16x16x32_bf16 v[48:51], v[174:177], v[190:193], v[48:51]
	v_mfma_f32_16x16x32_bf16 v[44:47], v[166:169], v[198:201], v[44:47]
	v_mfma_f32_16x16x32_bf16 v[40:43], v[174:177], v[198:201], v[40:43]
	v_mfma_f32_16x16x32_bf16 v[36:39], v[166:169], v[218:221], v[36:39]
	v_mfma_f32_16x16x32_bf16 v[32:35], v[174:177], v[218:221], v[32:35]
	v_mfma_f32_16x16x32_bf16 v[60:63], v[170:173], v[186:189], v[60:63]
	v_mfma_f32_16x16x32_bf16 v[56:59], v[178:181], v[186:189], v[56:59]
	v_mfma_f32_16x16x32_bf16 v[52:55], v[170:173], v[194:197], v[52:55]
	v_mfma_f32_16x16x32_bf16 v[48:51], v[178:181], v[194:197], v[48:51]
	v_mfma_f32_16x16x32_bf16 v[44:47], v[170:173], v[202:205], v[44:47]
	v_mfma_f32_16x16x32_bf16 v[40:43], v[178:181], v[202:205], v[40:43]
	s_setprio 2
	s_barrier
	v_mfma_f32_16x16x32_bf16 v[36:39], v[170:173], v[222:225], v[36:39]
	v_mfma_f32_16x16x32_bf16 v[32:35], v[178:181], v[222:225], v[32:35]
	s_setprio 0
	s_add_i32 s52, s33, s82
	v_lshl_add_u64 v[226:227], s[76:77], 0, v[138:139]
	s_mov_b32 m0, s52
	ds_read_b128 v[182:185], v216 offset:16384
	ds_read_b128 v[186:189], v216 offset:17408
	ds_read_b128 v[190:193], v216 offset:18432
	ds_read_b128 v[194:197], v216 offset:19456
	ds_read_b128 v[198:201], v216 offset:20480
	ds_read_b128 v[202:205], v216 offset:21504
	ds_read_b128 v[218:221], v216 offset:22528
	ds_read_b128 v[222:225], v216 offset:23552
	global_load_lds_dwordx4 v[226:227], off
	s_add_i32 m0, s52, 0x2000
	s_add_u32 s52, s76, 0x200000
	v_lshl_add_u64 v[228:229], s[76:77], 0, v[142:143]
	s_addc_u32 s53, s77, 0
	s_add_i32 s56, s92, s82
	global_load_lds_dwordx4 v[228:229], off
	v_lshl_add_u64 v[230:231], s[52:53], 0, v[138:139]
	s_mov_b32 m0, s56
	v_lshl_add_u64 v[232:233], s[78:79], 0, v[140:141]
	global_load_lds_dwordx4 v[230:231], off
	v_lshl_add_u64 v[230:231], s[52:53], 0, v[142:143]
	s_add_i32 m0, s56, 0x2000
	s_nop 0
	global_load_lds_dwordx4 v[230:231], off
	v_lshl_add_u64 v[230:231], s[78:79], 0, v[136:137]
	s_mov_b32 m0, s83
	s_nop 0
	global_load_lds_dwordx4 v[230:231], off
	s_mov_b32 m0, s84
	s_nop 0
	global_load_lds_dwordx4 v[232:233], off
	s_waitcnt vmcnt(8)
	s_waitcnt lgkmcnt(0)
	s_setprio 1
	s_barrier
; #define PG8_STAGE(bufoff, gbase, voff) do { _Pragma("unroll") for (int _i = 0; _i < 2; ++_i) \
;         __builtin_amdgcn_global_load_lds((const unsigned*)((const char*)(gbase) + (voff)[_i]), (PG8_LAS unsigned*)(lds + (bufoff) + ldsw + _i * 8192), 16, 0, 0); } while (0)
; #define PG8_LDA(dst, b, h) do { _Pragma("unroll") for (int m = 0; m < 4; ++m) _Pragma("unroll") for (int k = 0; k < 2; ++k) dst[m][k] = *(const PG8_LAS bf16x8*)(lds + PG8_SA(b, h) + aoff + m * 2048 + k * 1024); } while (0)
; #define PG8_LDB(dst, b, h) do { _Pragma("unroll") for (int n = 0; n < 2; ++n) _Pragma("unroll") for (int k = 0; k < 2; ++k) dst[n][k] = *(const PG8_LAS bf16x8*)(lds + PG8_SB(b, h) + boff + n * 2048 + k * 1024); } while (0)
; #define PG8_MMA(ai, bj, At, Bt) do { __builtin_amdgcn_s_setprio(1); _Pragma("unroll") for (int m = 0; m < 4; ++m) _Pragma("unroll") for (int n = 0; n < 2; ++n) _Pragma("unroll") for (int k = 0; k < 2; ++k) \
;         acc[ai][bj][m][n] = __builtin_amdgcn_mfma_f32_16x16x32_bf16(Bt[n][k], At[m][k], acc[ai][bj][m][n], 0, 0, 0); __builtin_amdgcn_s_setprio(0); } while (0)
; #define PG8_WAIT_V(n) asm volatile("s_waitcnt vmcnt(" #n ")" ::: "memory")
; #define PG8_WAIT_L(n) asm volatile("s_waitcnt lgkmcnt(" #n ")" ::: "memory")
; #define PG8_BAR __builtin_amdgcn_s_barrier()
; #define PG8_SCHED __builtin_amdgcn_sched_barrier(0)
; template <class Epi, class Sched, bool ALIGN_EPI = false, bool SP2 = false>
; __device__ __forceinline__ void gemm_phase(PG8_LAS unsigned char* lds, const Gemm g, const Sched& S, const Epi& E) {
;     ...
;             PG8_WAIT_V(8); PG8_WAIT_L(0); PG8_BAR; PG8_MMA(1, 0, At, B0); PG8_MMA(1, 1, At, B1); PG8_BAR; PG8_SCHED;
;             PG8_LDB(B0, 1, 0); PG8_LDB(B1, 1, 1); PG8_SCHED; PG8_LDA(At, 1, 0); PG8_STAGE(PG8_SA(0, 1), a2 + hstep, voffA);
;             PG8_WAIT_V(8); PG8_WAIT_L(0); PG8_BAR; PG8_MMA(0, 0, At, B0); PG8_MMA(0, 1, At, B1); PG8_BAR; PG8_SCHED;
	v_mfma_f32_16x16x32_bf16 v[92:95], v[128:131], v[182:185], v[92:95]
	v_mfma_f32_16x16x32_bf16 v[88:91], v[158:161], v[182:185], v[88:91]
	v_mfma_f32_16x16x32_bf16 v[84:87], v[128:131], v[190:193], v[84:87]
	v_mfma_f32_16x16x32_bf16 v[80:83], v[158:161], v[190:193], v[80:83]
	v_mfma_f32_16x16x32_bf16 v[76:79], v[128:131], v[198:201], v[76:79]
	v_mfma_f32_16x16x32_bf16 v[72:75], v[158:161], v[198:201], v[72:75]
	v_mfma_f32_16x16x32_bf16 v[68:71], v[128:131], v[218:221], v[68:71]
	v_mfma_f32_16x16x32_bf16 v[64:67], v[158:161], v[218:221], v[64:67]
	v_mfma_f32_16x16x32_bf16 v[92:95], v[132:135], v[186:189], v[92:95]
	v_mfma_f32_16x16x32_bf16 v[88:91], v[162:165], v[186:189], v[88:91]
	v_mfma_f32_16x16x32_bf16 v[84:87], v[132:135], v[194:197], v[84:87]
	v_mfma_f32_16x16x32_bf16 v[80:83], v[162:165], v[194:197], v[80:83]
	v_mfma_f32_16x16x32_bf16 v[76:79], v[132:135], v[202:205], v[76:79]
	v_mfma_f32_16x16x32_bf16 v[72:75], v[162:165], v[202:205], v[72:75]
	v_mfma_f32_16x16x32_bf16 v[68:71], v[132:135], v[222:225], v[68:71]
	v_mfma_f32_16x16x32_bf16 v[64:67], v[162:165], v[222:225], v[64:67]
	s_setprio 0
	s_setprio 1
	v_mfma_f32_16x16x32_bf16 v[28:31], v[166:169], v[182:185], v[28:31]
	v_mfma_f32_16x16x32_bf16 v[24:27], v[174:177], v[182:185], v[24:27]
	v_mfma_f32_16x16x32_bf16 v[20:23], v[166:169], v[190:193], v[20:23]
	v_mfma_f32_16x16x32_bf16 v[16:19], v[174:177], v[190:193], v[16:19]
	v_mfma_f32_16x16x32_bf16 v[12:15], v[166:169], v[198:201], v[12:15]
	v_mfma_f32_16x16x32_bf16 v[8:11], v[174:177], v[198:201], v[8:11]
	v_mfma_f32_16x16x32_bf16 v[4:7], v[166:169], v[218:221], v[4:7]
	v_mfma_f32_16x16x32_bf16 v[0:3], v[174:177], v[218:221], v[0:3]
	v_mfma_f32_16x16x32_bf16 v[28:31], v[170:173], v[186:189], v[28:31]
	v_mfma_f32_16x16x32_bf16 v[24:27], v[178:181], v[186:189], v[24:27]
	v_mfma_f32_16x16x32_bf16 v[20:23], v[170:173], v[194:197], v[20:23]
	v_mfma_f32_16x16x32_bf16 v[16:19], v[178:181], v[194:197], v[16:19]
	v_mfma_f32_16x16x32_bf16 v[12:15], v[170:173], v[202:205], v[12:15]
	v_mfma_f32_16x16x32_bf16 v[8:11], v[178:181], v[202:205], v[8:11]
	s_setprio 2
	s_barrier
	v_mfma_f32_16x16x32_bf16 v[4:7], v[170:173], v[222:225], v[4:7]
	v_mfma_f32_16x16x32_bf16 v[0:3], v[178:181], v[222:225], v[0:3]
	s_setprio 0
	s_add_i32 s56, 0, 0x18000
	s_add_i32 s57, 0, 0x1c000
	v_add_u32_e32 v162, s56, v212
	v_add_u32_e32 v178, s57, v212
	ds_read_b128 v[128:131], v162
	ds_read_b128 v[132:135], v162 offset:1024
	ds_read_b128 v[158:161], v162 offset:2048
	ds_read_b128 v[162:165], v162 offset:3072
	ds_read_b128 v[166:169], v178
	ds_read_b128 v[170:173], v178 offset:1024
	ds_read_b128 v[174:177], v178 offset:2048
	ds_read_b128 v[178:181], v178 offset:3072
	s_add_u32 s52, s78, 0x200000
	s_addc_u32 s53, s79, 0
	s_mov_b32 m0, s85
	v_lshl_add_u64 v[234:235], s[52:53], 0, v[136:137]
	ds_read_b128 v[182:185], v216 offset:32768
	ds_read_b128 v[186:189], v216 offset:33792
	ds_read_b128 v[190:193], v216 offset:34816
	ds_read_b128 v[194:197], v216 offset:35840
	ds_read_b128 v[198:201], v216 offset:36864
	ds_read_b128 v[202:205], v216 offset:37888
	ds_read_b128 v[218:221], v216 offset:38912
	ds_read_b128 v[222:225], v216 offset:39936
	global_load_lds_dwordx4 v[234:235], off
	v_lshl_add_u64 v[234:235], s[52:53], 0, v[140:141]
	s_mov_b32 m0, s86
	s_nop 0
	global_load_lds_dwordx4 v[234:235], off
	s_waitcnt vmcnt(8)
	s_waitcnt lgkmcnt(0)
	s_setprio 1
	s_barrier
	v_mfma_f32_16x16x32_bf16 v[124:127], v[128:131], v[182:185], v[124:127]
	v_mfma_f32_16x16x32_bf16 v[120:123], v[158:161], v[182:185], v[120:123]
	v_mfma_f32_16x16x32_bf16 v[116:119], v[128:131], v[190:193], v[116:119]
	v_mfma_f32_16x16x32_bf16 v[112:115], v[158:161], v[190:193], v[112:115]
	v_mfma_f32_16x16x32_bf16 v[108:111], v[128:131], v[198:201], v[108:111]
	v_mfma_f32_16x16x32_bf16 v[104:107], v[158:161], v[198:201], v[104:107]
	v_mfma_f32_16x16x32_bf16 v[100:103], v[128:131], v[218:221], v[100:103]
	v_mfma_f32_16x16x32_bf16 v[96:99], v[158:161], v[218:221], v[96:99]
	v_mfma_f32_16x16x32_bf16 v[124:127], v[132:135], v[186:189], v[124:127]
	v_mfma_f32_16x16x32_bf16 v[120:123], v[162:165], v[186:189], v[120:123]
	v_mfma_f32_16x16x32_bf16 v[116:119], v[132:135], v[194:197], v[116:119]
	v_mfma_f32_16x16x32_bf16 v[112:115], v[162:165], v[194:197], v[112:115]
	v_mfma_f32_16x16x32_bf16 v[108:111], v[132:135], v[202:205], v[108:111]
	v_mfma_f32_16x16x32_bf16 v[104:107], v[162:165], v[202:205], v[104:107]
	v_mfma_f32_16x16x32_bf16 v[100:103], v[132:135], v[222:225], v[100:103]
	v_mfma_f32_16x16x32_bf16 v[96:99], v[162:165], v[222:225], v[96:99]
	s_setprio 0
	s_setprio 1
	v_mfma_f32_16x16x32_bf16 v[60:63], v[166:169], v[182:185], v[60:63]
	v_mfma_f32_16x16x32_bf16 v[56:59], v[174:177], v[182:185], v[56:59]
	v_mfma_f32_16x16x32_bf16 v[52:55], v[166:169], v[190:193], v[52:55]
	v_mfma_f32_16x16x32_bf16 v[48:51], v[174:177], v[190:193], v[48:51]
	v_mfma_f32_16x16x32_bf16 v[44:47], v[166:169], v[198:201], v[44:47]
	v_mfma_f32_16x16x32_bf16 v[40:43], v[174:177], v[198:201], v[40:43]
	v_mfma_f32_16x16x32_bf16 v[36:39], v[166:169], v[218:221], v[36:39]
	v_mfma_f32_16x16x32_bf16 v[32:35], v[174:177], v[218:221], v[32:35]
	v_mfma_f32_16x16x32_bf16 v[60:63], v[170:173], v[186:189], v[60:63]
	v_mfma_f32_16x16x32_bf16 v[56:59], v[178:181], v[186:189], v[56:59]
	v_mfma_f32_16x16x32_bf16 v[52:55], v[170:173], v[194:197], v[52:55]
	v_mfma_f32_16x16x32_bf16 v[48:51], v[178:181], v[194:197], v[48:51]
	v_mfma_f32_16x16x32_bf16 v[44:47], v[170:173], v[202:205], v[44:47]
	v_mfma_f32_16x16x32_bf16 v[40:43], v[178:181], v[202:205], v[40:43]
	s_setprio 2
	s_barrier
; #define PG8_STAGE(bufoff, gbase, voff) do { _Pragma("unroll") for (int _i = 0; _i < 2; ++_i) \
;         __builtin_amdgcn_global_load_lds((const unsigned*)((const char*)(gbase) + (voff)[_i]), (PG8_LAS unsigned*)(lds + (bufoff) + ldsw + _i * 8192), 16, 0, 0); } while (0)
; #define PG8_LDA(dst, b, h) do { _Pragma("unroll") for (int m = 0; m < 4; ++m) _Pragma("unroll") for (int k = 0; k < 2; ++k) dst[m][k] = *(const PG8_LAS bf16x8*)(lds + PG8_SA(b, h) + aoff + m * 2048 + k * 1024); } while (0)
; #define PG8_MMA(ai, bj, At, Bt) do { __builtin_amdgcn_s_setprio(1); _Pragma("unroll") for (int m = 0; m < 4; ++m) _Pragma("unroll") for (int n = 0; n < 2; ++n) _Pragma("unroll") for (int k = 0; k < 2; ++k) \
;         acc[ai][bj][m][n] = __builtin_amdgcn_mfma_f32_16x16x32_bf16(Bt[n][k], At[m][k], acc[ai][bj][m][n], 0, 0, 0); __builtin_amdgcn_s_setprio(0); } while (0)
; #define PG8_WAIT_V(n) asm volatile("s_waitcnt vmcnt(" #n ")" ::: "memory")
; #define PG8_WAIT_L(n) asm volatile("s_waitcnt lgkmcnt(" #n ")" ::: "memory")
; #define PG8_BAR __builtin_amdgcn_s_barrier()
; #define PG8_SCHED __builtin_amdgcn_sched_barrier(0)
; template <class Epi, class Sched, bool ALIGN_EPI = false, bool SP2 = false>
; __device__ __forceinline__ void gemm_phase(PG8_LAS unsigned char* lds, const Gemm g, const Sched& S, const Epi& E) {
;     ...
;             PG8_WAIT_V(8); PG8_WAIT_L(0); PG8_BAR; PG8_MMA(0, 0, At, B0); PG8_MMA(0, 1, At, B1); PG8_BAR; PG8_SCHED;
;             PG8_LDA(At, 1, 1); PG8_STAGE(PG8_SB(1, 0), b3, voffB); PG8_STAGE(PG8_SB(1, 1), b3 + hstep, voffB); PG8_STAGE(PG8_SA(1, 0), a3, voffA);
;             PG8_WAIT_V(8); PG8_WAIT_L(0); PG8_BAR; PG8_MMA(1, 0, At, B0); PG8_MMA(1, 1, At, B1); PG8_BAR; PG8_SCHED;
;     ...
;         if constexpr (ALIGN_EPI) { if (wr == 0) PG8_BAR; }
	v_mfma_f32_16x16x32_bf16 v[36:39], v[170:173], v[222:225], v[36:39]
	v_mfma_f32_16x16x32_bf16 v[32:35], v[178:181], v[222:225], v[32:35]
	s_setprio 0
	s_add_i32 s52, s56, s82
	v_lshl_add_u64 v[226:227], v[226:227], 0, s[36:37]
	s_mov_b32 m0, s52
	ds_read_b128 v[182:185], v216 offset:49152
	ds_read_b128 v[186:189], v216 offset:50176
	ds_read_b128 v[190:193], v216 offset:51200
	ds_read_b128 v[194:197], v216 offset:52224
	ds_read_b128 v[198:201], v216 offset:53248
	ds_read_b128 v[202:205], v216 offset:54272
	ds_read_b128 v[218:221], v216 offset:55296
	ds_read_b128 v[222:225], v216 offset:56320
	global_load_lds_dwordx4 v[226:227], off
	s_add_i32 m0, s52, 0x2000
	s_add_u32 s52, s76, 0x200080
	v_lshl_add_u64 v[226:227], v[228:229], 0, s[36:37]
	s_addc_u32 s53, s77, 0
	s_add_i32 s56, s57, s82
	global_load_lds_dwordx4 v[226:227], off
	v_lshl_add_u64 v[226:227], s[52:53], 0, v[138:139]
	s_mov_b32 m0, s56
	s_nop 0
	global_load_lds_dwordx4 v[226:227], off
	v_lshl_add_u64 v[226:227], s[52:53], 0, v[142:143]
	s_add_i32 m0, s56, 0x2000
	s_nop 0
	global_load_lds_dwordx4 v[226:227], off
	v_lshl_add_u64 v[226:227], v[230:231], 0, s[36:37]
	s_mov_b32 m0, s94
	s_nop 0
	global_load_lds_dwordx4 v[226:227], off
	v_lshl_add_u64 v[226:227], v[232:233], 0, s[36:37]
	s_mov_b32 m0, s95
	s_nop 0
	global_load_lds_dwordx4 v[226:227], off
	s_waitcnt vmcnt(8)
	s_waitcnt lgkmcnt(0)
	s_setprio 1
	s_barrier
	v_mfma_f32_16x16x32_bf16 v[92:95], v[128:131], v[182:185], v[92:95]
	v_mfma_f32_16x16x32_bf16 v[88:91], v[158:161], v[182:185], v[88:91]
	v_mfma_f32_16x16x32_bf16 v[84:87], v[128:131], v[190:193], v[84:87]
	v_mfma_f32_16x16x32_bf16 v[80:83], v[158:161], v[190:193], v[80:83]
	v_mfma_f32_16x16x32_bf16 v[76:79], v[128:131], v[198:201], v[76:79]
	v_mfma_f32_16x16x32_bf16 v[72:75], v[158:161], v[198:201], v[72:75]
	v_mfma_f32_16x16x32_bf16 v[68:71], v[128:131], v[218:221], v[68:71]
	v_mfma_f32_16x16x32_bf16 v[64:67], v[158:161], v[218:221], v[64:67]
	v_mfma_f32_16x16x32_bf16 v[92:95], v[132:135], v[186:189], v[92:95]
	v_mfma_f32_16x16x32_bf16 v[88:91], v[162:165], v[186:189], v[88:91]
	v_mfma_f32_16x16x32_bf16 v[84:87], v[132:135], v[194:197], v[84:87]
	v_mfma_f32_16x16x32_bf16 v[80:83], v[162:165], v[194:197], v[80:83]
	v_mfma_f32_16x16x32_bf16 v[76:79], v[132:135], v[202:205], v[76:79]
	v_mfma_f32_16x16x32_bf16 v[72:75], v[162:165], v[202:205], v[72:75]
	v_mfma_f32_16x16x32_bf16 v[68:71], v[132:135], v[222:225], v[68:71]
	v_mfma_f32_16x16x32_bf16 v[64:67], v[162:165], v[222:225], v[64:67]
	s_setprio 0
	s_setprio 1
	v_mfma_f32_16x16x32_bf16 v[28:31], v[166:169], v[182:185], v[28:31]
	v_mfma_f32_16x16x32_bf16 v[24:27], v[174:177], v[182:185], v[24:27]
	v_mfma_f32_16x16x32_bf16 v[20:23], v[166:169], v[190:193], v[20:23]
	v_mfma_f32_16x16x32_bf16 v[16:19], v[174:177], v[190:193], v[16:19]
	v_mfma_f32_16x16x32_bf16 v[12:15], v[166:169], v[198:201], v[12:15]
	v_mfma_f32_16x16x32_bf16 v[8:11], v[174:177], v[198:201], v[8:11]
	v_mfma_f32_16x16x32_bf16 v[4:7], v[166:169], v[218:221], v[4:7]
	v_mfma_f32_16x16x32_bf16 v[0:3], v[174:177], v[218:221], v[0:3]
	v_mfma_f32_16x16x32_bf16 v[28:31], v[170:173], v[186:189], v[28:31]
	v_mfma_f32_16x16x32_bf16 v[24:27], v[178:181], v[186:189], v[24:27]
	v_mfma_f32_16x16x32_bf16 v[20:23], v[170:173], v[194:197], v[20:23]
	v_mfma_f32_16x16x32_bf16 v[16:19], v[178:181], v[194:197], v[16:19]
	v_mfma_f32_16x16x32_bf16 v[12:15], v[170:173], v[202:205], v[12:15]
	v_mfma_f32_16x16x32_bf16 v[8:11], v[178:181], v[202:205], v[8:11]
	s_setprio 2
	s_barrier
	v_mfma_f32_16x16x32_bf16 v[4:7], v[170:173], v[222:225], v[4:7]
	v_mfma_f32_16x16x32_bf16 v[0:3], v[178:181], v[222:225], v[0:3]
	s_setprio 0
	s_add_i32 vcc_hi, vcc_hi, 2
	s_add_u32 s74, s74, 0x100
	s_addc_u32 s75, s75, 0
	s_add_u32 s93, s93, 0x100
	s_addc_u32 vcc_lo, vcc_lo, 0
	s_cmpk_gt_u32 vcc_hi, 0x7d
	s_cbranch_scc0 .LBB0_624
	s_and_b64 vcc, exec, s[40:41]
	s_cbranch_vccz .LBB0_627
	s_barrier

; #define PG8_STAGE(bufoff, gbase, voff) do { _Pragma("unroll") for (int _i = 0; _i < 2; ++_i) \
;         __builtin_amdgcn_global_load_lds((const unsigned*)((const char*)(gbase) + (voff)[_i]), (PG8_LAS unsigned*)(lds + (bufoff) + ldsw + _i * 8192), 16, 0, 0); } while (0)
; #define PG8_LDA(dst, b, h) do { _Pragma("unroll") for (int m = 0; m < 4; ++m) _Pragma("unroll") for (int k = 0; k < 2; ++k) dst[m][k] = *(const PG8_LAS bf16x8*)(lds + PG8_SA(b, h) + aoff + m * 2048 + k * 1024); } while (0)
; #define PG8_LDB(dst, b, h) do { _Pragma("unroll") for (int n = 0; n < 2; ++n) _Pragma("unroll") for (int k = 0; k < 2; ++k) dst[n][k] = *(const PG8_LAS bf16x8*)(lds + PG8_SB(b, h) + boff + n * 2048 + k * 1024); } while (0)
; #define PG8_MMA(ai, bj, At, Bt) do { __builtin_amdgcn_s_setprio(1); _Pragma("unroll") for (int m = 0; m < 4; ++m) _Pragma("unroll") for (int n = 0; n < 2; ++n) _Pragma("unroll") for (int k = 0; k < 2; ++k) \
;         acc[ai][bj][m][n] = __builtin_amdgcn_mfma_f32_16x16x32_bf16(Bt[n][k], At[m][k], acc[ai][bj][m][n], 0, 0, 0); __builtin_amdgcn_s_setprio(0); } while (0)
; #define PG8_WAIT_V(n) asm volatile("s_waitcnt vmcnt(" #n ")" ::: "memory")
; #define PG8_WAIT_L(n) asm volatile("s_waitcnt lgkmcnt(" #n ")" ::: "memory")
; #define PG8_BAR __builtin_amdgcn_s_barrier()
; #define PG8_SCHED __builtin_amdgcn_sched_barrier(0)
; template <class Epi, class Sched, bool ALIGN_EPI = false, bool SP2 = false>
; __device__ __forceinline__ void gemm_phase(PG8_LAS unsigned char* lds, const Gemm g, const Sched& S, const Epi& E) {
;     ...
;         for (int t = 0; t < nt; t += 2) {
;             const bool last = (t == nt - 2);
;             const char* a1 = cA + (size_t)(t + 1) * kstep;
;             const char* a2 = last ? nA : cA + (size_t)(t + 2) * kstep; const char* b2 = last ? nB : cB + (size_t)(t + 2) * kstep;
;             const char* a3 = a2 + kstep; const char* b3 = b2 + kstep;
;             if constexpr (SP2) {
;             PG8_LDB(B0, 0, 0); PG8_LDB(B1, 0, 1); PG8_SCHED; PG8_LDA(At, 0, 0); PG8_STAGE(PG8_SA(1, 1), a1 + hstep, voffA);
;             PG8_WAIT_V(8); PG8_WAIT_L(0); PG8_BAR; PG8_MMA(0, 0, At, B0); PG8_MMA(0, 1, At, B1); PG8_BAR; PG8_SCHED;
;             PG8_LDA(At, 0, 1); PG8_STAGE(PG8_SB(0, 0), b2, voffB); PG8_STAGE(PG8_SB(0, 1), b2 + hstep, voffB); PG8_STAGE(PG8_SA(0, 0), a2, voffA);
.LBB0_660:
	ds_read_b128 v[166:169], v145
	ds_read_b128 v[170:173], v145 offset:1024
	ds_read_b128 v[174:177], v145 offset:2048
	ds_read_b128 v[178:181], v145 offset:3072
	ds_read_b128 v[182:185], v149
	ds_read_b128 v[186:189], v149 offset:1024
	ds_read_b128 v[190:193], v149 offset:2048
	ds_read_b128 v[194:197], v149 offset:3072
	s_add_u32 s52, s72, 0xffe00080
	s_addc_u32 s53, s73, -1
	s_cmp_eq_u32 s49, 28
	s_cselect_b32 s77, s51, s53
	s_cselect_b32 s76, s50, s52
	s_cselect_b32 s75, s55, s41
	s_cselect_b32 s74, s54, s37
	s_mov_b32 m0, s82
	v_lshl_add_u64 v[230:231], s[72:73], 0, v[160:161]
	ds_read_b128 v[198:201], v164
	ds_read_b128 v[202:205], v164 offset:1024
	ds_read_b128 v[206:209], v164 offset:2048
	ds_read_b128 v[210:213], v164 offset:3072
	ds_read_b128 v[214:217], v164 offset:4096
	ds_read_b128 v[218:221], v164 offset:5120
	ds_read_b128 v[222:225], v164 offset:6144
	ds_read_b128 v[226:229], v164 offset:7168
	global_load_lds_dwordx4 v[230:231], off
	v_lshl_add_u64 v[230:231], s[72:73], 0, v[162:163]
	s_mov_b32 m0, s83
	s_nop 0
	global_load_lds_dwordx4 v[230:231], off
	s_waitcnt vmcnt(8)
	s_waitcnt lgkmcnt(0)
	s_setprio 1
	s_barrier
	v_mfma_f32_16x16x32_bf16 v[124:127], v[166:169], v[198:201], v[124:127]
	v_mfma_f32_16x16x32_bf16 v[120:123], v[174:177], v[198:201], v[120:123]
	v_mfma_f32_16x16x32_bf16 v[116:119], v[166:169], v[206:209], v[116:119]
	v_mfma_f32_16x16x32_bf16 v[108:111], v[174:177], v[206:209], v[108:111]
	v_mfma_f32_16x16x32_bf16 v[100:103], v[166:169], v[214:217], v[100:103]
	v_mfma_f32_16x16x32_bf16 v[92:95], v[174:177], v[214:217], v[92:95]
	v_mfma_f32_16x16x32_bf16 v[84:87], v[166:169], v[222:225], v[84:87]
	v_mfma_f32_16x16x32_bf16 v[76:79], v[174:177], v[222:225], v[76:79]
	v_mfma_f32_16x16x32_bf16 v[124:127], v[170:173], v[202:205], v[124:127]
	v_mfma_f32_16x16x32_bf16 v[120:123], v[178:181], v[202:205], v[120:123]
	v_mfma_f32_16x16x32_bf16 v[116:119], v[170:173], v[210:213], v[116:119]
	v_mfma_f32_16x16x32_bf16 v[108:111], v[178:181], v[210:213], v[108:111]
	v_mfma_f32_16x16x32_bf16 v[100:103], v[170:173], v[218:221], v[100:103]
	v_mfma_f32_16x16x32_bf16 v[92:95], v[178:181], v[218:221], v[92:95]
	v_mfma_f32_16x16x32_bf16 v[84:87], v[170:173], v[226:229], v[84:87]
	v_mfma_f32_16x16x32_bf16 v[76:79], v[178:181], v[226:229], v[76:79]
	s_setprio 0
	s_setprio 1
	v_mfma_f32_16x16x32_bf16 v[112:115], v[182:185], v[198:201], v[112:115]
	v_mfma_f32_16x16x32_bf16 v[104:107], v[190:193], v[198:201], v[104:107]
	v_mfma_f32_16x16x32_bf16 v[96:99], v[182:185], v[206:209], v[96:99]
	v_mfma_f32_16x16x32_bf16 v[88:91], v[190:193], v[206:209], v[88:91]
	v_mfma_f32_16x16x32_bf16 v[80:83], v[182:185], v[214:217], v[80:83]
	v_mfma_f32_16x16x32_bf16 v[72:75], v[190:193], v[214:217], v[72:75]
	v_mfma_f32_16x16x32_bf16 v[68:71], v[182:185], v[222:225], v[68:71]
	v_mfma_f32_16x16x32_bf16 v[64:67], v[190:193], v[222:225], v[64:67]
	v_mfma_f32_16x16x32_bf16 v[112:115], v[186:189], v[202:205], v[112:115]
	v_mfma_f32_16x16x32_bf16 v[104:107], v[194:197], v[202:205], v[104:107]
	v_mfma_f32_16x16x32_bf16 v[96:99], v[186:189], v[210:213], v[96:99]
	v_mfma_f32_16x16x32_bf16 v[88:91], v[194:197], v[210:213], v[88:91]
	v_mfma_f32_16x16x32_bf16 v[80:83], v[186:189], v[218:221], v[80:83]
	v_mfma_f32_16x16x32_bf16 v[72:75], v[194:197], v[218:221], v[72:75]
	s_setprio 2
	s_barrier
	v_mfma_f32_16x16x32_bf16 v[68:71], v[186:189], v[226:229], v[68:71]
	v_mfma_f32_16x16x32_bf16 v[64:67], v[194:197], v[226:229], v[64:67]
	s_setprio 0
	s_mov_b32 m0, s84
	v_lshl_add_u64 v[230:231], s[74:75], 0, v[138:139]
	s_add_u32 s52, s74, 0x200000
	ds_read_b128 v[198:201], v164 offset:16384
	ds_read_b128 v[202:205], v164 offset:17408
	ds_read_b128 v[206:209], v164 offset:18432
	ds_read_b128 v[210:213], v164 offset:19456
	ds_read_b128 v[214:217], v164 offset:20480
	ds_read_b128 v[218:221], v164 offset:21504
	ds_read_b128 v[222:225], v164 offset:22528
	ds_read_b128 v[226:229], v164 offset:23552
	global_load_lds_dwordx4 v[230:231], off
	v_lshl_add_u64 v[232:233], s[74:75], 0, v[142:143]
	s_mov_b32 m0, s85
	s_addc_u32 s53, s75, 0
	global_load_lds_dwordx4 v[232:233], off
	v_lshl_add_u64 v[234:235], s[52:53], 0, v[138:139]
	s_mov_b32 m0, s86
	v_lshl_add_u64 v[236:237], s[76:77], 0, v[140:141]
	global_load_lds_dwordx4 v[234:235], off
	v_lshl_add_u64 v[234:235], s[52:53], 0, v[142:143]
	s_mov_b32 m0, s87
	s_nop 0
	global_load_lds_dwordx4 v[234:235], off
	v_lshl_add_u64 v[234:235], s[76:77], 0, v[136:137]
	s_mov_b32 m0, s28
	s_nop 0
	global_load_lds_dwordx4 v[234:235], off
	s_mov_b32 m0, s29
	s_nop 0
	global_load_lds_dwordx4 v[236:237], off
	s_waitcnt vmcnt(8)
	s_waitcnt lgkmcnt(0)
	s_setprio 1
	s_barrier
; #define PG8_STAGE(bufoff, gbase, voff) do { _Pragma("unroll") for (int _i = 0; _i < 2; ++_i) \
;         __builtin_amdgcn_global_load_lds((const unsigned*)((const char*)(gbase) + (voff)[_i]), (PG8_LAS unsigned*)(lds + (bufoff) + ldsw + _i * 8192), 16, 0, 0); } while (0)
; #define PG8_LDA(dst, b, h) do { _Pragma("unroll") for (int m = 0; m < 4; ++m) _Pragma("unroll") for (int k = 0; k < 2; ++k) dst[m][k] = *(const PG8_LAS bf16x8*)(lds + PG8_SA(b, h) + aoff + m * 2048 + k * 1024); } while (0)
; #define PG8_LDB(dst, b, h) do { _Pragma("unroll") for (int n = 0; n < 2; ++n) _Pragma("unroll") for (int k = 0; k < 2; ++k) dst[n][k] = *(const PG8_LAS bf16x8*)(lds + PG8_SB(b, h) + boff + n * 2048 + k * 1024); } while (0)
; #define PG8_MMA(ai, bj, At, Bt) do { __builtin_amdgcn_s_setprio(1); _Pragma("unroll") for (int m = 0; m < 4; ++m) _Pragma("unroll") for (int n = 0; n < 2; ++n) _Pragma("unroll") for (int k = 0; k < 2; ++k) \
;         acc[ai][bj][m][n] = __builtin_amdgcn_mfma_f32_16x16x32_bf16(Bt[n][k], At[m][k], acc[ai][bj][m][n], 0, 0, 0); __builtin_amdgcn_s_setprio(0); } while (0)
; #define PG8_WAIT_V(n) asm volatile("s_waitcnt vmcnt(" #n ")" ::: "memory")
; #define PG8_WAIT_L(n) asm volatile("s_waitcnt lgkmcnt(" #n ")" ::: "memory")
; #define PG8_BAR __builtin_amdgcn_s_barrier()
; #define PG8_SCHED __builtin_amdgcn_sched_barrier(0)
; template <class Epi, class Sched, bool ALIGN_EPI = false, bool SP2 = false>
; __device__ __forceinline__ void gemm_phase(PG8_LAS unsigned char* lds, const Gemm g, const Sched& S, const Epi& E) {
;     ...
;             PG8_WAIT_V(8); PG8_WAIT_L(0); PG8_BAR; PG8_MMA(1, 0, At, B0); PG8_MMA(1, 1, At, B1); PG8_BAR; PG8_SCHED;
;             PG8_LDB(B0, 1, 0); PG8_LDB(B1, 1, 1); PG8_SCHED; PG8_LDA(At, 1, 0); PG8_STAGE(PG8_SA(0, 1), a2 + hstep, voffA);
;             PG8_WAIT_V(8); PG8_WAIT_L(0); PG8_BAR; PG8_MMA(0, 0, At, B0); PG8_MMA(0, 1, At, B1); PG8_BAR; PG8_SCHED;
	v_mfma_f32_16x16x32_bf16 v[60:63], v[166:169], v[198:201], v[60:63]
	v_mfma_f32_16x16x32_bf16 v[56:59], v[174:177], v[198:201], v[56:59]
	v_mfma_f32_16x16x32_bf16 v[52:55], v[166:169], v[206:209], v[52:55]
	v_mfma_f32_16x16x32_bf16 v[44:47], v[174:177], v[206:209], v[44:47]
	v_mfma_f32_16x16x32_bf16 v[36:39], v[166:169], v[214:217], v[36:39]
	v_mfma_f32_16x16x32_bf16 v[28:31], v[174:177], v[214:217], v[28:31]
	v_mfma_f32_16x16x32_bf16 v[20:23], v[166:169], v[222:225], v[20:23]
	v_mfma_f32_16x16x32_bf16 v[12:15], v[174:177], v[222:225], v[12:15]
	v_mfma_f32_16x16x32_bf16 v[60:63], v[170:173], v[202:205], v[60:63]
	v_mfma_f32_16x16x32_bf16 v[56:59], v[178:181], v[202:205], v[56:59]
	v_mfma_f32_16x16x32_bf16 v[52:55], v[170:173], v[210:213], v[52:55]
	v_mfma_f32_16x16x32_bf16 v[44:47], v[178:181], v[210:213], v[44:47]
	v_mfma_f32_16x16x32_bf16 v[36:39], v[170:173], v[218:221], v[36:39]
	v_mfma_f32_16x16x32_bf16 v[28:31], v[178:181], v[218:221], v[28:31]
	v_mfma_f32_16x16x32_bf16 v[20:23], v[170:173], v[226:229], v[20:23]
	v_mfma_f32_16x16x32_bf16 v[12:15], v[178:181], v[226:229], v[12:15]
	s_setprio 0
	s_setprio 1
	v_mfma_f32_16x16x32_bf16 v[48:51], v[182:185], v[198:201], v[48:51]
	v_mfma_f32_16x16x32_bf16 v[40:43], v[190:193], v[198:201], v[40:43]
	v_mfma_f32_16x16x32_bf16 v[32:35], v[182:185], v[206:209], v[32:35]
	v_mfma_f32_16x16x32_bf16 v[24:27], v[190:193], v[206:209], v[24:27]
	v_mfma_f32_16x16x32_bf16 v[16:19], v[182:185], v[214:217], v[16:19]
	v_mfma_f32_16x16x32_bf16 v[8:11], v[190:193], v[214:217], v[8:11]
	v_mfma_f32_16x16x32_bf16 v[4:7], v[182:185], v[222:225], v[4:7]
	v_mfma_f32_16x16x32_bf16 v[0:3], v[190:193], v[222:225], v[0:3]
	v_mfma_f32_16x16x32_bf16 v[48:51], v[186:189], v[202:205], v[48:51]
	v_mfma_f32_16x16x32_bf16 v[40:43], v[194:197], v[202:205], v[40:43]
	v_mfma_f32_16x16x32_bf16 v[32:35], v[186:189], v[210:213], v[32:35]
	v_mfma_f32_16x16x32_bf16 v[24:27], v[194:197], v[210:213], v[24:27]
	v_mfma_f32_16x16x32_bf16 v[16:19], v[186:189], v[218:221], v[16:19]
	v_mfma_f32_16x16x32_bf16 v[8:11], v[194:197], v[218:221], v[8:11]
	s_setprio 2
	s_barrier
	v_mfma_f32_16x16x32_bf16 v[4:7], v[186:189], v[226:229], v[4:7]
	v_mfma_f32_16x16x32_bf16 v[0:3], v[194:197], v[226:229], v[0:3]
	s_setprio 0
	ds_read_b128 v[166:169], v148
	ds_read_b128 v[170:173], v148 offset:1024
	ds_read_b128 v[174:177], v148 offset:2048
	ds_read_b128 v[178:181], v148 offset:3072
	ds_read_b128 v[182:185], v165
	ds_read_b128 v[186:189], v165 offset:1024
	ds_read_b128 v[190:193], v165 offset:2048
	ds_read_b128 v[194:197], v165 offset:3072
	s_add_u32 s52, s76, 0x200000
	s_addc_u32 s53, s77, 0
	s_mov_b32 m0, s33
	v_lshl_add_u64 v[238:239], s[52:53], 0, v[136:137]
	ds_read_b128 v[198:201], v164 offset:32768
	ds_read_b128 v[202:205], v164 offset:33792
	ds_read_b128 v[206:209], v164 offset:34816
	ds_read_b128 v[210:213], v164 offset:35840
	ds_read_b128 v[214:217], v164 offset:36864
	ds_read_b128 v[218:221], v164 offset:37888
	ds_read_b128 v[222:225], v164 offset:38912
	ds_read_b128 v[226:229], v164 offset:39936
	global_load_lds_dwordx4 v[238:239], off
	v_lshl_add_u64 v[238:239], s[52:53], 0, v[140:141]
	s_mov_b32 m0, s38
	s_nop 0
	global_load_lds_dwordx4 v[238:239], off
	s_waitcnt vmcnt(8)
	s_waitcnt lgkmcnt(0)
	s_setprio 1
	s_barrier
	v_mfma_f32_16x16x32_bf16 v[124:127], v[166:169], v[198:201], v[124:127]
	v_mfma_f32_16x16x32_bf16 v[120:123], v[174:177], v[198:201], v[120:123]
	v_mfma_f32_16x16x32_bf16 v[116:119], v[166:169], v[206:209], v[116:119]
	v_mfma_f32_16x16x32_bf16 v[108:111], v[174:177], v[206:209], v[108:111]
	v_mfma_f32_16x16x32_bf16 v[100:103], v[166:169], v[214:217], v[100:103]
	v_mfma_f32_16x16x32_bf16 v[92:95], v[174:177], v[214:217], v[92:95]
	v_mfma_f32_16x16x32_bf16 v[84:87], v[166:169], v[222:225], v[84:87]
	v_mfma_f32_16x16x32_bf16 v[76:79], v[174:177], v[222:225], v[76:79]
	v_mfma_f32_16x16x32_bf16 v[124:127], v[170:173], v[202:205], v[124:127]
	v_mfma_f32_16x16x32_bf16 v[120:123], v[178:181], v[202:205], v[120:123]
	v_mfma_f32_16x16x32_bf16 v[116:119], v[170:173], v[210:213], v[116:119]
	v_mfma_f32_16x16x32_bf16 v[108:111], v[178:181], v[210:213], v[108:111]
	v_mfma_f32_16x16x32_bf16 v[100:103], v[170:173], v[218:221], v[100:103]
	v_mfma_f32_16x16x32_bf16 v[92:95], v[178:181], v[218:221], v[92:95]
	v_mfma_f32_16x16x32_bf16 v[84:87], v[170:173], v[226:229], v[84:87]
	v_mfma_f32_16x16x32_bf16 v[76:79], v[178:181], v[226:229], v[76:79]
	s_setprio 0
	s_setprio 1
	v_mfma_f32_16x16x32_bf16 v[112:115], v[182:185], v[198:201], v[112:115]
	v_mfma_f32_16x16x32_bf16 v[104:107], v[190:193], v[198:201], v[104:107]
	v_mfma_f32_16x16x32_bf16 v[96:99], v[182:185], v[206:209], v[96:99]
	v_mfma_f32_16x16x32_bf16 v[88:91], v[190:193], v[206:209], v[88:91]
	v_mfma_f32_16x16x32_bf16 v[80:83], v[182:185], v[214:217], v[80:83]
	v_mfma_f32_16x16x32_bf16 v[72:75], v[190:193], v[214:217], v[72:75]
	v_mfma_f32_16x16x32_bf16 v[68:71], v[182:185], v[222:225], v[68:71]
	v_mfma_f32_16x16x32_bf16 v[64:67], v[190:193], v[222:225], v[64:67]
	v_mfma_f32_16x16x32_bf16 v[112:115], v[186:189], v[202:205], v[112:115]
	v_mfma_f32_16x16x32_bf16 v[104:107], v[194:197], v[202:205], v[104:107]
	v_mfma_f32_16x16x32_bf16 v[96:99], v[186:189], v[210:213], v[96:99]
	v_mfma_f32_16x16x32_bf16 v[88:91], v[194:197], v[210:213], v[88:91]
	v_mfma_f32_16x16x32_bf16 v[80:83], v[186:189], v[218:221], v[80:83]
	v_mfma_f32_16x16x32_bf16 v[72:75], v[194:197], v[218:221], v[72:75]
	s_setprio 2
	s_barrier
; #define PG8_STAGE(bufoff, gbase, voff) do { _Pragma("unroll") for (int _i = 0; _i < 2; ++_i) \
;         __builtin_amdgcn_global_load_lds((const unsigned*)((const char*)(gbase) + (voff)[_i]), (PG8_LAS unsigned*)(lds + (bufoff) + ldsw + _i * 8192), 16, 0, 0); } while (0)
; #define PG8_LDA(dst, b, h) do { _Pragma("unroll") for (int m = 0; m < 4; ++m) _Pragma("unroll") for (int k = 0; k < 2; ++k) dst[m][k] = *(const PG8_LAS bf16x8*)(lds + PG8_SA(b, h) + aoff + m * 2048 + k * 1024); } while (0)
; #define PG8_MMA(ai, bj, At, Bt) do { __builtin_amdgcn_s_setprio(1); _Pragma("unroll") for (int m = 0; m < 4; ++m) _Pragma("unroll") for (int n = 0; n < 2; ++n) _Pragma("unroll") for (int k = 0; k < 2; ++k) \
;         acc[ai][bj][m][n] = __builtin_amdgcn_mfma_f32_16x16x32_bf16(Bt[n][k], At[m][k], acc[ai][bj][m][n], 0, 0, 0); __builtin_amdgcn_s_setprio(0); } while (0)
; #define PG8_WAIT_V(n) asm volatile("s_waitcnt vmcnt(" #n ")" ::: "memory")
; #define PG8_WAIT_L(n) asm volatile("s_waitcnt lgkmcnt(" #n ")" ::: "memory")
; #define PG8_BAR __builtin_amdgcn_s_barrier()
; #define PG8_SCHED __builtin_amdgcn_sched_barrier(0)
; template <class Epi, class Sched, bool ALIGN_EPI = false, bool SP2 = false>
; __device__ __forceinline__ void gemm_phase(PG8_LAS unsigned char* lds, const Gemm g, const Sched& S, const Epi& E) {
;     ...
;             PG8_WAIT_V(8); PG8_WAIT_L(0); PG8_BAR; PG8_MMA(0, 0, At, B0); PG8_MMA(0, 1, At, B1); PG8_BAR; PG8_SCHED;
;             PG8_LDA(At, 1, 1); PG8_STAGE(PG8_SB(1, 0), b3, voffB); PG8_STAGE(PG8_SB(1, 1), b3 + hstep, voffB); PG8_STAGE(PG8_SA(1, 0), a3, voffA);
;             PG8_WAIT_V(8); PG8_WAIT_L(0); PG8_BAR; PG8_MMA(1, 0, At, B0); PG8_MMA(1, 1, At, B1); PG8_BAR; PG8_SCHED;
;     ...
;         if constexpr (ALIGN_EPI) { if (wr == 0) PG8_BAR; }
	v_mfma_f32_16x16x32_bf16 v[68:71], v[186:189], v[226:229], v[68:71]
	v_mfma_f32_16x16x32_bf16 v[64:67], v[194:197], v[226:229], v[64:67]
	s_setprio 0
	s_mov_b32 m0, s89
	v_lshl_add_u64 v[230:231], v[230:231], 0, s[12:13]
	ds_read_b128 v[198:201], v164 offset:49152
	ds_read_b128 v[202:205], v164 offset:50176
	ds_read_b128 v[206:209], v164 offset:51200
	ds_read_b128 v[210:213], v164 offset:52224
	ds_read_b128 v[214:217], v164 offset:53248
	ds_read_b128 v[218:221], v164 offset:54272
	ds_read_b128 v[222:225], v164 offset:55296
	ds_read_b128 v[226:229], v164 offset:56320
	global_load_lds_dwordx4 v[230:231], off
	s_add_i32 m0, s89, 0x2000
	s_add_u32 s52, s74, 0x200080
	v_lshl_add_u64 v[230:231], v[232:233], 0, s[12:13]
	s_addc_u32 s53, s75, 0
	s_add_i32 s56, s88, s3
	global_load_lds_dwordx4 v[230:231], off
	v_lshl_add_u64 v[230:231], s[52:53], 0, v[138:139]
	s_mov_b32 m0, s56
	s_nop 0
	global_load_lds_dwordx4 v[230:231], off
	v_lshl_add_u64 v[230:231], s[52:53], 0, v[142:143]
	s_add_i32 m0, s56, 0x2000
	s_nop 0
	global_load_lds_dwordx4 v[230:231], off
	v_lshl_add_u64 v[230:231], v[234:235], 0, s[12:13]
	s_mov_b32 m0, s71
	s_nop 0
	global_load_lds_dwordx4 v[230:231], off
	v_lshl_add_u64 v[230:231], v[236:237], 0, s[12:13]
	s_mov_b32 m0, s78
	s_nop 0
	global_load_lds_dwordx4 v[230:231], off
	s_waitcnt vmcnt(8)
	s_waitcnt lgkmcnt(0)
	s_setprio 1
	s_barrier
	v_mfma_f32_16x16x32_bf16 v[60:63], v[166:169], v[198:201], v[60:63]
	v_mfma_f32_16x16x32_bf16 v[56:59], v[174:177], v[198:201], v[56:59]
	v_mfma_f32_16x16x32_bf16 v[52:55], v[166:169], v[206:209], v[52:55]
	v_mfma_f32_16x16x32_bf16 v[44:47], v[174:177], v[206:209], v[44:47]
	v_mfma_f32_16x16x32_bf16 v[36:39], v[166:169], v[214:217], v[36:39]
	v_mfma_f32_16x16x32_bf16 v[28:31], v[174:177], v[214:217], v[28:31]
	v_mfma_f32_16x16x32_bf16 v[20:23], v[166:169], v[222:225], v[20:23]
	v_mfma_f32_16x16x32_bf16 v[12:15], v[174:177], v[222:225], v[12:15]
	v_mfma_f32_16x16x32_bf16 v[60:63], v[170:173], v[202:205], v[60:63]
	v_mfma_f32_16x16x32_bf16 v[56:59], v[178:181], v[202:205], v[56:59]
	v_mfma_f32_16x16x32_bf16 v[52:55], v[170:173], v[210:213], v[52:55]
	v_mfma_f32_16x16x32_bf16 v[44:47], v[178:181], v[210:213], v[44:47]
	v_mfma_f32_16x16x32_bf16 v[36:39], v[170:173], v[218:221], v[36:39]
	v_mfma_f32_16x16x32_bf16 v[28:31], v[178:181], v[218:221], v[28:31]
	v_mfma_f32_16x16x32_bf16 v[20:23], v[170:173], v[226:229], v[20:23]
	v_mfma_f32_16x16x32_bf16 v[12:15], v[178:181], v[226:229], v[12:15]
	s_setprio 0
	s_setprio 1
	v_mfma_f32_16x16x32_bf16 v[48:51], v[182:185], v[198:201], v[48:51]
	v_mfma_f32_16x16x32_bf16 v[40:43], v[190:193], v[198:201], v[40:43]
	v_mfma_f32_16x16x32_bf16 v[32:35], v[182:185], v[206:209], v[32:35]
	v_mfma_f32_16x16x32_bf16 v[24:27], v[190:193], v[206:209], v[24:27]
	v_mfma_f32_16x16x32_bf16 v[16:19], v[182:185], v[214:217], v[16:19]
	v_mfma_f32_16x16x32_bf16 v[8:11], v[190:193], v[214:217], v[8:11]
	v_mfma_f32_16x16x32_bf16 v[4:7], v[182:185], v[222:225], v[4:7]
	v_mfma_f32_16x16x32_bf16 v[0:3], v[190:193], v[222:225], v[0:3]
	v_mfma_f32_16x16x32_bf16 v[48:51], v[186:189], v[202:205], v[48:51]
	v_mfma_f32_16x16x32_bf16 v[40:43], v[194:197], v[202:205], v[40:43]
	v_mfma_f32_16x16x32_bf16 v[32:35], v[186:189], v[210:213], v[32:35]
	v_mfma_f32_16x16x32_bf16 v[24:27], v[194:197], v[210:213], v[24:27]
	v_mfma_f32_16x16x32_bf16 v[16:19], v[186:189], v[218:221], v[16:19]
	v_mfma_f32_16x16x32_bf16 v[8:11], v[194:197], v[218:221], v[8:11]
	s_setprio 2
	s_barrier
	v_mfma_f32_16x16x32_bf16 v[4:7], v[186:189], v[226:229], v[4:7]
	v_mfma_f32_16x16x32_bf16 v[0:3], v[194:197], v[226:229], v[0:3]
	s_setprio 0
	s_add_i32 s49, s49, 2
	s_add_u32 s72, s72, 0x100
	s_addc_u32 s73, s73, 0
	s_add_u32 s37, s37, 0x100
	s_addc_u32 s41, s41, 0
	s_cmp_gt_u32 s49, 29
	s_cbranch_scc0 .LBB0_660
	s_and_b64 vcc, exec, s[14:15]
	s_cbranch_vccz .LBB0_663
	s_barrier

; #define PG8_STAGE(bufoff, gbase, voff) do { _Pragma("unroll") for (int _i = 0; _i < 2; ++_i) \
;         __builtin_amdgcn_global_load_lds((const unsigned*)((const char*)(gbase) + (voff)[_i]), (PG8_LAS unsigned*)(lds + (bufoff) + ldsw + _i * 8192), 16, 0, 0); } while (0)
; #define PG8_LDA(dst, b, h) do { _Pragma("unroll") for (int m = 0; m < 4; ++m) _Pragma("unroll") for (int k = 0; k < 2; ++k) dst[m][k] = *(const PG8_LAS bf16x8*)(lds + PG8_SA(b, h) + aoff + m * 2048 + k * 1024); } while (0)
; #define PG8_LDB(dst, b, h) do { _Pragma("unroll") for (int n = 0; n < 2; ++n) _Pragma("unroll") for (int k = 0; k < 2; ++k) dst[n][k] = *(const PG8_LAS bf16x8*)(lds + PG8_SB(b, h) + boff + n * 2048 + k * 1024); } while (0)
; #define PG8_MMA(ai, bj, At, Bt) do { __builtin_amdgcn_s_setprio(1); _Pragma("unroll") for (int m = 0; m < 4; ++m) _Pragma("unroll") for (int n = 0; n < 2; ++n) _Pragma("unroll") for (int k = 0; k < 2; ++k) \
;         acc[ai][bj][m][n] = __builtin_amdgcn_mfma_f32_16x16x32_bf16(Bt[n][k], At[m][k], acc[ai][bj][m][n], 0, 0, 0); __builtin_amdgcn_s_setprio(0); } while (0)
; #define PG8_WAIT_V(n) asm volatile("s_waitcnt vmcnt(" #n ")" ::: "memory")
; #define PG8_WAIT_L(n) asm volatile("s_waitcnt lgkmcnt(" #n ")" ::: "memory")
; #define PG8_BAR __builtin_amdgcn_s_barrier()
; #define PG8_SCHED __builtin_amdgcn_sched_barrier(0)
; template <class Epi, class Sched, bool ALIGN_EPI = false, bool SP2 = false>
; __device__ __forceinline__ void gemm_phase(PG8_LAS unsigned char* lds, const Gemm g, const Sched& S, const Epi& E) {
;     ...
;         for (int t = 0; t < nt; t += 2) {
;             const bool last = (t == nt - 2);
;             const char* a1 = cA + (size_t)(t + 1) * kstep;
;             const char* a2 = last ? nA : cA + (size_t)(t + 2) * kstep; const char* b2 = last ? nB : cB + (size_t)(t + 2) * kstep;
;             const char* a3 = a2 + kstep; const char* b3 = b2 + kstep;
;             if constexpr (SP2) {
;             PG8_LDB(B0, 0, 0); PG8_LDB(B1, 0, 1); PG8_SCHED; PG8_LDA(At, 0, 0); PG8_STAGE(PG8_SA(1, 1), a1 + hstep, voffA);
;             PG8_WAIT_V(8); PG8_WAIT_L(0); PG8_BAR; PG8_MMA(0, 0, At, B0); PG8_MMA(0, 1, At, B1); PG8_BAR; PG8_SCHED;
;             PG8_LDA(At, 0, 1); PG8_STAGE(PG8_SB(0, 0), b2, voffB); PG8_STAGE(PG8_SB(0, 1), b2 + hstep, voffB); PG8_STAGE(PG8_SA(0, 0), a2, voffA);
.LBB0_809:
	ds_read_b128 v[128:131], v180
	ds_read_b128 v[132:135], v180 offset:1024
	ds_read_b128 v[136:139], v180 offset:2048
	ds_read_b128 v[140:143], v180 offset:3072
	ds_read_b128 v[160:163], v181
	ds_read_b128 v[164:167], v181 offset:1024
	ds_read_b128 v[184:187], v181 offset:2048
	ds_read_b128 v[188:191], v181 offset:3072
	s_add_u32 s52, s72, 0xfff80080
	s_addc_u32 s53, s73, -1
	s_cmp_eq_u32 s92, 28
	s_cselect_b32 s77, s5, s53
	s_cselect_b32 s76, s49, s52
	s_cselect_b32 s75, s45, s91
	s_cselect_b32 s74, s89, s90
	v_lshl_add_u64 v[168:169], s[72:73], 0, v[154:155]
	s_add_i32 m0, s71, 0xc000
	ds_read_b128 v[192:195], v182
	ds_read_b128 v[196:199], v182 offset:1024
	ds_read_b128 v[200:203], v182 offset:2048
	ds_read_b128 v[204:207], v182 offset:3072
	ds_read_b128 v[208:211], v182 offset:4096
	ds_read_b128 v[212:215], v182 offset:5120
	ds_read_b128 v[216:219], v182 offset:6144
	ds_read_b128 v[220:223], v182 offset:7168
	global_load_lds_dwordx4 v[168:169], off
	v_lshl_add_u64 v[168:169], s[72:73], 0, v[156:157]
	s_add_i32 m0, s71, 0xe000
	s_nop 0
	global_load_lds_dwordx4 v[168:169], off
	s_waitcnt vmcnt(8)
	s_waitcnt lgkmcnt(0)
	s_setprio 1
	s_barrier
	v_mfma_f32_16x16x32_bf16 v[124:127], v[128:131], v[192:195], v[124:127]
	v_mfma_f32_16x16x32_bf16 v[120:123], v[136:139], v[192:195], v[120:123]
	v_mfma_f32_16x16x32_bf16 v[108:111], v[128:131], v[200:203], v[108:111]
	v_mfma_f32_16x16x32_bf16 v[104:107], v[136:139], v[200:203], v[104:107]
	v_mfma_f32_16x16x32_bf16 v[92:95], v[128:131], v[208:211], v[92:95]
	v_mfma_f32_16x16x32_bf16 v[88:91], v[136:139], v[208:211], v[88:91]
	v_mfma_f32_16x16x32_bf16 v[76:79], v[128:131], v[216:219], v[76:79]
	v_mfma_f32_16x16x32_bf16 v[72:75], v[136:139], v[216:219], v[72:75]
	v_mfma_f32_16x16x32_bf16 v[124:127], v[132:135], v[196:199], v[124:127]
	v_mfma_f32_16x16x32_bf16 v[120:123], v[140:143], v[196:199], v[120:123]
	v_mfma_f32_16x16x32_bf16 v[108:111], v[132:135], v[204:207], v[108:111]
	v_mfma_f32_16x16x32_bf16 v[104:107], v[140:143], v[204:207], v[104:107]
	v_mfma_f32_16x16x32_bf16 v[92:95], v[132:135], v[212:215], v[92:95]
	v_mfma_f32_16x16x32_bf16 v[88:91], v[140:143], v[212:215], v[88:91]
	v_mfma_f32_16x16x32_bf16 v[76:79], v[132:135], v[220:223], v[76:79]
	v_mfma_f32_16x16x32_bf16 v[72:75], v[140:143], v[220:223], v[72:75]
	s_setprio 0
	s_setprio 1
	v_mfma_f32_16x16x32_bf16 v[116:119], v[160:163], v[192:195], v[116:119]
	v_mfma_f32_16x16x32_bf16 v[112:115], v[184:187], v[192:195], v[112:115]
	v_mfma_f32_16x16x32_bf16 v[100:103], v[160:163], v[200:203], v[100:103]
	v_mfma_f32_16x16x32_bf16 v[96:99], v[184:187], v[200:203], v[96:99]
	v_mfma_f32_16x16x32_bf16 v[84:87], v[160:163], v[208:211], v[84:87]
	v_mfma_f32_16x16x32_bf16 v[80:83], v[184:187], v[208:211], v[80:83]
	v_mfma_f32_16x16x32_bf16 v[68:71], v[160:163], v[216:219], v[68:71]
	v_mfma_f32_16x16x32_bf16 v[64:67], v[184:187], v[216:219], v[64:67]
	v_mfma_f32_16x16x32_bf16 v[116:119], v[164:167], v[196:199], v[116:119]
	v_mfma_f32_16x16x32_bf16 v[112:115], v[188:191], v[196:199], v[112:115]
	v_mfma_f32_16x16x32_bf16 v[100:103], v[164:167], v[204:207], v[100:103]
	v_mfma_f32_16x16x32_bf16 v[96:99], v[188:191], v[204:207], v[96:99]
	v_mfma_f32_16x16x32_bf16 v[84:87], v[164:167], v[212:215], v[84:87]
	v_mfma_f32_16x16x32_bf16 v[80:83], v[188:191], v[212:215], v[80:83]
	s_setprio 2
	s_barrier
	v_mfma_f32_16x16x32_bf16 v[68:71], v[164:167], v[220:223], v[68:71]
	v_mfma_f32_16x16x32_bf16 v[64:67], v[188:191], v[220:223], v[64:67]
	s_setprio 0
	s_add_i32 s52, s83, s78
	v_lshl_add_u64 v[168:169], s[74:75], 0, v[148:149]
	s_mov_b32 m0, s52
	ds_read_b128 v[192:195], v182 offset:16384
	ds_read_b128 v[196:199], v182 offset:17408
	ds_read_b128 v[200:203], v182 offset:18432
	ds_read_b128 v[204:207], v182 offset:19456
	ds_read_b128 v[208:211], v182 offset:20480
	ds_read_b128 v[212:215], v182 offset:21504
	ds_read_b128 v[216:219], v182 offset:22528
	ds_read_b128 v[220:223], v182 offset:23552
	global_load_lds_dwordx4 v[168:169], off
	s_add_i32 m0, s52, 0x2000
	s_add_u32 s52, s74, 0x80000
	v_lshl_add_u64 v[224:225], s[74:75], 0, v[152:153]
	s_addc_u32 s53, s75, 0
	s_add_i32 s56, s84, s78
	global_load_lds_dwordx4 v[224:225], off
	v_lshl_add_u64 v[226:227], s[52:53], 0, v[148:149]
	s_mov_b32 m0, s56
	v_lshl_add_u64 v[228:229], s[76:77], 0, v[150:151]
	global_load_lds_dwordx4 v[226:227], off
	v_lshl_add_u64 v[226:227], s[52:53], 0, v[152:153]
	s_add_i32 m0, s56, 0x2000
	s_nop 0
	global_load_lds_dwordx4 v[226:227], off
	v_lshl_add_u64 v[226:227], s[76:77], 0, v[144:145]
	s_mov_b32 m0, s71
	s_nop 0
	global_load_lds_dwordx4 v[226:227], off
	s_mov_b32 m0, s79
	s_nop 0
	global_load_lds_dwordx4 v[228:229], off
	s_waitcnt vmcnt(8)
	s_waitcnt lgkmcnt(0)
	s_setprio 1
	s_barrier
; #define PG8_STAGE(bufoff, gbase, voff) do { _Pragma("unroll") for (int _i = 0; _i < 2; ++_i) \
;         __builtin_amdgcn_global_load_lds((const unsigned*)((const char*)(gbase) + (voff)[_i]), (PG8_LAS unsigned*)(lds + (bufoff) + ldsw + _i * 8192), 16, 0, 0); } while (0)
; #define PG8_LDA(dst, b, h) do { _Pragma("unroll") for (int m = 0; m < 4; ++m) _Pragma("unroll") for (int k = 0; k < 2; ++k) dst[m][k] = *(const PG8_LAS bf16x8*)(lds + PG8_SA(b, h) + aoff + m * 2048 + k * 1024); } while (0)
; #define PG8_LDB(dst, b, h) do { _Pragma("unroll") for (int n = 0; n < 2; ++n) _Pragma("unroll") for (int k = 0; k < 2; ++k) dst[n][k] = *(const PG8_LAS bf16x8*)(lds + PG8_SB(b, h) + boff + n * 2048 + k * 1024); } while (0)
; #define PG8_MMA(ai, bj, At, Bt) do { __builtin_amdgcn_s_setprio(1); _Pragma("unroll") for (int m = 0; m < 4; ++m) _Pragma("unroll") for (int n = 0; n < 2; ++n) _Pragma("unroll") for (int k = 0; k < 2; ++k) \
;         acc[ai][bj][m][n] = __builtin_amdgcn_mfma_f32_16x16x32_bf16(Bt[n][k], At[m][k], acc[ai][bj][m][n], 0, 0, 0); __builtin_amdgcn_s_setprio(0); } while (0)
; #define PG8_WAIT_V(n) asm volatile("s_waitcnt vmcnt(" #n ")" ::: "memory")
; #define PG8_WAIT_L(n) asm volatile("s_waitcnt lgkmcnt(" #n ")" ::: "memory")
; #define PG8_BAR __builtin_amdgcn_s_barrier()
; #define PG8_SCHED __builtin_amdgcn_sched_barrier(0)
; template <class Epi, class Sched, bool ALIGN_EPI = false, bool SP2 = false>
; __device__ __forceinline__ void gemm_phase(PG8_LAS unsigned char* lds, const Gemm g, const Sched& S, const Epi& E) {
;     ...
;             PG8_WAIT_V(8); PG8_WAIT_L(0); PG8_BAR; PG8_MMA(1, 0, At, B0); PG8_MMA(1, 1, At, B1); PG8_BAR; PG8_SCHED;
;             PG8_LDB(B0, 1, 0); PG8_LDB(B1, 1, 1); PG8_SCHED; PG8_LDA(At, 1, 0); PG8_STAGE(PG8_SA(0, 1), a2 + hstep, voffA);
;             PG8_WAIT_V(8); PG8_WAIT_L(0); PG8_BAR; PG8_MMA(0, 0, At, B0); PG8_MMA(0, 1, At, B1); PG8_BAR; PG8_SCHED;
	v_mfma_f32_16x16x32_bf16 v[60:63], v[128:131], v[192:195], v[60:63]
	v_mfma_f32_16x16x32_bf16 v[56:59], v[136:139], v[192:195], v[56:59]
	v_mfma_f32_16x16x32_bf16 v[44:47], v[128:131], v[200:203], v[44:47]
	v_mfma_f32_16x16x32_bf16 v[40:43], v[136:139], v[200:203], v[40:43]
	v_mfma_f32_16x16x32_bf16 v[28:31], v[128:131], v[208:211], v[28:31]
	v_mfma_f32_16x16x32_bf16 v[24:27], v[136:139], v[208:211], v[24:27]
	v_mfma_f32_16x16x32_bf16 v[12:15], v[128:131], v[216:219], v[12:15]
	v_mfma_f32_16x16x32_bf16 v[8:11], v[136:139], v[216:219], v[8:11]
	v_mfma_f32_16x16x32_bf16 v[60:63], v[132:135], v[196:199], v[60:63]
	v_mfma_f32_16x16x32_bf16 v[56:59], v[140:143], v[196:199], v[56:59]
	v_mfma_f32_16x16x32_bf16 v[44:47], v[132:135], v[204:207], v[44:47]
	v_mfma_f32_16x16x32_bf16 v[40:43], v[140:143], v[204:207], v[40:43]
	v_mfma_f32_16x16x32_bf16 v[28:31], v[132:135], v[212:215], v[28:31]
	v_mfma_f32_16x16x32_bf16 v[24:27], v[140:143], v[212:215], v[24:27]
	v_mfma_f32_16x16x32_bf16 v[12:15], v[132:135], v[220:223], v[12:15]
	v_mfma_f32_16x16x32_bf16 v[8:11], v[140:143], v[220:223], v[8:11]
	s_setprio 0
	s_setprio 1
	v_mfma_f32_16x16x32_bf16 v[52:55], v[160:163], v[192:195], v[52:55]
	v_mfma_f32_16x16x32_bf16 v[48:51], v[184:187], v[192:195], v[48:51]
	v_mfma_f32_16x16x32_bf16 v[36:39], v[160:163], v[200:203], v[36:39]
	v_mfma_f32_16x16x32_bf16 v[32:35], v[184:187], v[200:203], v[32:35]
	v_mfma_f32_16x16x32_bf16 v[20:23], v[160:163], v[208:211], v[20:23]
	v_mfma_f32_16x16x32_bf16 v[16:19], v[184:187], v[208:211], v[16:19]
	v_mfma_f32_16x16x32_bf16 v[4:7], v[160:163], v[216:219], v[4:7]
	v_mfma_f32_16x16x32_bf16 v[0:3], v[184:187], v[216:219], v[0:3]
	v_mfma_f32_16x16x32_bf16 v[52:55], v[164:167], v[196:199], v[52:55]
	v_mfma_f32_16x16x32_bf16 v[48:51], v[188:191], v[196:199], v[48:51]
	v_mfma_f32_16x16x32_bf16 v[36:39], v[164:167], v[204:207], v[36:39]
	v_mfma_f32_16x16x32_bf16 v[32:35], v[188:191], v[204:207], v[32:35]
	v_mfma_f32_16x16x32_bf16 v[20:23], v[164:167], v[212:215], v[20:23]
	v_mfma_f32_16x16x32_bf16 v[16:19], v[188:191], v[212:215], v[16:19]
	s_setprio 2
	s_barrier
	v_mfma_f32_16x16x32_bf16 v[4:7], v[164:167], v[220:223], v[4:7]
	v_mfma_f32_16x16x32_bf16 v[0:3], v[188:191], v[220:223], v[0:3]
	s_setprio 0
	s_add_i32 s56, 0, 0x18000
	s_add_i32 s57, 0, 0x1c000
	v_add_u32_e32 v140, s56, v171
	v_add_u32_e32 v188, s57, v171
	ds_read_b128 v[128:131], v140
	ds_read_b128 v[132:135], v140 offset:1024
	ds_read_b128 v[136:139], v140 offset:2048
	ds_read_b128 v[140:143], v140 offset:3072
	ds_read_b128 v[160:163], v188
	ds_read_b128 v[164:167], v188 offset:1024
	ds_read_b128 v[184:187], v188 offset:2048
	ds_read_b128 v[188:191], v188 offset:3072
	s_add_u32 s52, s76, 0x80000
	s_addc_u32 s53, s77, 0
	s_mov_b32 m0, s80
	v_lshl_add_u64 v[230:231], s[52:53], 0, v[144:145]
	ds_read_b128 v[192:195], v182 offset:32768
	ds_read_b128 v[196:199], v182 offset:33792
	ds_read_b128 v[200:203], v182 offset:34816
	ds_read_b128 v[204:207], v182 offset:35840
	ds_read_b128 v[208:211], v182 offset:36864
	ds_read_b128 v[212:215], v182 offset:37888
	ds_read_b128 v[216:219], v182 offset:38912
	ds_read_b128 v[220:223], v182 offset:39936
	global_load_lds_dwordx4 v[230:231], off
	v_lshl_add_u64 v[230:231], s[52:53], 0, v[150:151]
	s_mov_b32 m0, s81
	s_nop 0
	global_load_lds_dwordx4 v[230:231], off
	s_waitcnt vmcnt(8)
	s_waitcnt lgkmcnt(0)
	s_setprio 1
	s_barrier
	v_mfma_f32_16x16x32_bf16 v[124:127], v[128:131], v[192:195], v[124:127]
	v_mfma_f32_16x16x32_bf16 v[120:123], v[136:139], v[192:195], v[120:123]
	v_mfma_f32_16x16x32_bf16 v[108:111], v[128:131], v[200:203], v[108:111]
	v_mfma_f32_16x16x32_bf16 v[104:107], v[136:139], v[200:203], v[104:107]
	v_mfma_f32_16x16x32_bf16 v[92:95], v[128:131], v[208:211], v[92:95]
	v_mfma_f32_16x16x32_bf16 v[88:91], v[136:139], v[208:211], v[88:91]
	v_mfma_f32_16x16x32_bf16 v[76:79], v[128:131], v[216:219], v[76:79]
	v_mfma_f32_16x16x32_bf16 v[72:75], v[136:139], v[216:219], v[72:75]
	v_mfma_f32_16x16x32_bf16 v[124:127], v[132:135], v[196:199], v[124:127]
	v_mfma_f32_16x16x32_bf16 v[120:123], v[140:143], v[196:199], v[120:123]
	v_mfma_f32_16x16x32_bf16 v[108:111], v[132:135], v[204:207], v[108:111]
	v_mfma_f32_16x16x32_bf16 v[104:107], v[140:143], v[204:207], v[104:107]
	v_mfma_f32_16x16x32_bf16 v[92:95], v[132:135], v[212:215], v[92:95]
	v_mfma_f32_16x16x32_bf16 v[88:91], v[140:143], v[212:215], v[88:91]
	v_mfma_f32_16x16x32_bf16 v[76:79], v[132:135], v[220:223], v[76:79]
	v_mfma_f32_16x16x32_bf16 v[72:75], v[140:143], v[220:223], v[72:75]
	s_setprio 0
	s_setprio 1
	v_mfma_f32_16x16x32_bf16 v[116:119], v[160:163], v[192:195], v[116:119]
	v_mfma_f32_16x16x32_bf16 v[112:115], v[184:187], v[192:195], v[112:115]
	v_mfma_f32_16x16x32_bf16 v[100:103], v[160:163], v[200:203], v[100:103]
	v_mfma_f32_16x16x32_bf16 v[96:99], v[184:187], v[200:203], v[96:99]
	v_mfma_f32_16x16x32_bf16 v[84:87], v[160:163], v[208:211], v[84:87]
	v_mfma_f32_16x16x32_bf16 v[80:83], v[184:187], v[208:211], v[80:83]
	v_mfma_f32_16x16x32_bf16 v[68:71], v[160:163], v[216:219], v[68:71]
	v_mfma_f32_16x16x32_bf16 v[64:67], v[184:187], v[216:219], v[64:67]
	v_mfma_f32_16x16x32_bf16 v[116:119], v[164:167], v[196:199], v[116:119]
	v_mfma_f32_16x16x32_bf16 v[112:115], v[188:191], v[196:199], v[112:115]
	v_mfma_f32_16x16x32_bf16 v[100:103], v[164:167], v[204:207], v[100:103]
	v_mfma_f32_16x16x32_bf16 v[96:99], v[188:191], v[204:207], v[96:99]
	v_mfma_f32_16x16x32_bf16 v[84:87], v[164:167], v[212:215], v[84:87]
	v_mfma_f32_16x16x32_bf16 v[80:83], v[188:191], v[212:215], v[80:83]
	s_setprio 2
	s_barrier
; #define PG8_STAGE(bufoff, gbase, voff) do { _Pragma("unroll") for (int _i = 0; _i < 2; ++_i) \
;         __builtin_amdgcn_global_load_lds((const unsigned*)((const char*)(gbase) + (voff)[_i]), (PG8_LAS unsigned*)(lds + (bufoff) + ldsw + _i * 8192), 16, 0, 0); } while (0)
; #define PG8_LDA(dst, b, h) do { _Pragma("unroll") for (int m = 0; m < 4; ++m) _Pragma("unroll") for (int k = 0; k < 2; ++k) dst[m][k] = *(const PG8_LAS bf16x8*)(lds + PG8_SA(b, h) + aoff + m * 2048 + k * 1024); } while (0)
; #define PG8_MMA(ai, bj, At, Bt) do { __builtin_amdgcn_s_setprio(1); _Pragma("unroll") for (int m = 0; m < 4; ++m) _Pragma("unroll") for (int n = 0; n < 2; ++n) _Pragma("unroll") for (int k = 0; k < 2; ++k) \
;         acc[ai][bj][m][n] = __builtin_amdgcn_mfma_f32_16x16x32_bf16(Bt[n][k], At[m][k], acc[ai][bj][m][n], 0, 0, 0); __builtin_amdgcn_s_setprio(0); } while (0)
; #define PG8_WAIT_V(n) asm volatile("s_waitcnt vmcnt(" #n ")" ::: "memory")
; #define PG8_WAIT_L(n) asm volatile("s_waitcnt lgkmcnt(" #n ")" ::: "memory")
; #define PG8_BAR __builtin_amdgcn_s_barrier()
; #define PG8_SCHED __builtin_amdgcn_sched_barrier(0)
; template <class Epi, class Sched, bool ALIGN_EPI = false, bool SP2 = false>
; __device__ __forceinline__ void gemm_phase(PG8_LAS unsigned char* lds, const Gemm g, const Sched& S, const Epi& E) {
;     ...
;             PG8_WAIT_V(8); PG8_WAIT_L(0); PG8_BAR; PG8_MMA(0, 0, At, B0); PG8_MMA(0, 1, At, B1); PG8_BAR; PG8_SCHED;
;             PG8_LDA(At, 1, 1); PG8_STAGE(PG8_SB(1, 0), b3, voffB); PG8_STAGE(PG8_SB(1, 1), b3 + hstep, voffB); PG8_STAGE(PG8_SA(1, 0), a3, voffA);
;             PG8_WAIT_V(8); PG8_WAIT_L(0); PG8_BAR; PG8_MMA(1, 0, At, B0); PG8_MMA(1, 1, At, B1); PG8_BAR; PG8_SCHED;
;     ...
;         if constexpr (ALIGN_EPI) { if (wr == 0) PG8_BAR; }
	v_mfma_f32_16x16x32_bf16 v[68:71], v[164:167], v[220:223], v[68:71]
	v_mfma_f32_16x16x32_bf16 v[64:67], v[188:191], v[220:223], v[64:67]
	s_setprio 0
	s_add_i32 s52, s56, s78
	v_lshl_add_u64 v[168:169], v[168:169], 0, s[40:41]
	s_mov_b32 m0, s52
	ds_read_b128 v[192:195], v182 offset:49152
	ds_read_b128 v[196:199], v182 offset:50176
	ds_read_b128 v[200:203], v182 offset:51200
	ds_read_b128 v[204:207], v182 offset:52224
	ds_read_b128 v[208:211], v182 offset:53248
	ds_read_b128 v[212:215], v182 offset:54272
	ds_read_b128 v[216:219], v182 offset:55296
	ds_read_b128 v[220:223], v182 offset:56320
	global_load_lds_dwordx4 v[168:169], off
	s_add_i32 m0, s52, 0x2000
	s_add_u32 s52, s74, 0x80080
	v_lshl_add_u64 v[168:169], v[224:225], 0, s[40:41]
	s_addc_u32 s53, s75, 0
	s_add_i32 s56, s57, s78
	global_load_lds_dwordx4 v[168:169], off
	v_lshl_add_u64 v[168:169], s[52:53], 0, v[148:149]
	s_mov_b32 m0, s56
	s_nop 0
	global_load_lds_dwordx4 v[168:169], off
	v_lshl_add_u64 v[168:169], s[52:53], 0, v[152:153]
	s_add_i32 m0, s56, 0x2000
	s_nop 0
	global_load_lds_dwordx4 v[168:169], off
	v_lshl_add_u64 v[168:169], v[226:227], 0, s[40:41]
	s_mov_b32 m0, s3
	s_nop 0
	global_load_lds_dwordx4 v[168:169], off
	v_lshl_add_u64 v[168:169], v[228:229], 0, s[40:41]
	s_mov_b32 m0, s28
	s_nop 0
	global_load_lds_dwordx4 v[168:169], off
	s_waitcnt vmcnt(8)
	s_waitcnt lgkmcnt(0)
	s_setprio 1
	s_barrier
	v_mfma_f32_16x16x32_bf16 v[60:63], v[128:131], v[192:195], v[60:63]
	v_mfma_f32_16x16x32_bf16 v[56:59], v[136:139], v[192:195], v[56:59]
	v_mfma_f32_16x16x32_bf16 v[44:47], v[128:131], v[200:203], v[44:47]
	v_mfma_f32_16x16x32_bf16 v[40:43], v[136:139], v[200:203], v[40:43]
	v_mfma_f32_16x16x32_bf16 v[28:31], v[128:131], v[208:211], v[28:31]
	v_mfma_f32_16x16x32_bf16 v[24:27], v[136:139], v[208:211], v[24:27]
	v_mfma_f32_16x16x32_bf16 v[12:15], v[128:131], v[216:219], v[12:15]
	v_mfma_f32_16x16x32_bf16 v[8:11], v[136:139], v[216:219], v[8:11]
	v_mfma_f32_16x16x32_bf16 v[60:63], v[132:135], v[196:199], v[60:63]
	v_mfma_f32_16x16x32_bf16 v[56:59], v[140:143], v[196:199], v[56:59]
	v_mfma_f32_16x16x32_bf16 v[44:47], v[132:135], v[204:207], v[44:47]
	v_mfma_f32_16x16x32_bf16 v[40:43], v[140:143], v[204:207], v[40:43]
	v_mfma_f32_16x16x32_bf16 v[28:31], v[132:135], v[212:215], v[28:31]
	v_mfma_f32_16x16x32_bf16 v[24:27], v[140:143], v[212:215], v[24:27]
	v_mfma_f32_16x16x32_bf16 v[12:15], v[132:135], v[220:223], v[12:15]
	v_mfma_f32_16x16x32_bf16 v[8:11], v[140:143], v[220:223], v[8:11]
	s_setprio 0
	s_setprio 1
	v_mfma_f32_16x16x32_bf16 v[52:55], v[160:163], v[192:195], v[52:55]
	v_mfma_f32_16x16x32_bf16 v[48:51], v[184:187], v[192:195], v[48:51]
	v_mfma_f32_16x16x32_bf16 v[36:39], v[160:163], v[200:203], v[36:39]
	v_mfma_f32_16x16x32_bf16 v[32:35], v[184:187], v[200:203], v[32:35]
	v_mfma_f32_16x16x32_bf16 v[20:23], v[160:163], v[208:211], v[20:23]
	v_mfma_f32_16x16x32_bf16 v[16:19], v[184:187], v[208:211], v[16:19]
	v_mfma_f32_16x16x32_bf16 v[4:7], v[160:163], v[216:219], v[4:7]
	v_mfma_f32_16x16x32_bf16 v[0:3], v[184:187], v[216:219], v[0:3]
	v_mfma_f32_16x16x32_bf16 v[52:55], v[164:167], v[196:199], v[52:55]
	v_mfma_f32_16x16x32_bf16 v[48:51], v[188:191], v[196:199], v[48:51]
	v_mfma_f32_16x16x32_bf16 v[36:39], v[164:167], v[204:207], v[36:39]
	v_mfma_f32_16x16x32_bf16 v[32:35], v[188:191], v[204:207], v[32:35]
	v_mfma_f32_16x16x32_bf16 v[20:23], v[164:167], v[212:215], v[20:23]
	v_mfma_f32_16x16x32_bf16 v[16:19], v[188:191], v[212:215], v[16:19]
	s_setprio 2
	s_barrier
	v_mfma_f32_16x16x32_bf16 v[4:7], v[164:167], v[220:223], v[4:7]
	v_mfma_f32_16x16x32_bf16 v[0:3], v[188:191], v[220:223], v[0:3]
	s_setprio 0
	s_add_i32 s92, s92, 2
	s_add_u32 s72, s72, 0x100
	s_addc_u32 s73, s73, 0
	s_add_u32 s90, s90, 0x100
	s_addc_u32 s91, s91, 0
	s_cmp_gt_u32 s92, 29
	s_cbranch_scc0 .LBB0_809
	s_and_b64 vcc, exec, s[42:43]
	s_cbranch_vccz .LBB0_812
	s_barrier

; #define PG8_STAGE(bufoff, gbase, voff) do { _Pragma("unroll") for (int _i = 0; _i < 2; ++_i) \
;         __builtin_amdgcn_global_load_lds((const unsigned*)((const char*)(gbase) + (voff)[_i]), (PG8_LAS unsigned*)(lds + (bufoff) + ldsw + _i * 8192), 16, 0, 0); } while (0)
; #define PG8_LDA(dst, b, h) do { _Pragma("unroll") for (int m = 0; m < 4; ++m) _Pragma("unroll") for (int k = 0; k < 2; ++k) dst[m][k] = *(const PG8_LAS bf16x8*)(lds + PG8_SA(b, h) + aoff + m * 2048 + k * 1024); } while (0)
; #define PG8_LDB(dst, b, h) do { _Pragma("unroll") for (int n = 0; n < 2; ++n) _Pragma("unroll") for (int k = 0; k < 2; ++k) dst[n][k] = *(const PG8_LAS bf16x8*)(lds + PG8_SB(b, h) + boff + n * 2048 + k * 1024); } while (0)
; #define PG8_MMA(ai, bj, At, Bt) do { __builtin_amdgcn_s_setprio(1); _Pragma("unroll") for (int m = 0; m < 4; ++m) _Pragma("unroll") for (int n = 0; n < 2; ++n) _Pragma("unroll") for (int k = 0; k < 2; ++k) \
;         acc[ai][bj][m][n] = __builtin_amdgcn_mfma_f32_16x16x32_bf16(Bt[n][k], At[m][k], acc[ai][bj][m][n], 0, 0, 0); __builtin_amdgcn_s_setprio(0); } while (0)
; #define PG8_WAIT_V(n) asm volatile("s_waitcnt vmcnt(" #n ")" ::: "memory")
; #define PG8_WAIT_L(n) asm volatile("s_waitcnt lgkmcnt(" #n ")" ::: "memory")
; #define PG8_BAR __builtin_amdgcn_s_barrier()
; #define PG8_SCHED __builtin_amdgcn_sched_barrier(0)
; template <class Epi, class Sched, bool ALIGN_EPI = false, bool SP2 = false>
; __device__ __forceinline__ void gemm_phase(PG8_LAS unsigned char* lds, const Gemm g, const Sched& S, const Epi& E) {
;     ...
;         for (int t = 0; t < nt; t += 2) {
;             const bool last = (t == nt - 2);
;             const char* a1 = cA + (size_t)(t + 1) * kstep;
;             const char* a2 = last ? nA : cA + (size_t)(t + 2) * kstep; const char* b2 = last ? nB : cB + (size_t)(t + 2) * kstep;
;             const char* a3 = a2 + kstep; const char* b3 = b2 + kstep;
;             if constexpr (SP2) {
;             PG8_LDB(B0, 0, 0); PG8_LDB(B1, 0, 1); PG8_SCHED; PG8_LDA(At, 0, 0); PG8_STAGE(PG8_SA(1, 1), a1 + hstep, voffA);
;             PG8_WAIT_V(8); PG8_WAIT_L(0); PG8_BAR; PG8_MMA(0, 0, At, B0); PG8_MMA(0, 1, At, B1); PG8_BAR; PG8_SCHED;
;             PG8_LDA(At, 0, 1); PG8_STAGE(PG8_SB(0, 0), b2, voffB); PG8_STAGE(PG8_SB(0, 1), b2 + hstep, voffB); PG8_STAGE(PG8_SA(0, 0), a2, voffA);
.LBB0_1051:
	ds_read_b128 v[128:131], v205
	ds_read_b128 v[132:135], v205 offset:1024
	ds_read_b128 v[154:157], v205 offset:2048
	ds_read_b128 v[158:161], v205 offset:3072
	ds_read_b128 v[162:165], v206
	ds_read_b128 v[166:169], v206 offset:1024
	ds_read_b128 v[170:173], v206 offset:2048
	ds_read_b128 v[174:177], v206 offset:3072
	s_add_u32 s54, s52, 0xfff80080
	s_addc_u32 s55, s53, -1
	s_cmp_eq_u32 s77, 28
	s_cselect_b32 s57, s43, s55
	s_cselect_b32 s56, s49, s54
	s_cselect_b32 s55, s37, s76
	s_cselect_b32 s54, s51, s75
	v_lshl_add_u64 v[218:219], s[52:53], 0, v[144:145]
	s_add_i32 m0, s61, 0xc000
	ds_read_b128 v[178:181], v207
	ds_read_b128 v[182:185], v207 offset:1024
	ds_read_b128 v[186:189], v207 offset:2048
	ds_read_b128 v[190:193], v207 offset:3072
	ds_read_b128 v[194:197], v207 offset:4096
	ds_read_b128 v[198:201], v207 offset:5120
	ds_read_b128 v[210:213], v207 offset:6144
	ds_read_b128 v[214:217], v207 offset:7168
	global_load_lds_dwordx4 v[218:219], off
	v_lshl_add_u64 v[218:219], s[52:53], 0, v[148:149]
	s_add_i32 m0, s61, 0xe000
	s_nop 0
	global_load_lds_dwordx4 v[218:219], off
	s_waitcnt vmcnt(8)
	s_waitcnt lgkmcnt(0)
	s_setprio 1
	s_barrier
	v_mfma_f32_16x16x32_bf16 v[124:127], v[128:131], v[178:181], v[124:127]
	v_mfma_f32_16x16x32_bf16 v[120:123], v[154:157], v[178:181], v[120:123]
	v_mfma_f32_16x16x32_bf16 v[116:119], v[128:131], v[186:189], v[116:119]
	v_mfma_f32_16x16x32_bf16 v[112:115], v[154:157], v[186:189], v[112:115]
	v_mfma_f32_16x16x32_bf16 v[108:111], v[128:131], v[194:197], v[108:111]
	v_mfma_f32_16x16x32_bf16 v[104:107], v[154:157], v[194:197], v[104:107]
	v_mfma_f32_16x16x32_bf16 v[100:103], v[128:131], v[210:213], v[100:103]
	v_mfma_f32_16x16x32_bf16 v[96:99], v[154:157], v[210:213], v[96:99]
	v_mfma_f32_16x16x32_bf16 v[124:127], v[132:135], v[182:185], v[124:127]
	v_mfma_f32_16x16x32_bf16 v[120:123], v[158:161], v[182:185], v[120:123]
	v_mfma_f32_16x16x32_bf16 v[116:119], v[132:135], v[190:193], v[116:119]
	v_mfma_f32_16x16x32_bf16 v[112:115], v[158:161], v[190:193], v[112:115]
	v_mfma_f32_16x16x32_bf16 v[108:111], v[132:135], v[198:201], v[108:111]
	v_mfma_f32_16x16x32_bf16 v[104:107], v[158:161], v[198:201], v[104:107]
	v_mfma_f32_16x16x32_bf16 v[100:103], v[132:135], v[214:217], v[100:103]
	v_mfma_f32_16x16x32_bf16 v[96:99], v[158:161], v[214:217], v[96:99]
	s_setprio 0
	s_setprio 1
	v_mfma_f32_16x16x32_bf16 v[60:63], v[162:165], v[178:181], v[60:63]
	v_mfma_f32_16x16x32_bf16 v[56:59], v[170:173], v[178:181], v[56:59]
	v_mfma_f32_16x16x32_bf16 v[52:55], v[162:165], v[186:189], v[52:55]
	v_mfma_f32_16x16x32_bf16 v[48:51], v[170:173], v[186:189], v[48:51]
	v_mfma_f32_16x16x32_bf16 v[44:47], v[162:165], v[194:197], v[44:47]
	v_mfma_f32_16x16x32_bf16 v[40:43], v[170:173], v[194:197], v[40:43]
	v_mfma_f32_16x16x32_bf16 v[36:39], v[162:165], v[210:213], v[36:39]
	v_mfma_f32_16x16x32_bf16 v[32:35], v[170:173], v[210:213], v[32:35]
	v_mfma_f32_16x16x32_bf16 v[60:63], v[166:169], v[182:185], v[60:63]
	v_mfma_f32_16x16x32_bf16 v[56:59], v[174:177], v[182:185], v[56:59]
	v_mfma_f32_16x16x32_bf16 v[52:55], v[166:169], v[190:193], v[52:55]
	v_mfma_f32_16x16x32_bf16 v[48:51], v[174:177], v[190:193], v[48:51]
	v_mfma_f32_16x16x32_bf16 v[44:47], v[166:169], v[198:201], v[44:47]
	v_mfma_f32_16x16x32_bf16 v[40:43], v[174:177], v[198:201], v[40:43]
	s_setprio 2
	s_barrier
	v_mfma_f32_16x16x32_bf16 v[36:39], v[166:169], v[214:217], v[36:39]
	v_mfma_f32_16x16x32_bf16 v[32:35], v[174:177], v[214:217], v[32:35]
	s_setprio 0
	s_add_i32 s78, s33, s60
	v_lshl_add_u64 v[218:219], s[54:55], 0, v[138:139]
	s_mov_b32 m0, s78
	ds_read_b128 v[178:181], v207 offset:16384
	ds_read_b128 v[182:185], v207 offset:17408
	ds_read_b128 v[186:189], v207 offset:18432
	ds_read_b128 v[190:193], v207 offset:19456
	ds_read_b128 v[194:197], v207 offset:20480
	ds_read_b128 v[198:201], v207 offset:21504
	ds_read_b128 v[210:213], v207 offset:22528
	ds_read_b128 v[214:217], v207 offset:23552
	global_load_lds_dwordx4 v[218:219], off
	s_add_i32 m0, s78, 0x2000
	s_add_u32 s78, s54, 0x80000
	v_lshl_add_u64 v[220:221], s[54:55], 0, v[142:143]
	s_addc_u32 s79, s55, 0
	s_add_i32 s80, s74, s60
	global_load_lds_dwordx4 v[220:221], off
	v_lshl_add_u64 v[222:223], s[78:79], 0, v[138:139]
	s_mov_b32 m0, s80
	v_lshl_add_u64 v[224:225], s[56:57], 0, v[140:141]
	global_load_lds_dwordx4 v[222:223], off
	v_lshl_add_u64 v[222:223], s[78:79], 0, v[142:143]
	s_add_i32 m0, s80, 0x2000
	s_nop 0
	global_load_lds_dwordx4 v[222:223], off
	v_lshl_add_u64 v[222:223], s[56:57], 0, v[136:137]
	s_mov_b32 m0, s61
	s_nop 0
	global_load_lds_dwordx4 v[222:223], off
	s_mov_b32 m0, s62
	s_nop 0
	global_load_lds_dwordx4 v[224:225], off
	s_waitcnt vmcnt(8)
	s_waitcnt lgkmcnt(0)
	s_setprio 1
	s_barrier
; #define PG8_STAGE(bufoff, gbase, voff) do { _Pragma("unroll") for (int _i = 0; _i < 2; ++_i) \
;         __builtin_amdgcn_global_load_lds((const unsigned*)((const char*)(gbase) + (voff)[_i]), (PG8_LAS unsigned*)(lds + (bufoff) + ldsw + _i * 8192), 16, 0, 0); } while (0)
; #define PG8_LDA(dst, b, h) do { _Pragma("unroll") for (int m = 0; m < 4; ++m) _Pragma("unroll") for (int k = 0; k < 2; ++k) dst[m][k] = *(const PG8_LAS bf16x8*)(lds + PG8_SA(b, h) + aoff + m * 2048 + k * 1024); } while (0)
; #define PG8_LDB(dst, b, h) do { _Pragma("unroll") for (int n = 0; n < 2; ++n) _Pragma("unroll") for (int k = 0; k < 2; ++k) dst[n][k] = *(const PG8_LAS bf16x8*)(lds + PG8_SB(b, h) + boff + n * 2048 + k * 1024); } while (0)
; #define PG8_MMA(ai, bj, At, Bt) do { __builtin_amdgcn_s_setprio(1); _Pragma("unroll") for (int m = 0; m < 4; ++m) _Pragma("unroll") for (int n = 0; n < 2; ++n) _Pragma("unroll") for (int k = 0; k < 2; ++k) \
;         acc[ai][bj][m][n] = __builtin_amdgcn_mfma_f32_16x16x32_bf16(Bt[n][k], At[m][k], acc[ai][bj][m][n], 0, 0, 0); __builtin_amdgcn_s_setprio(0); } while (0)
; #define PG8_WAIT_V(n) asm volatile("s_waitcnt vmcnt(" #n ")" ::: "memory")
; #define PG8_WAIT_L(n) asm volatile("s_waitcnt lgkmcnt(" #n ")" ::: "memory")
; #define PG8_BAR __builtin_amdgcn_s_barrier()
; #define PG8_SCHED __builtin_amdgcn_sched_barrier(0)
; template <class Epi, class Sched, bool ALIGN_EPI = false, bool SP2 = false>
; __device__ __forceinline__ void gemm_phase(PG8_LAS unsigned char* lds, const Gemm g, const Sched& S, const Epi& E) {
;     ...
;             PG8_WAIT_V(8); PG8_WAIT_L(0); PG8_BAR; PG8_MMA(1, 0, At, B0); PG8_MMA(1, 1, At, B1); PG8_BAR; PG8_SCHED;
;             PG8_LDB(B0, 1, 0); PG8_LDB(B1, 1, 1); PG8_SCHED; PG8_LDA(At, 1, 0); PG8_STAGE(PG8_SA(0, 1), a2 + hstep, voffA);
;             PG8_WAIT_V(8); PG8_WAIT_L(0); PG8_BAR; PG8_MMA(0, 0, At, B0); PG8_MMA(0, 1, At, B1); PG8_BAR; PG8_SCHED;
	v_mfma_f32_16x16x32_bf16 v[92:95], v[128:131], v[178:181], v[92:95]
	v_mfma_f32_16x16x32_bf16 v[88:91], v[154:157], v[178:181], v[88:91]
	v_mfma_f32_16x16x32_bf16 v[84:87], v[128:131], v[186:189], v[84:87]
	v_mfma_f32_16x16x32_bf16 v[80:83], v[154:157], v[186:189], v[80:83]
	v_mfma_f32_16x16x32_bf16 v[76:79], v[128:131], v[194:197], v[76:79]
	v_mfma_f32_16x16x32_bf16 v[72:75], v[154:157], v[194:197], v[72:75]
	v_mfma_f32_16x16x32_bf16 v[68:71], v[128:131], v[210:213], v[68:71]
	v_mfma_f32_16x16x32_bf16 v[64:67], v[154:157], v[210:213], v[64:67]
	v_mfma_f32_16x16x32_bf16 v[92:95], v[132:135], v[182:185], v[92:95]
	v_mfma_f32_16x16x32_bf16 v[88:91], v[158:161], v[182:185], v[88:91]
	v_mfma_f32_16x16x32_bf16 v[84:87], v[132:135], v[190:193], v[84:87]
	v_mfma_f32_16x16x32_bf16 v[80:83], v[158:161], v[190:193], v[80:83]
	v_mfma_f32_16x16x32_bf16 v[76:79], v[132:135], v[198:201], v[76:79]
	v_mfma_f32_16x16x32_bf16 v[72:75], v[158:161], v[198:201], v[72:75]
	v_mfma_f32_16x16x32_bf16 v[68:71], v[132:135], v[214:217], v[68:71]
	v_mfma_f32_16x16x32_bf16 v[64:67], v[158:161], v[214:217], v[64:67]
	s_setprio 0
	s_setprio 1
	v_mfma_f32_16x16x32_bf16 v[28:31], v[162:165], v[178:181], v[28:31]
	v_mfma_f32_16x16x32_bf16 v[24:27], v[170:173], v[178:181], v[24:27]
	v_mfma_f32_16x16x32_bf16 v[20:23], v[162:165], v[186:189], v[20:23]
	v_mfma_f32_16x16x32_bf16 v[16:19], v[170:173], v[186:189], v[16:19]
	v_mfma_f32_16x16x32_bf16 v[12:15], v[162:165], v[194:197], v[12:15]
	v_mfma_f32_16x16x32_bf16 v[8:11], v[170:173], v[194:197], v[8:11]
	v_mfma_f32_16x16x32_bf16 v[4:7], v[162:165], v[210:213], v[4:7]
	v_mfma_f32_16x16x32_bf16 v[0:3], v[170:173], v[210:213], v[0:3]
	v_mfma_f32_16x16x32_bf16 v[28:31], v[166:169], v[182:185], v[28:31]
	v_mfma_f32_16x16x32_bf16 v[24:27], v[174:177], v[182:185], v[24:27]
	v_mfma_f32_16x16x32_bf16 v[20:23], v[166:169], v[190:193], v[20:23]
	v_mfma_f32_16x16x32_bf16 v[16:19], v[174:177], v[190:193], v[16:19]
	v_mfma_f32_16x16x32_bf16 v[12:15], v[166:169], v[198:201], v[12:15]
	v_mfma_f32_16x16x32_bf16 v[8:11], v[174:177], v[198:201], v[8:11]
	s_setprio 2
	s_barrier
	v_mfma_f32_16x16x32_bf16 v[4:7], v[166:169], v[214:217], v[4:7]
	v_mfma_f32_16x16x32_bf16 v[0:3], v[174:177], v[214:217], v[0:3]
	s_setprio 0
	s_add_i32 s78, 0, 0x18000
	s_add_i32 s79, 0, 0x1c000
	v_add_u32_e32 v158, s78, v203
	v_add_u32_e32 v174, s79, v203
	ds_read_b128 v[128:131], v158
	ds_read_b128 v[132:135], v158 offset:1024
	ds_read_b128 v[154:157], v158 offset:2048
	ds_read_b128 v[158:161], v158 offset:3072
	ds_read_b128 v[162:165], v174
	ds_read_b128 v[166:169], v174 offset:1024
	ds_read_b128 v[170:173], v174 offset:2048
	ds_read_b128 v[174:177], v174 offset:3072
	s_add_u32 s56, s56, 0x80000
	s_addc_u32 s57, s57, 0
	s_mov_b32 m0, s63
	v_lshl_add_u64 v[226:227], s[56:57], 0, v[136:137]
	ds_read_b128 v[178:181], v207 offset:32768
	ds_read_b128 v[182:185], v207 offset:33792
	ds_read_b128 v[186:189], v207 offset:34816
	ds_read_b128 v[190:193], v207 offset:35840
	ds_read_b128 v[194:197], v207 offset:36864
	ds_read_b128 v[198:201], v207 offset:37888
	ds_read_b128 v[210:213], v207 offset:38912
	ds_read_b128 v[214:217], v207 offset:39936
	global_load_lds_dwordx4 v[226:227], off
	v_lshl_add_u64 v[226:227], s[56:57], 0, v[140:141]
	s_mov_b32 m0, s64
	s_nop 0
	global_load_lds_dwordx4 v[226:227], off
	s_waitcnt vmcnt(8)
	s_waitcnt lgkmcnt(0)
	s_setprio 1
	s_barrier
	v_mfma_f32_16x16x32_bf16 v[124:127], v[128:131], v[178:181], v[124:127]
	v_mfma_f32_16x16x32_bf16 v[120:123], v[154:157], v[178:181], v[120:123]
	v_mfma_f32_16x16x32_bf16 v[116:119], v[128:131], v[186:189], v[116:119]
	v_mfma_f32_16x16x32_bf16 v[112:115], v[154:157], v[186:189], v[112:115]
	v_mfma_f32_16x16x32_bf16 v[108:111], v[128:131], v[194:197], v[108:111]
	v_mfma_f32_16x16x32_bf16 v[104:107], v[154:157], v[194:197], v[104:107]
	v_mfma_f32_16x16x32_bf16 v[100:103], v[128:131], v[210:213], v[100:103]
	v_mfma_f32_16x16x32_bf16 v[96:99], v[154:157], v[210:213], v[96:99]
	v_mfma_f32_16x16x32_bf16 v[124:127], v[132:135], v[182:185], v[124:127]
	v_mfma_f32_16x16x32_bf16 v[120:123], v[158:161], v[182:185], v[120:123]
	v_mfma_f32_16x16x32_bf16 v[116:119], v[132:135], v[190:193], v[116:119]
	v_mfma_f32_16x16x32_bf16 v[112:115], v[158:161], v[190:193], v[112:115]
	v_mfma_f32_16x16x32_bf16 v[108:111], v[132:135], v[198:201], v[108:111]
	v_mfma_f32_16x16x32_bf16 v[104:107], v[158:161], v[198:201], v[104:107]
	v_mfma_f32_16x16x32_bf16 v[100:103], v[132:135], v[214:217], v[100:103]
	v_mfma_f32_16x16x32_bf16 v[96:99], v[158:161], v[214:217], v[96:99]
	s_setprio 0
	s_setprio 1
	v_mfma_f32_16x16x32_bf16 v[60:63], v[162:165], v[178:181], v[60:63]
	v_mfma_f32_16x16x32_bf16 v[56:59], v[170:173], v[178:181], v[56:59]
	v_mfma_f32_16x16x32_bf16 v[52:55], v[162:165], v[186:189], v[52:55]
	v_mfma_f32_16x16x32_bf16 v[48:51], v[170:173], v[186:189], v[48:51]
	v_mfma_f32_16x16x32_bf16 v[44:47], v[162:165], v[194:197], v[44:47]
	v_mfma_f32_16x16x32_bf16 v[40:43], v[170:173], v[194:197], v[40:43]
	v_mfma_f32_16x16x32_bf16 v[36:39], v[162:165], v[210:213], v[36:39]
	v_mfma_f32_16x16x32_bf16 v[32:35], v[170:173], v[210:213], v[32:35]
	v_mfma_f32_16x16x32_bf16 v[60:63], v[166:169], v[182:185], v[60:63]
	v_mfma_f32_16x16x32_bf16 v[56:59], v[174:177], v[182:185], v[56:59]
	v_mfma_f32_16x16x32_bf16 v[52:55], v[166:169], v[190:193], v[52:55]
	v_mfma_f32_16x16x32_bf16 v[48:51], v[174:177], v[190:193], v[48:51]
	v_mfma_f32_16x16x32_bf16 v[44:47], v[166:169], v[198:201], v[44:47]
	v_mfma_f32_16x16x32_bf16 v[40:43], v[174:177], v[198:201], v[40:43]
	s_setprio 2
	s_barrier
; #define PG8_STAGE(bufoff, gbase, voff) do { _Pragma("unroll") for (int _i = 0; _i < 2; ++_i) \
;         __builtin_amdgcn_global_load_lds((const unsigned*)((const char*)(gbase) + (voff)[_i]), (PG8_LAS unsigned*)(lds + (bufoff) + ldsw + _i * 8192), 16, 0, 0); } while (0)
; #define PG8_LDA(dst, b, h) do { _Pragma("unroll") for (int m = 0; m < 4; ++m) _Pragma("unroll") for (int k = 0; k < 2; ++k) dst[m][k] = *(const PG8_LAS bf16x8*)(lds + PG8_SA(b, h) + aoff + m * 2048 + k * 1024); } while (0)
; #define PG8_MMA(ai, bj, At, Bt) do { __builtin_amdgcn_s_setprio(1); _Pragma("unroll") for (int m = 0; m < 4; ++m) _Pragma("unroll") for (int n = 0; n < 2; ++n) _Pragma("unroll") for (int k = 0; k < 2; ++k) \
;         acc[ai][bj][m][n] = __builtin_amdgcn_mfma_f32_16x16x32_bf16(Bt[n][k], At[m][k], acc[ai][bj][m][n], 0, 0, 0); __builtin_amdgcn_s_setprio(0); } while (0)
; #define PG8_WAIT_V(n) asm volatile("s_waitcnt vmcnt(" #n ")" ::: "memory")
; #define PG8_WAIT_L(n) asm volatile("s_waitcnt lgkmcnt(" #n ")" ::: "memory")
; #define PG8_BAR __builtin_amdgcn_s_barrier()
; #define PG8_SCHED __builtin_amdgcn_sched_barrier(0)
; template <class Epi, class Sched, bool ALIGN_EPI = false, bool SP2 = false>
; __device__ __forceinline__ void gemm_phase(PG8_LAS unsigned char* lds, const Gemm g, const Sched& S, const Epi& E) {
;     ...
;             PG8_WAIT_V(8); PG8_WAIT_L(0); PG8_BAR; PG8_MMA(0, 0, At, B0); PG8_MMA(0, 1, At, B1); PG8_BAR; PG8_SCHED;
;             PG8_LDA(At, 1, 1); PG8_STAGE(PG8_SB(1, 0), b3, voffB); PG8_STAGE(PG8_SB(1, 1), b3 + hstep, voffB); PG8_STAGE(PG8_SA(1, 0), a3, voffA);
;             PG8_WAIT_V(8); PG8_WAIT_L(0); PG8_BAR; PG8_MMA(1, 0, At, B0); PG8_MMA(1, 1, At, B1); PG8_BAR; PG8_SCHED;
;     ...
;         if constexpr (ALIGN_EPI) { if (wr == 0) PG8_BAR; }
	v_mfma_f32_16x16x32_bf16 v[36:39], v[166:169], v[214:217], v[36:39]
	v_mfma_f32_16x16x32_bf16 v[32:35], v[174:177], v[214:217], v[32:35]
	s_setprio 0
	s_add_i32 s56, s78, s60
	v_lshl_add_u64 v[218:219], v[218:219], 0, s[12:13]
	s_mov_b32 m0, s56
	ds_read_b128 v[178:181], v207 offset:49152
	ds_read_b128 v[182:185], v207 offset:50176
	ds_read_b128 v[186:189], v207 offset:51200
	ds_read_b128 v[190:193], v207 offset:52224
	ds_read_b128 v[194:197], v207 offset:53248
	ds_read_b128 v[198:201], v207 offset:54272
	ds_read_b128 v[210:213], v207 offset:55296
	ds_read_b128 v[214:217], v207 offset:56320
	global_load_lds_dwordx4 v[218:219], off
	s_add_i32 m0, s56, 0x2000
	s_add_u32 s54, s54, 0x80080
	v_lshl_add_u64 v[218:219], v[220:221], 0, s[12:13]
	s_addc_u32 s55, s55, 0
	s_add_i32 s56, s79, s60
	global_load_lds_dwordx4 v[218:219], off
	v_lshl_add_u64 v[218:219], s[54:55], 0, v[138:139]
	s_mov_b32 m0, s56
	s_nop 0
	global_load_lds_dwordx4 v[218:219], off
	v_lshl_add_u64 v[218:219], s[54:55], 0, v[142:143]
	s_add_i32 m0, s56, 0x2000
	s_nop 0
	global_load_lds_dwordx4 v[218:219], off
	v_lshl_add_u64 v[218:219], v[222:223], 0, s[12:13]
	s_mov_b32 m0, s70
	s_nop 0
	global_load_lds_dwordx4 v[218:219], off
	v_lshl_add_u64 v[218:219], v[224:225], 0, s[12:13]
	s_mov_b32 m0, s71
	s_nop 0
	global_load_lds_dwordx4 v[218:219], off
	s_waitcnt vmcnt(8)
	s_waitcnt lgkmcnt(0)
	s_setprio 1
	s_barrier
	v_mfma_f32_16x16x32_bf16 v[92:95], v[128:131], v[178:181], v[92:95]
	v_mfma_f32_16x16x32_bf16 v[88:91], v[154:157], v[178:181], v[88:91]
	v_mfma_f32_16x16x32_bf16 v[84:87], v[128:131], v[186:189], v[84:87]
	v_mfma_f32_16x16x32_bf16 v[80:83], v[154:157], v[186:189], v[80:83]
	v_mfma_f32_16x16x32_bf16 v[76:79], v[128:131], v[194:197], v[76:79]
	v_mfma_f32_16x16x32_bf16 v[72:75], v[154:157], v[194:197], v[72:75]
	v_mfma_f32_16x16x32_bf16 v[68:71], v[128:131], v[210:213], v[68:71]
	v_mfma_f32_16x16x32_bf16 v[64:67], v[154:157], v[210:213], v[64:67]
	v_mfma_f32_16x16x32_bf16 v[92:95], v[132:135], v[182:185], v[92:95]
	v_mfma_f32_16x16x32_bf16 v[88:91], v[158:161], v[182:185], v[88:91]
	v_mfma_f32_16x16x32_bf16 v[84:87], v[132:135], v[190:193], v[84:87]
	v_mfma_f32_16x16x32_bf16 v[80:83], v[158:161], v[190:193], v[80:83]
	v_mfma_f32_16x16x32_bf16 v[76:79], v[132:135], v[198:201], v[76:79]
	v_mfma_f32_16x16x32_bf16 v[72:75], v[158:161], v[198:201], v[72:75]
	v_mfma_f32_16x16x32_bf16 v[68:71], v[132:135], v[214:217], v[68:71]
	v_mfma_f32_16x16x32_bf16 v[64:67], v[158:161], v[214:217], v[64:67]
	s_setprio 0
	s_setprio 1
	v_mfma_f32_16x16x32_bf16 v[28:31], v[162:165], v[178:181], v[28:31]
	v_mfma_f32_16x16x32_bf16 v[24:27], v[170:173], v[178:181], v[24:27]
	v_mfma_f32_16x16x32_bf16 v[20:23], v[162:165], v[186:189], v[20:23]
	v_mfma_f32_16x16x32_bf16 v[16:19], v[170:173], v[186:189], v[16:19]
	v_mfma_f32_16x16x32_bf16 v[12:15], v[162:165], v[194:197], v[12:15]
	v_mfma_f32_16x16x32_bf16 v[8:11], v[170:173], v[194:197], v[8:11]
	v_mfma_f32_16x16x32_bf16 v[4:7], v[162:165], v[210:213], v[4:7]
	v_mfma_f32_16x16x32_bf16 v[0:3], v[170:173], v[210:213], v[0:3]
	v_mfma_f32_16x16x32_bf16 v[28:31], v[166:169], v[182:185], v[28:31]
	v_mfma_f32_16x16x32_bf16 v[24:27], v[174:177], v[182:185], v[24:27]
	v_mfma_f32_16x16x32_bf16 v[20:23], v[166:169], v[190:193], v[20:23]
	v_mfma_f32_16x16x32_bf16 v[16:19], v[174:177], v[190:193], v[16:19]
	v_mfma_f32_16x16x32_bf16 v[12:15], v[166:169], v[198:201], v[12:15]
	v_mfma_f32_16x16x32_bf16 v[8:11], v[174:177], v[198:201], v[8:11]
	s_setprio 2
	s_barrier
	v_mfma_f32_16x16x32_bf16 v[4:7], v[166:169], v[214:217], v[4:7]
	v_mfma_f32_16x16x32_bf16 v[0:3], v[174:177], v[214:217], v[0:3]
	s_setprio 0
	s_add_i32 s77, s77, 2
	s_add_u32 s52, s52, 0x100
	s_addc_u32 s53, s53, 0
	s_add_u32 s75, s75, 0x100
	s_addc_u32 s76, s76, 0
	s_cmp_gt_u32 s77, 29
	s_cbranch_scc0 .LBB0_1051
	s_and_b64 vcc, exec, s[14:15]
	s_cbranch_vccz .LBB0_1054
	s_barrier

; #define PG8_STAGE(bufoff, gbase, voff) do { _Pragma("unroll") for (int _i = 0; _i < 2; ++_i) \
;         __builtin_amdgcn_global_load_lds((const unsigned*)((const char*)(gbase) + (voff)[_i]), (PG8_LAS unsigned*)(lds + (bufoff) + ldsw + _i * 8192), 16, 0, 0); } while (0)
; #define PG8_LDA(dst, b, h) do { _Pragma("unroll") for (int m = 0; m < 4; ++m) _Pragma("unroll") for (int k = 0; k < 2; ++k) dst[m][k] = *(const PG8_LAS bf16x8*)(lds + PG8_SA(b, h) + aoff + m * 2048 + k * 1024); } while (0)
; #define PG8_LDB(dst, b, h) do { _Pragma("unroll") for (int n = 0; n < 2; ++n) _Pragma("unroll") for (int k = 0; k < 2; ++k) dst[n][k] = *(const PG8_LAS bf16x8*)(lds + PG8_SB(b, h) + boff + n * 2048 + k * 1024); } while (0)
; #define PG8_MMA(ai, bj, At, Bt) do { __builtin_amdgcn_s_setprio(1); _Pragma("unroll") for (int m = 0; m < 4; ++m) _Pragma("unroll") for (int n = 0; n < 2; ++n) _Pragma("unroll") for (int k = 0; k < 2; ++k) \
;         acc[ai][bj][m][n] = __builtin_amdgcn_mfma_f32_16x16x32_bf16(Bt[n][k], At[m][k], acc[ai][bj][m][n], 0, 0, 0); __builtin_amdgcn_s_setprio(0); } while (0)
; #define PG8_WAIT_V(n) asm volatile("s_waitcnt vmcnt(" #n ")" ::: "memory")
; #define PG8_WAIT_L(n) asm volatile("s_waitcnt lgkmcnt(" #n ")" ::: "memory")
; #define PG8_BAR __builtin_amdgcn_s_barrier()
; #define PG8_SCHED __builtin_amdgcn_sched_barrier(0)
; template <class Epi, class Sched, bool ALIGN_EPI = false, bool SP2 = false>
; __device__ __forceinline__ void gemm_phase(PG8_LAS unsigned char* lds, const Gemm g, const Sched& S, const Epi& E) {
;     ...
;         for (int t = 0; t < nt; t += 2) {
;             const bool last = (t == nt - 2);
;             const char* a1 = cA + (size_t)(t + 1) * kstep;
;             const char* a2 = last ? nA : cA + (size_t)(t + 2) * kstep; const char* b2 = last ? nB : cB + (size_t)(t + 2) * kstep;
;             const char* a3 = a2 + kstep; const char* b3 = b2 + kstep;
;             if constexpr (SP2) {
;             PG8_LDB(B0, 0, 0); PG8_LDB(B1, 0, 1); PG8_SCHED; PG8_LDA(At, 0, 0); PG8_STAGE(PG8_SA(1, 1), a1 + hstep, voffA);
;             PG8_WAIT_V(8); PG8_WAIT_L(0); PG8_BAR; PG8_MMA(0, 0, At, B0); PG8_MMA(0, 1, At, B1); PG8_BAR; PG8_SCHED;
;             PG8_LDA(At, 0, 1); PG8_STAGE(PG8_SB(0, 0), b2, voffB); PG8_STAGE(PG8_SB(0, 1), b2 + hstep, voffB); PG8_STAGE(PG8_SA(0, 0), a2, voffA);
.LBB0_1142:
	ds_read_b128 v[80:83], v171
	ds_read_b128 v[84:87], v171 offset:1024
	ds_read_b128 v[88:91], v171 offset:2048
	ds_read_b128 v[92:95], v171 offset:3072
	ds_read_b128 v[164:167], v172
	ds_read_b128 v[176:179], v172 offset:1024
	ds_read_b128 v[180:183], v172 offset:2048
	ds_read_b128 v[184:187], v172 offset:3072
	s_add_u32 s44, s42, 0xfff80080
	s_addc_u32 s45, s43, -1
	s_cmp_eq_u32 s64, 28
	s_cselect_b32 s47, s15, s45
	s_cselect_b32 s46, s60, s44
	s_cselect_b32 s45, s13, s63
	s_cselect_b32 s44, s61, s62
	v_lshl_add_u64 v[220:221], s[42:43], 0, v[156:157]
	s_add_i32 m0, s41, 0xc000
	ds_read_b128 v[188:191], v173
	ds_read_b128 v[192:195], v173 offset:1024
	ds_read_b128 v[196:199], v173 offset:2048
	ds_read_b128 v[200:203], v173 offset:3072
	ds_read_b128 v[204:207], v173 offset:4096
	ds_read_b128 v[208:211], v173 offset:5120
	ds_read_b128 v[212:215], v173 offset:6144
	ds_read_b128 v[216:219], v173 offset:7168
	global_load_lds_dwordx4 v[220:221], off
	v_lshl_add_u64 v[220:221], s[42:43], 0, v[158:159]
	s_add_i32 m0, s41, 0xe000
	s_nop 0
	global_load_lds_dwordx4 v[220:221], off
	s_waitcnt vmcnt(8)
	s_waitcnt lgkmcnt(0)
	s_setprio 1
	s_barrier
	v_mfma_f32_16x16x32_bf16 v[140:143], v[80:83], v[188:191], v[140:143]
	v_mfma_f32_16x16x32_bf16 v[136:139], v[88:91], v[188:191], v[136:139]
	v_mfma_f32_16x16x32_bf16 v[124:127], v[80:83], v[196:199], v[124:127]
	v_mfma_f32_16x16x32_bf16 v[120:123], v[88:91], v[196:199], v[120:123]
	v_mfma_f32_16x16x32_bf16 v[108:111], v[80:83], v[204:207], v[108:111]
	v_mfma_f32_16x16x32_bf16 v[104:107], v[88:91], v[204:207], v[104:107]
	v_mfma_f32_16x16x32_bf16 v[76:79], v[80:83], v[212:215], v[76:79]
	v_mfma_f32_16x16x32_bf16 v[72:75], v[88:91], v[212:215], v[72:75]
	v_mfma_f32_16x16x32_bf16 v[140:143], v[84:87], v[192:195], v[140:143]
	v_mfma_f32_16x16x32_bf16 v[136:139], v[92:95], v[192:195], v[136:139]
	v_mfma_f32_16x16x32_bf16 v[124:127], v[84:87], v[200:203], v[124:127]
	v_mfma_f32_16x16x32_bf16 v[120:123], v[92:95], v[200:203], v[120:123]
	v_mfma_f32_16x16x32_bf16 v[108:111], v[84:87], v[208:211], v[108:111]
	v_mfma_f32_16x16x32_bf16 v[104:107], v[92:95], v[208:211], v[104:107]
	v_mfma_f32_16x16x32_bf16 v[76:79], v[84:87], v[216:219], v[76:79]
	v_mfma_f32_16x16x32_bf16 v[72:75], v[92:95], v[216:219], v[72:75]
	s_setprio 0
	s_setprio 1
	v_mfma_f32_16x16x32_bf16 v[132:135], v[164:167], v[188:191], v[132:135]
	v_mfma_f32_16x16x32_bf16 v[128:131], v[180:183], v[188:191], v[128:131]
	v_mfma_f32_16x16x32_bf16 v[116:119], v[164:167], v[196:199], v[116:119]
	v_mfma_f32_16x16x32_bf16 v[112:115], v[180:183], v[196:199], v[112:115]
	v_mfma_f32_16x16x32_bf16 v[100:103], v[164:167], v[204:207], v[100:103]
	v_mfma_f32_16x16x32_bf16 v[96:99], v[180:183], v[204:207], v[96:99]
	v_mfma_f32_16x16x32_bf16 v[68:71], v[164:167], v[212:215], v[68:71]
	v_mfma_f32_16x16x32_bf16 v[64:67], v[180:183], v[212:215], v[64:67]
	v_mfma_f32_16x16x32_bf16 v[132:135], v[176:179], v[192:195], v[132:135]
	v_mfma_f32_16x16x32_bf16 v[128:131], v[184:187], v[192:195], v[128:131]
	v_mfma_f32_16x16x32_bf16 v[116:119], v[176:179], v[200:203], v[116:119]
	v_mfma_f32_16x16x32_bf16 v[112:115], v[184:187], v[200:203], v[112:115]
	v_mfma_f32_16x16x32_bf16 v[100:103], v[176:179], v[208:211], v[100:103]
	v_mfma_f32_16x16x32_bf16 v[96:99], v[184:187], v[208:211], v[96:99]
	s_setprio 2
	s_barrier
	v_mfma_f32_16x16x32_bf16 v[68:71], v[176:179], v[216:219], v[68:71]
	v_mfma_f32_16x16x32_bf16 v[64:67], v[184:187], v[216:219], v[64:67]
	s_setprio 0
	s_add_i32 s65, s56, s33
	v_lshl_add_u64 v[220:221], s[44:45], 0, v[148:149]
	s_mov_b32 m0, s65
	ds_read_b128 v[188:191], v173 offset:16384
	ds_read_b128 v[192:195], v173 offset:17408
	ds_read_b128 v[196:199], v173 offset:18432
	ds_read_b128 v[200:203], v173 offset:19456
	ds_read_b128 v[204:207], v173 offset:20480
	ds_read_b128 v[208:211], v173 offset:21504
	ds_read_b128 v[212:215], v173 offset:22528
	ds_read_b128 v[216:219], v173 offset:23552
	global_load_lds_dwordx4 v[220:221], off
	s_add_i32 m0, s65, 0x2000
	s_add_u32 s66, s44, 0x80000
	v_lshl_add_u64 v[222:223], s[44:45], 0, v[152:153]
	s_addc_u32 s67, s45, 0
	s_add_i32 s65, s57, s33
	global_load_lds_dwordx4 v[222:223], off
	v_lshl_add_u64 v[224:225], s[66:67], 0, v[148:149]
	s_mov_b32 m0, s65
	v_lshl_add_u64 v[226:227], s[46:47], 0, v[150:151]
	global_load_lds_dwordx4 v[224:225], off
	v_lshl_add_u64 v[224:225], s[66:67], 0, v[152:153]
	s_add_i32 m0, s65, 0x2000
	s_nop 0
	global_load_lds_dwordx4 v[224:225], off
	v_lshl_add_u64 v[224:225], s[46:47], 0, v[144:145]
	s_mov_b32 m0, s41
	s_nop 0
	global_load_lds_dwordx4 v[224:225], off
	s_mov_b32 m0, s48
	s_nop 0
	global_load_lds_dwordx4 v[226:227], off
	s_waitcnt vmcnt(8)
	s_waitcnt lgkmcnt(0)
	s_setprio 1
	s_barrier
; #define PG8_STAGE(bufoff, gbase, voff) do { _Pragma("unroll") for (int _i = 0; _i < 2; ++_i) \
;         __builtin_amdgcn_global_load_lds((const unsigned*)((const char*)(gbase) + (voff)[_i]), (PG8_LAS unsigned*)(lds + (bufoff) + ldsw + _i * 8192), 16, 0, 0); } while (0)
; #define PG8_LDA(dst, b, h) do { _Pragma("unroll") for (int m = 0; m < 4; ++m) _Pragma("unroll") for (int k = 0; k < 2; ++k) dst[m][k] = *(const PG8_LAS bf16x8*)(lds + PG8_SA(b, h) + aoff + m * 2048 + k * 1024); } while (0)
; #define PG8_LDB(dst, b, h) do { _Pragma("unroll") for (int n = 0; n < 2; ++n) _Pragma("unroll") for (int k = 0; k < 2; ++k) dst[n][k] = *(const PG8_LAS bf16x8*)(lds + PG8_SB(b, h) + boff + n * 2048 + k * 1024); } while (0)
; #define PG8_MMA(ai, bj, At, Bt) do { __builtin_amdgcn_s_setprio(1); _Pragma("unroll") for (int m = 0; m < 4; ++m) _Pragma("unroll") for (int n = 0; n < 2; ++n) _Pragma("unroll") for (int k = 0; k < 2; ++k) \
;         acc[ai][bj][m][n] = __builtin_amdgcn_mfma_f32_16x16x32_bf16(Bt[n][k], At[m][k], acc[ai][bj][m][n], 0, 0, 0); __builtin_amdgcn_s_setprio(0); } while (0)
; #define PG8_WAIT_V(n) asm volatile("s_waitcnt vmcnt(" #n ")" ::: "memory")
; #define PG8_WAIT_L(n) asm volatile("s_waitcnt lgkmcnt(" #n ")" ::: "memory")
; #define PG8_BAR __builtin_amdgcn_s_barrier()
; #define PG8_SCHED __builtin_amdgcn_sched_barrier(0)
; template <class Epi, class Sched, bool ALIGN_EPI = false, bool SP2 = false>
; __device__ __forceinline__ void gemm_phase(PG8_LAS unsigned char* lds, const Gemm g, const Sched& S, const Epi& E) {
;     ...
;             PG8_WAIT_V(8); PG8_WAIT_L(0); PG8_BAR; PG8_MMA(1, 0, At, B0); PG8_MMA(1, 1, At, B1); PG8_BAR; PG8_SCHED;
;             PG8_LDB(B0, 1, 0); PG8_LDB(B1, 1, 1); PG8_SCHED; PG8_LDA(At, 1, 0); PG8_STAGE(PG8_SA(0, 1), a2 + hstep, voffA);
;             PG8_WAIT_V(8); PG8_WAIT_L(0); PG8_BAR; PG8_MMA(0, 0, At, B0); PG8_MMA(0, 1, At, B1); PG8_BAR; PG8_SCHED;
	v_mfma_f32_16x16x32_bf16 v[60:63], v[80:83], v[188:191], v[60:63]
	v_mfma_f32_16x16x32_bf16 v[56:59], v[88:91], v[188:191], v[56:59]
	v_mfma_f32_16x16x32_bf16 v[44:47], v[80:83], v[196:199], v[44:47]
	v_mfma_f32_16x16x32_bf16 v[40:43], v[88:91], v[196:199], v[40:43]
	v_mfma_f32_16x16x32_bf16 v[28:31], v[80:83], v[204:207], v[28:31]
	v_mfma_f32_16x16x32_bf16 v[24:27], v[88:91], v[204:207], v[24:27]
	v_mfma_f32_16x16x32_bf16 v[12:15], v[80:83], v[212:215], v[12:15]
	v_mfma_f32_16x16x32_bf16 v[8:11], v[88:91], v[212:215], v[8:11]
	v_mfma_f32_16x16x32_bf16 v[60:63], v[84:87], v[192:195], v[60:63]
	v_mfma_f32_16x16x32_bf16 v[56:59], v[92:95], v[192:195], v[56:59]
	v_mfma_f32_16x16x32_bf16 v[44:47], v[84:87], v[200:203], v[44:47]
	v_mfma_f32_16x16x32_bf16 v[40:43], v[92:95], v[200:203], v[40:43]
	v_mfma_f32_16x16x32_bf16 v[28:31], v[84:87], v[208:211], v[28:31]
	v_mfma_f32_16x16x32_bf16 v[24:27], v[92:95], v[208:211], v[24:27]
	v_mfma_f32_16x16x32_bf16 v[12:15], v[84:87], v[216:219], v[12:15]
	v_mfma_f32_16x16x32_bf16 v[8:11], v[92:95], v[216:219], v[8:11]
	s_setprio 0
	s_setprio 1
	v_mfma_f32_16x16x32_bf16 v[52:55], v[164:167], v[188:191], v[52:55]
	v_mfma_f32_16x16x32_bf16 v[48:51], v[180:183], v[188:191], v[48:51]
	v_mfma_f32_16x16x32_bf16 v[36:39], v[164:167], v[196:199], v[36:39]
	v_mfma_f32_16x16x32_bf16 v[32:35], v[180:183], v[196:199], v[32:35]
	v_mfma_f32_16x16x32_bf16 v[20:23], v[164:167], v[204:207], v[20:23]
	v_mfma_f32_16x16x32_bf16 v[16:19], v[180:183], v[204:207], v[16:19]
	v_mfma_f32_16x16x32_bf16 v[4:7], v[164:167], v[212:215], v[4:7]
	v_mfma_f32_16x16x32_bf16 v[0:3], v[180:183], v[212:215], v[0:3]
	v_mfma_f32_16x16x32_bf16 v[52:55], v[176:179], v[192:195], v[52:55]
	v_mfma_f32_16x16x32_bf16 v[48:51], v[184:187], v[192:195], v[48:51]
	v_mfma_f32_16x16x32_bf16 v[36:39], v[176:179], v[200:203], v[36:39]
	v_mfma_f32_16x16x32_bf16 v[32:35], v[184:187], v[200:203], v[32:35]
	v_mfma_f32_16x16x32_bf16 v[20:23], v[176:179], v[208:211], v[20:23]
	v_mfma_f32_16x16x32_bf16 v[16:19], v[184:187], v[208:211], v[16:19]
	s_setprio 2
	s_barrier
	v_mfma_f32_16x16x32_bf16 v[4:7], v[176:179], v[216:219], v[4:7]
	v_mfma_f32_16x16x32_bf16 v[0:3], v[184:187], v[216:219], v[0:3]
	s_setprio 0
	s_add_i32 s65, 0, 0x18000
	s_add_i32 s66, 0, 0x1c000
	v_add_u32_e32 v92, s65, v169
	v_add_u32_e32 v184, s66, v169
	ds_read_b128 v[80:83], v92
	ds_read_b128 v[84:87], v92 offset:1024
	ds_read_b128 v[88:91], v92 offset:2048
	ds_read_b128 v[92:95], v92 offset:3072
	ds_read_b128 v[164:167], v184
	ds_read_b128 v[176:179], v184 offset:1024
	ds_read_b128 v[180:183], v184 offset:2048
	ds_read_b128 v[184:187], v184 offset:3072
	s_add_u32 s46, s46, 0x80000
	s_addc_u32 s47, s47, 0
	s_mov_b32 m0, s49
	v_lshl_add_u64 v[228:229], s[46:47], 0, v[144:145]
	ds_read_b128 v[188:191], v173 offset:32768
	ds_read_b128 v[192:195], v173 offset:33792
	ds_read_b128 v[196:199], v173 offset:34816
	ds_read_b128 v[200:203], v173 offset:35840
	ds_read_b128 v[204:207], v173 offset:36864
	ds_read_b128 v[208:211], v173 offset:37888
	ds_read_b128 v[212:215], v173 offset:38912
	ds_read_b128 v[216:219], v173 offset:39936
	global_load_lds_dwordx4 v[228:229], off
	v_lshl_add_u64 v[228:229], s[46:47], 0, v[150:151]
	s_mov_b32 m0, s50
	s_nop 0
	global_load_lds_dwordx4 v[228:229], off
	s_waitcnt vmcnt(8)
	s_waitcnt lgkmcnt(0)
	s_setprio 1
	s_barrier
	v_mfma_f32_16x16x32_bf16 v[140:143], v[80:83], v[188:191], v[140:143]
	v_mfma_f32_16x16x32_bf16 v[136:139], v[88:91], v[188:191], v[136:139]
	v_mfma_f32_16x16x32_bf16 v[124:127], v[80:83], v[196:199], v[124:127]
	v_mfma_f32_16x16x32_bf16 v[120:123], v[88:91], v[196:199], v[120:123]
	v_mfma_f32_16x16x32_bf16 v[108:111], v[80:83], v[204:207], v[108:111]
	v_mfma_f32_16x16x32_bf16 v[104:107], v[88:91], v[204:207], v[104:107]
	v_mfma_f32_16x16x32_bf16 v[76:79], v[80:83], v[212:215], v[76:79]
	v_mfma_f32_16x16x32_bf16 v[72:75], v[88:91], v[212:215], v[72:75]
	v_mfma_f32_16x16x32_bf16 v[140:143], v[84:87], v[192:195], v[140:143]
	v_mfma_f32_16x16x32_bf16 v[136:139], v[92:95], v[192:195], v[136:139]
	v_mfma_f32_16x16x32_bf16 v[124:127], v[84:87], v[200:203], v[124:127]
	v_mfma_f32_16x16x32_bf16 v[120:123], v[92:95], v[200:203], v[120:123]
	v_mfma_f32_16x16x32_bf16 v[108:111], v[84:87], v[208:211], v[108:111]
	v_mfma_f32_16x16x32_bf16 v[104:107], v[92:95], v[208:211], v[104:107]
	v_mfma_f32_16x16x32_bf16 v[76:79], v[84:87], v[216:219], v[76:79]
	v_mfma_f32_16x16x32_bf16 v[72:75], v[92:95], v[216:219], v[72:75]
	s_setprio 0
	s_setprio 1
	v_mfma_f32_16x16x32_bf16 v[132:135], v[164:167], v[188:191], v[132:135]
	v_mfma_f32_16x16x32_bf16 v[128:131], v[180:183], v[188:191], v[128:131]
	v_mfma_f32_16x16x32_bf16 v[116:119], v[164:167], v[196:199], v[116:119]
	v_mfma_f32_16x16x32_bf16 v[112:115], v[180:183], v[196:199], v[112:115]
	v_mfma_f32_16x16x32_bf16 v[100:103], v[164:167], v[204:207], v[100:103]
	v_mfma_f32_16x16x32_bf16 v[96:99], v[180:183], v[204:207], v[96:99]
	v_mfma_f32_16x16x32_bf16 v[68:71], v[164:167], v[212:215], v[68:71]
	v_mfma_f32_16x16x32_bf16 v[64:67], v[180:183], v[212:215], v[64:67]
	v_mfma_f32_16x16x32_bf16 v[132:135], v[176:179], v[192:195], v[132:135]
	v_mfma_f32_16x16x32_bf16 v[128:131], v[184:187], v[192:195], v[128:131]
	v_mfma_f32_16x16x32_bf16 v[116:119], v[176:179], v[200:203], v[116:119]
	v_mfma_f32_16x16x32_bf16 v[112:115], v[184:187], v[200:203], v[112:115]
	v_mfma_f32_16x16x32_bf16 v[100:103], v[176:179], v[208:211], v[100:103]
	v_mfma_f32_16x16x32_bf16 v[96:99], v[184:187], v[208:211], v[96:99]
	s_setprio 2
	s_barrier
; #define PG8_STAGE(bufoff, gbase, voff) do { _Pragma("unroll") for (int _i = 0; _i < 2; ++_i) \
;         __builtin_amdgcn_global_load_lds((const unsigned*)((const char*)(gbase) + (voff)[_i]), (PG8_LAS unsigned*)(lds + (bufoff) + ldsw + _i * 8192), 16, 0, 0); } while (0)
; #define PG8_LDA(dst, b, h) do { _Pragma("unroll") for (int m = 0; m < 4; ++m) _Pragma("unroll") for (int k = 0; k < 2; ++k) dst[m][k] = *(const PG8_LAS bf16x8*)(lds + PG8_SA(b, h) + aoff + m * 2048 + k * 1024); } while (0)
; #define PG8_MMA(ai, bj, At, Bt) do { __builtin_amdgcn_s_setprio(1); _Pragma("unroll") for (int m = 0; m < 4; ++m) _Pragma("unroll") for (int n = 0; n < 2; ++n) _Pragma("unroll") for (int k = 0; k < 2; ++k) \
;         acc[ai][bj][m][n] = __builtin_amdgcn_mfma_f32_16x16x32_bf16(Bt[n][k], At[m][k], acc[ai][bj][m][n], 0, 0, 0); __builtin_amdgcn_s_setprio(0); } while (0)
; #define PG8_WAIT_V(n) asm volatile("s_waitcnt vmcnt(" #n ")" ::: "memory")
; #define PG8_WAIT_L(n) asm volatile("s_waitcnt lgkmcnt(" #n ")" ::: "memory")
; #define PG8_BAR __builtin_amdgcn_s_barrier()
; #define PG8_SCHED __builtin_amdgcn_sched_barrier(0)
; template <class Epi, class Sched, bool ALIGN_EPI = false, bool SP2 = false>
; __device__ __forceinline__ void gemm_phase(PG8_LAS unsigned char* lds, const Gemm g, const Sched& S, const Epi& E) {
;     ...
;             PG8_WAIT_V(8); PG8_WAIT_L(0); PG8_BAR; PG8_MMA(0, 0, At, B0); PG8_MMA(0, 1, At, B1); PG8_BAR; PG8_SCHED;
;             PG8_LDA(At, 1, 1); PG8_STAGE(PG8_SB(1, 0), b3, voffB); PG8_STAGE(PG8_SB(1, 1), b3 + hstep, voffB); PG8_STAGE(PG8_SA(1, 0), a3, voffA);
;             PG8_WAIT_V(8); PG8_WAIT_L(0); PG8_BAR; PG8_MMA(1, 0, At, B0); PG8_MMA(1, 1, At, B1); PG8_BAR; PG8_SCHED;
;     ...
;         if constexpr (ALIGN_EPI) { if (wr == 0) PG8_BAR; }
	v_mfma_f32_16x16x32_bf16 v[68:71], v[176:179], v[216:219], v[68:71]
	v_mfma_f32_16x16x32_bf16 v[64:67], v[184:187], v[216:219], v[64:67]
	s_setprio 0
	s_add_i32 s46, s65, s33
	v_lshl_add_u64 v[220:221], v[220:221], 0, s[8:9]
	s_mov_b32 m0, s46
	ds_read_b128 v[188:191], v173 offset:49152
	ds_read_b128 v[192:195], v173 offset:50176
	ds_read_b128 v[196:199], v173 offset:51200
	ds_read_b128 v[200:203], v173 offset:52224
	ds_read_b128 v[204:207], v173 offset:53248
	ds_read_b128 v[208:211], v173 offset:54272
	ds_read_b128 v[212:215], v173 offset:55296
	ds_read_b128 v[216:219], v173 offset:56320
	global_load_lds_dwordx4 v[220:221], off
	s_add_i32 m0, s46, 0x2000
	s_add_u32 s44, s44, 0x80080
	v_lshl_add_u64 v[220:221], v[222:223], 0, s[8:9]
	s_addc_u32 s45, s45, 0
	s_add_i32 s46, s66, s33
	global_load_lds_dwordx4 v[220:221], off
	v_lshl_add_u64 v[220:221], s[44:45], 0, v[148:149]
	s_mov_b32 m0, s46
	s_nop 0
	global_load_lds_dwordx4 v[220:221], off
	v_lshl_add_u64 v[220:221], s[44:45], 0, v[152:153]
	s_add_i32 m0, s46, 0x2000
	s_nop 0
	global_load_lds_dwordx4 v[220:221], off
	v_lshl_add_u64 v[220:221], v[224:225], 0, s[8:9]
	s_mov_b32 m0, s52
	s_nop 0
	global_load_lds_dwordx4 v[220:221], off
	v_lshl_add_u64 v[220:221], v[226:227], 0, s[8:9]
	s_mov_b32 m0, s53
	s_nop 0
	global_load_lds_dwordx4 v[220:221], off
	s_waitcnt vmcnt(8)
	s_waitcnt lgkmcnt(0)
	s_setprio 1
	s_barrier
	v_mfma_f32_16x16x32_bf16 v[60:63], v[80:83], v[188:191], v[60:63]
	v_mfma_f32_16x16x32_bf16 v[56:59], v[88:91], v[188:191], v[56:59]
	v_mfma_f32_16x16x32_bf16 v[44:47], v[80:83], v[196:199], v[44:47]
	v_mfma_f32_16x16x32_bf16 v[40:43], v[88:91], v[196:199], v[40:43]
	v_mfma_f32_16x16x32_bf16 v[28:31], v[80:83], v[204:207], v[28:31]
	v_mfma_f32_16x16x32_bf16 v[24:27], v[88:91], v[204:207], v[24:27]
	v_mfma_f32_16x16x32_bf16 v[12:15], v[80:83], v[212:215], v[12:15]
	v_mfma_f32_16x16x32_bf16 v[8:11], v[88:91], v[212:215], v[8:11]
	v_mfma_f32_16x16x32_bf16 v[60:63], v[84:87], v[192:195], v[60:63]
	v_mfma_f32_16x16x32_bf16 v[56:59], v[92:95], v[192:195], v[56:59]
	v_mfma_f32_16x16x32_bf16 v[44:47], v[84:87], v[200:203], v[44:47]
	v_mfma_f32_16x16x32_bf16 v[40:43], v[92:95], v[200:203], v[40:43]
	v_mfma_f32_16x16x32_bf16 v[28:31], v[84:87], v[208:211], v[28:31]
	v_mfma_f32_16x16x32_bf16 v[24:27], v[92:95], v[208:211], v[24:27]
	v_mfma_f32_16x16x32_bf16 v[12:15], v[84:87], v[216:219], v[12:15]
	v_mfma_f32_16x16x32_bf16 v[8:11], v[92:95], v[216:219], v[8:11]
	s_setprio 0
	s_setprio 1
	v_mfma_f32_16x16x32_bf16 v[52:55], v[164:167], v[188:191], v[52:55]
	v_mfma_f32_16x16x32_bf16 v[48:51], v[180:183], v[188:191], v[48:51]
	v_mfma_f32_16x16x32_bf16 v[36:39], v[164:167], v[196:199], v[36:39]
	v_mfma_f32_16x16x32_bf16 v[32:35], v[180:183], v[196:199], v[32:35]
	v_mfma_f32_16x16x32_bf16 v[20:23], v[164:167], v[204:207], v[20:23]
	v_mfma_f32_16x16x32_bf16 v[16:19], v[180:183], v[204:207], v[16:19]
	v_mfma_f32_16x16x32_bf16 v[4:7], v[164:167], v[212:215], v[4:7]
	v_mfma_f32_16x16x32_bf16 v[0:3], v[180:183], v[212:215], v[0:3]
	v_mfma_f32_16x16x32_bf16 v[52:55], v[176:179], v[192:195], v[52:55]
	v_mfma_f32_16x16x32_bf16 v[48:51], v[184:187], v[192:195], v[48:51]
	v_mfma_f32_16x16x32_bf16 v[36:39], v[176:179], v[200:203], v[36:39]
	v_mfma_f32_16x16x32_bf16 v[32:35], v[184:187], v[200:203], v[32:35]
	v_mfma_f32_16x16x32_bf16 v[20:23], v[176:179], v[208:211], v[20:23]
	v_mfma_f32_16x16x32_bf16 v[16:19], v[184:187], v[208:211], v[16:19]
	s_setprio 2
	s_barrier
	v_mfma_f32_16x16x32_bf16 v[4:7], v[176:179], v[216:219], v[4:7]
	v_mfma_f32_16x16x32_bf16 v[0:3], v[184:187], v[216:219], v[0:3]
	s_setprio 0
	s_add_i32 s64, s64, 2
	s_add_u32 s42, s42, 0x100
	s_addc_u32 s43, s43, 0
	s_add_u32 s62, s62, 0x100
	s_addc_u32 s63, s63, 0
	s_cmp_gt_u32 s64, 29
	s_cbranch_scc0 .LBB0_1142
	s_and_b64 vcc, exec, s[10:11]
	s_cbranch_vccz .LBB0_1145
	s_barrier

; #define PG8_STAGE(bufoff, gbase, voff) do { _Pragma("unroll") for (int _i = 0; _i < 2; ++_i) \
;         __builtin_amdgcn_global_load_lds((const unsigned*)((const char*)(gbase) + (voff)[_i]), (PG8_LAS unsigned*)(lds + (bufoff) + ldsw + _i * 8192), 16, 0, 0); } while (0)
; #define PG8_LDA(dst, b, h) do { _Pragma("unroll") for (int m = 0; m < 4; ++m) _Pragma("unroll") for (int k = 0; k < 2; ++k) dst[m][k] = *(const PG8_LAS bf16x8*)(lds + PG8_SA(b, h) + aoff + m * 2048 + k * 1024); } while (0)
; #define PG8_LDB(dst, b, h) do { _Pragma("unroll") for (int n = 0; n < 2; ++n) _Pragma("unroll") for (int k = 0; k < 2; ++k) dst[n][k] = *(const PG8_LAS bf16x8*)(lds + PG8_SB(b, h) + boff + n * 2048 + k * 1024); } while (0)
; #define PG8_MMA(ai, bj, At, Bt) do { __builtin_amdgcn_s_setprio(1); _Pragma("unroll") for (int m = 0; m < 4; ++m) _Pragma("unroll") for (int n = 0; n < 2; ++n) _Pragma("unroll") for (int k = 0; k < 2; ++k) \
;         acc[ai][bj][m][n] = __builtin_amdgcn_mfma_f32_16x16x32_bf16(Bt[n][k], At[m][k], acc[ai][bj][m][n], 0, 0, 0); __builtin_amdgcn_s_setprio(0); } while (0)
; #define PG8_WAIT_V(n) asm volatile("s_waitcnt vmcnt(" #n ")" ::: "memory")
; #define PG8_WAIT_L(n) asm volatile("s_waitcnt lgkmcnt(" #n ")" ::: "memory")
; #define PG8_BAR __builtin_amdgcn_s_barrier()
; #define PG8_SCHED __builtin_amdgcn_sched_barrier(0)
; template <class Epi, class Sched, bool ALIGN_EPI = false, bool SP2 = false>
; __device__ __forceinline__ void gemm_phase(PG8_LAS unsigned char* lds, const Gemm g, const Sched& S, const Epi& E) {
;     ...
;         for (int t = 0; t < nt; t += 2) {
;             const bool last = (t == nt - 2);
;             const char* a1 = cA + (size_t)(t + 1) * kstep;
;             const char* a2 = last ? nA : cA + (size_t)(t + 2) * kstep; const char* b2 = last ? nB : cB + (size_t)(t + 2) * kstep;
;             const char* a3 = a2 + kstep; const char* b3 = b2 + kstep;
;             if constexpr (SP2) {
;             PG8_LDB(B0, 0, 0); PG8_LDB(B1, 0, 1); PG8_SCHED; PG8_LDA(At, 0, 0); PG8_STAGE(PG8_SA(1, 1), a1 + hstep, voffA);
;             PG8_WAIT_V(8); PG8_WAIT_L(0); PG8_BAR; PG8_MMA(0, 0, At, B0); PG8_MMA(0, 1, At, B1); PG8_BAR; PG8_SCHED;
;             PG8_LDA(At, 0, 1); PG8_STAGE(PG8_SB(0, 0), b2, voffB); PG8_STAGE(PG8_SB(0, 1), b2 + hstep, voffB); PG8_STAGE(PG8_SA(0, 0), a2, voffA);
.LBB0_1219:
	ds_read_b128 v[128:131], v167
	ds_read_b128 v[132:135], v167 offset:1024
	ds_read_b128 v[154:157], v167 offset:2048
	ds_read_b128 v[158:161], v167 offset:3072
	ds_read_b128 v[170:173], v168
	ds_read_b128 v[174:177], v168 offset:1024
	ds_read_b128 v[178:181], v168 offset:2048
	ds_read_b128 v[182:185], v168 offset:3072
	s_add_u32 s42, s40, 0xffe00080
	s_addc_u32 s43, s41, -1
	s_cmpk_eq_i32 s63, 0x7c
	s_cselect_b32 s45, s15, s43
	s_cselect_b32 s44, s59, s42
	s_cselect_b32 s43, s13, s62
	s_cselect_b32 s42, s60, s61
	v_lshl_add_u64 v[162:163], s[40:41], 0, v[144:145]
	s_add_i32 m0, s39, 0xc000
	ds_read_b128 v[186:189], v169
	ds_read_b128 v[190:193], v169 offset:1024
	ds_read_b128 v[194:197], v169 offset:2048
	ds_read_b128 v[198:201], v169 offset:3072
	ds_read_b128 v[202:205], v169 offset:4096
	ds_read_b128 v[206:209], v169 offset:5120
	ds_read_b128 v[210:213], v169 offset:6144
	ds_read_b128 v[214:217], v169 offset:7168
	global_load_lds_dwordx4 v[162:163], off
	v_lshl_add_u64 v[162:163], s[40:41], 0, v[148:149]
	s_add_i32 m0, s39, 0xe000
	s_nop 0
	global_load_lds_dwordx4 v[162:163], off
	s_waitcnt vmcnt(8)
	s_waitcnt lgkmcnt(0)
	s_setprio 1
	s_barrier
	v_mfma_f32_16x16x32_bf16 v[124:127], v[128:131], v[186:189], v[124:127]
	v_mfma_f32_16x16x32_bf16 v[120:123], v[154:157], v[186:189], v[120:123]
	v_mfma_f32_16x16x32_bf16 v[116:119], v[128:131], v[194:197], v[116:119]
	v_mfma_f32_16x16x32_bf16 v[112:115], v[154:157], v[194:197], v[112:115]
	v_mfma_f32_16x16x32_bf16 v[108:111], v[128:131], v[202:205], v[108:111]
	v_mfma_f32_16x16x32_bf16 v[104:107], v[154:157], v[202:205], v[104:107]
	v_mfma_f32_16x16x32_bf16 v[100:103], v[128:131], v[210:213], v[100:103]
	v_mfma_f32_16x16x32_bf16 v[96:99], v[154:157], v[210:213], v[96:99]
	v_mfma_f32_16x16x32_bf16 v[124:127], v[132:135], v[190:193], v[124:127]
	v_mfma_f32_16x16x32_bf16 v[120:123], v[158:161], v[190:193], v[120:123]
	v_mfma_f32_16x16x32_bf16 v[116:119], v[132:135], v[198:201], v[116:119]
	v_mfma_f32_16x16x32_bf16 v[112:115], v[158:161], v[198:201], v[112:115]
	v_mfma_f32_16x16x32_bf16 v[108:111], v[132:135], v[206:209], v[108:111]
	v_mfma_f32_16x16x32_bf16 v[104:107], v[158:161], v[206:209], v[104:107]
	v_mfma_f32_16x16x32_bf16 v[100:103], v[132:135], v[214:217], v[100:103]
	v_mfma_f32_16x16x32_bf16 v[96:99], v[158:161], v[214:217], v[96:99]
	s_setprio 0
	s_setprio 1
	v_mfma_f32_16x16x32_bf16 v[68:71], v[170:173], v[186:189], v[68:71]
	v_mfma_f32_16x16x32_bf16 v[60:63], v[178:181], v[186:189], v[60:63]
	v_mfma_f32_16x16x32_bf16 v[52:55], v[170:173], v[194:197], v[52:55]
	v_mfma_f32_16x16x32_bf16 v[48:51], v[178:181], v[194:197], v[48:51]
	v_mfma_f32_16x16x32_bf16 v[44:47], v[170:173], v[202:205], v[44:47]
	v_mfma_f32_16x16x32_bf16 v[40:43], v[178:181], v[202:205], v[40:43]
	v_mfma_f32_16x16x32_bf16 v[36:39], v[170:173], v[210:213], v[36:39]
	v_mfma_f32_16x16x32_bf16 v[32:35], v[178:181], v[210:213], v[32:35]
	v_mfma_f32_16x16x32_bf16 v[68:71], v[174:177], v[190:193], v[68:71]
	v_mfma_f32_16x16x32_bf16 v[60:63], v[182:185], v[190:193], v[60:63]
	v_mfma_f32_16x16x32_bf16 v[52:55], v[174:177], v[198:201], v[52:55]
	v_mfma_f32_16x16x32_bf16 v[48:51], v[182:185], v[198:201], v[48:51]
	v_mfma_f32_16x16x32_bf16 v[44:47], v[174:177], v[206:209], v[44:47]
	v_mfma_f32_16x16x32_bf16 v[40:43], v[182:185], v[206:209], v[40:43]
	s_setprio 2
	s_barrier
	v_mfma_f32_16x16x32_bf16 v[36:39], v[174:177], v[214:217], v[36:39]
	v_mfma_f32_16x16x32_bf16 v[32:35], v[182:185], v[214:217], v[32:35]
	s_setprio 0
	s_add_i32 s64, s56, s33
	v_lshl_add_u64 v[162:163], s[42:43], 0, v[138:139]
	s_mov_b32 m0, s64
	ds_read_b128 v[186:189], v169 offset:16384
	ds_read_b128 v[190:193], v169 offset:17408
	ds_read_b128 v[194:197], v169 offset:18432
	ds_read_b128 v[198:201], v169 offset:19456
	ds_read_b128 v[202:205], v169 offset:20480
	ds_read_b128 v[206:209], v169 offset:21504
	ds_read_b128 v[210:213], v169 offset:22528
	ds_read_b128 v[214:217], v169 offset:23552
	global_load_lds_dwordx4 v[162:163], off
	s_add_i32 m0, s64, 0x2000
	s_add_u32 s64, s42, 0x200000
	v_lshl_add_u64 v[218:219], s[42:43], 0, v[142:143]
	s_addc_u32 s65, s43, 0
	s_add_i32 s66, s57, s33
	global_load_lds_dwordx4 v[218:219], off
	v_lshl_add_u64 v[220:221], s[64:65], 0, v[138:139]
	s_mov_b32 m0, s66
	v_lshl_add_u64 v[222:223], s[44:45], 0, v[140:141]
	global_load_lds_dwordx4 v[220:221], off
	v_lshl_add_u64 v[220:221], s[64:65], 0, v[142:143]
	s_add_i32 m0, s66, 0x2000
	s_nop 0
	global_load_lds_dwordx4 v[220:221], off
	v_lshl_add_u64 v[220:221], s[44:45], 0, v[136:137]
	s_mov_b32 m0, s39
	s_nop 0
	global_load_lds_dwordx4 v[220:221], off
	s_mov_b32 m0, s46
	s_nop 0
	global_load_lds_dwordx4 v[222:223], off
	s_waitcnt vmcnt(8)
	s_waitcnt lgkmcnt(0)
	s_setprio 1
	s_barrier
; #define PG8_STAGE(bufoff, gbase, voff) do { _Pragma("unroll") for (int _i = 0; _i < 2; ++_i) \
;         __builtin_amdgcn_global_load_lds((const unsigned*)((const char*)(gbase) + (voff)[_i]), (PG8_LAS unsigned*)(lds + (bufoff) + ldsw + _i * 8192), 16, 0, 0); } while (0)
; #define PG8_LDA(dst, b, h) do { _Pragma("unroll") for (int m = 0; m < 4; ++m) _Pragma("unroll") for (int k = 0; k < 2; ++k) dst[m][k] = *(const PG8_LAS bf16x8*)(lds + PG8_SA(b, h) + aoff + m * 2048 + k * 1024); } while (0)
; #define PG8_LDB(dst, b, h) do { _Pragma("unroll") for (int n = 0; n < 2; ++n) _Pragma("unroll") for (int k = 0; k < 2; ++k) dst[n][k] = *(const PG8_LAS bf16x8*)(lds + PG8_SB(b, h) + boff + n * 2048 + k * 1024); } while (0)
; #define PG8_MMA(ai, bj, At, Bt) do { __builtin_amdgcn_s_setprio(1); _Pragma("unroll") for (int m = 0; m < 4; ++m) _Pragma("unroll") for (int n = 0; n < 2; ++n) _Pragma("unroll") for (int k = 0; k < 2; ++k) \
;         acc[ai][bj][m][n] = __builtin_amdgcn_mfma_f32_16x16x32_bf16(Bt[n][k], At[m][k], acc[ai][bj][m][n], 0, 0, 0); __builtin_amdgcn_s_setprio(0); } while (0)
; #define PG8_WAIT_V(n) asm volatile("s_waitcnt vmcnt(" #n ")" ::: "memory")
; #define PG8_WAIT_L(n) asm volatile("s_waitcnt lgkmcnt(" #n ")" ::: "memory")
; #define PG8_BAR __builtin_amdgcn_s_barrier()
; #define PG8_SCHED __builtin_amdgcn_sched_barrier(0)
; template <class Epi, class Sched, bool ALIGN_EPI = false, bool SP2 = false>
; __device__ __forceinline__ void gemm_phase(PG8_LAS unsigned char* lds, const Gemm g, const Sched& S, const Epi& E) {
;     ...
;             PG8_WAIT_V(8); PG8_WAIT_L(0); PG8_BAR; PG8_MMA(1, 0, At, B0); PG8_MMA(1, 1, At, B1); PG8_BAR; PG8_SCHED;
;             PG8_LDB(B0, 1, 0); PG8_LDB(B1, 1, 1); PG8_SCHED; PG8_LDA(At, 1, 0); PG8_STAGE(PG8_SA(0, 1), a2 + hstep, voffA);
;             PG8_WAIT_V(8); PG8_WAIT_L(0); PG8_BAR; PG8_MMA(0, 0, At, B0); PG8_MMA(0, 1, At, B1); PG8_BAR; PG8_SCHED;
	v_mfma_f32_16x16x32_bf16 v[92:95], v[128:131], v[186:189], v[92:95]
	v_mfma_f32_16x16x32_bf16 v[88:91], v[154:157], v[186:189], v[88:91]
	v_mfma_f32_16x16x32_bf16 v[84:87], v[128:131], v[194:197], v[84:87]
	v_mfma_f32_16x16x32_bf16 v[80:83], v[154:157], v[194:197], v[80:83]
	v_mfma_f32_16x16x32_bf16 v[76:79], v[128:131], v[202:205], v[76:79]
	v_mfma_f32_16x16x32_bf16 v[72:75], v[154:157], v[202:205], v[72:75]
	v_mfma_f32_16x16x32_bf16 v[64:67], v[128:131], v[210:213], v[64:67]
	v_mfma_f32_16x16x32_bf16 v[56:59], v[154:157], v[210:213], v[56:59]
	v_mfma_f32_16x16x32_bf16 v[92:95], v[132:135], v[190:193], v[92:95]
	v_mfma_f32_16x16x32_bf16 v[88:91], v[158:161], v[190:193], v[88:91]
	v_mfma_f32_16x16x32_bf16 v[84:87], v[132:135], v[198:201], v[84:87]
	v_mfma_f32_16x16x32_bf16 v[80:83], v[158:161], v[198:201], v[80:83]
	v_mfma_f32_16x16x32_bf16 v[76:79], v[132:135], v[206:209], v[76:79]
	v_mfma_f32_16x16x32_bf16 v[72:75], v[158:161], v[206:209], v[72:75]
	v_mfma_f32_16x16x32_bf16 v[64:67], v[132:135], v[214:217], v[64:67]
	v_mfma_f32_16x16x32_bf16 v[56:59], v[158:161], v[214:217], v[56:59]
	s_setprio 0
	s_setprio 1
	v_mfma_f32_16x16x32_bf16 v[28:31], v[170:173], v[186:189], v[28:31]
	v_mfma_f32_16x16x32_bf16 v[24:27], v[178:181], v[186:189], v[24:27]
	v_mfma_f32_16x16x32_bf16 v[20:23], v[170:173], v[194:197], v[20:23]
	v_mfma_f32_16x16x32_bf16 v[16:19], v[178:181], v[194:197], v[16:19]
	v_mfma_f32_16x16x32_bf16 v[12:15], v[170:173], v[202:205], v[12:15]
	v_mfma_f32_16x16x32_bf16 v[8:11], v[178:181], v[202:205], v[8:11]
	v_mfma_f32_16x16x32_bf16 v[4:7], v[170:173], v[210:213], v[4:7]
	v_mfma_f32_16x16x32_bf16 v[0:3], v[178:181], v[210:213], v[0:3]
	v_mfma_f32_16x16x32_bf16 v[28:31], v[174:177], v[190:193], v[28:31]
	v_mfma_f32_16x16x32_bf16 v[24:27], v[182:185], v[190:193], v[24:27]
	v_mfma_f32_16x16x32_bf16 v[20:23], v[174:177], v[198:201], v[20:23]
	v_mfma_f32_16x16x32_bf16 v[16:19], v[182:185], v[198:201], v[16:19]
	v_mfma_f32_16x16x32_bf16 v[12:15], v[174:177], v[206:209], v[12:15]
	v_mfma_f32_16x16x32_bf16 v[8:11], v[182:185], v[206:209], v[8:11]
	s_setprio 2
	s_barrier
	v_mfma_f32_16x16x32_bf16 v[4:7], v[174:177], v[214:217], v[4:7]
	v_mfma_f32_16x16x32_bf16 v[0:3], v[182:185], v[214:217], v[0:3]
	s_setprio 0
	s_add_i32 s64, 0, 0x18000
	s_add_i32 s65, 0, 0x1c000
	v_add_u32_e32 v158, s64, v165
	v_add_u32_e32 v182, s65, v165
	ds_read_b128 v[128:131], v158
	ds_read_b128 v[132:135], v158 offset:1024
	ds_read_b128 v[154:157], v158 offset:2048
	ds_read_b128 v[158:161], v158 offset:3072
	ds_read_b128 v[170:173], v182
	ds_read_b128 v[174:177], v182 offset:1024
	ds_read_b128 v[178:181], v182 offset:2048
	ds_read_b128 v[182:185], v182 offset:3072
	s_add_u32 s44, s44, 0x200000
	s_addc_u32 s45, s45, 0
	s_mov_b32 m0, s47
	v_lshl_add_u64 v[224:225], s[44:45], 0, v[136:137]
	ds_read_b128 v[186:189], v169 offset:32768
	ds_read_b128 v[190:193], v169 offset:33792
	ds_read_b128 v[194:197], v169 offset:34816
	ds_read_b128 v[198:201], v169 offset:35840
	ds_read_b128 v[202:205], v169 offset:36864
	ds_read_b128 v[206:209], v169 offset:37888
	ds_read_b128 v[210:213], v169 offset:38912
	ds_read_b128 v[214:217], v169 offset:39936
	global_load_lds_dwordx4 v[224:225], off
	v_lshl_add_u64 v[224:225], s[44:45], 0, v[140:141]
	s_mov_b32 m0, s48
	s_nop 0
	global_load_lds_dwordx4 v[224:225], off
	s_waitcnt vmcnt(8)
	s_waitcnt lgkmcnt(0)
	s_setprio 1
	s_barrier
	v_mfma_f32_16x16x32_bf16 v[124:127], v[128:131], v[186:189], v[124:127]
	v_mfma_f32_16x16x32_bf16 v[120:123], v[154:157], v[186:189], v[120:123]
	v_mfma_f32_16x16x32_bf16 v[116:119], v[128:131], v[194:197], v[116:119]
	v_mfma_f32_16x16x32_bf16 v[112:115], v[154:157], v[194:197], v[112:115]
	v_mfma_f32_16x16x32_bf16 v[108:111], v[128:131], v[202:205], v[108:111]
	v_mfma_f32_16x16x32_bf16 v[104:107], v[154:157], v[202:205], v[104:107]
	v_mfma_f32_16x16x32_bf16 v[100:103], v[128:131], v[210:213], v[100:103]
	v_mfma_f32_16x16x32_bf16 v[96:99], v[154:157], v[210:213], v[96:99]
	v_mfma_f32_16x16x32_bf16 v[124:127], v[132:135], v[190:193], v[124:127]
	v_mfma_f32_16x16x32_bf16 v[120:123], v[158:161], v[190:193], v[120:123]
	v_mfma_f32_16x16x32_bf16 v[116:119], v[132:135], v[198:201], v[116:119]
	v_mfma_f32_16x16x32_bf16 v[112:115], v[158:161], v[198:201], v[112:115]
	v_mfma_f32_16x16x32_bf16 v[108:111], v[132:135], v[206:209], v[108:111]
	v_mfma_f32_16x16x32_bf16 v[104:107], v[158:161], v[206:209], v[104:107]
	v_mfma_f32_16x16x32_bf16 v[100:103], v[132:135], v[214:217], v[100:103]
	v_mfma_f32_16x16x32_bf16 v[96:99], v[158:161], v[214:217], v[96:99]
	s_setprio 0
	s_setprio 1
	v_mfma_f32_16x16x32_bf16 v[68:71], v[170:173], v[186:189], v[68:71]
	v_mfma_f32_16x16x32_bf16 v[60:63], v[178:181], v[186:189], v[60:63]
	v_mfma_f32_16x16x32_bf16 v[52:55], v[170:173], v[194:197], v[52:55]
	v_mfma_f32_16x16x32_bf16 v[48:51], v[178:181], v[194:197], v[48:51]
	v_mfma_f32_16x16x32_bf16 v[44:47], v[170:173], v[202:205], v[44:47]
	v_mfma_f32_16x16x32_bf16 v[40:43], v[178:181], v[202:205], v[40:43]
	v_mfma_f32_16x16x32_bf16 v[36:39], v[170:173], v[210:213], v[36:39]
	v_mfma_f32_16x16x32_bf16 v[32:35], v[178:181], v[210:213], v[32:35]
	v_mfma_f32_16x16x32_bf16 v[68:71], v[174:177], v[190:193], v[68:71]
	v_mfma_f32_16x16x32_bf16 v[60:63], v[182:185], v[190:193], v[60:63]
	v_mfma_f32_16x16x32_bf16 v[52:55], v[174:177], v[198:201], v[52:55]
	v_mfma_f32_16x16x32_bf16 v[48:51], v[182:185], v[198:201], v[48:51]
	v_mfma_f32_16x16x32_bf16 v[44:47], v[174:177], v[206:209], v[44:47]
	v_mfma_f32_16x16x32_bf16 v[40:43], v[182:185], v[206:209], v[40:43]
	s_setprio 2
	s_barrier
; #define PG8_STAGE(bufoff, gbase, voff) do { _Pragma("unroll") for (int _i = 0; _i < 2; ++_i) \
;         __builtin_amdgcn_global_load_lds((const unsigned*)((const char*)(gbase) + (voff)[_i]), (PG8_LAS unsigned*)(lds + (bufoff) + ldsw + _i * 8192), 16, 0, 0); } while (0)
; #define PG8_LDA(dst, b, h) do { _Pragma("unroll") for (int m = 0; m < 4; ++m) _Pragma("unroll") for (int k = 0; k < 2; ++k) dst[m][k] = *(const PG8_LAS bf16x8*)(lds + PG8_SA(b, h) + aoff + m * 2048 + k * 1024); } while (0)
; #define PG8_MMA(ai, bj, At, Bt) do { __builtin_amdgcn_s_setprio(1); _Pragma("unroll") for (int m = 0; m < 4; ++m) _Pragma("unroll") for (int n = 0; n < 2; ++n) _Pragma("unroll") for (int k = 0; k < 2; ++k) \
;         acc[ai][bj][m][n] = __builtin_amdgcn_mfma_f32_16x16x32_bf16(Bt[n][k], At[m][k], acc[ai][bj][m][n], 0, 0, 0); __builtin_amdgcn_s_setprio(0); } while (0)
; #define PG8_WAIT_V(n) asm volatile("s_waitcnt vmcnt(" #n ")" ::: "memory")
; #define PG8_WAIT_L(n) asm volatile("s_waitcnt lgkmcnt(" #n ")" ::: "memory")
; #define PG8_BAR __builtin_amdgcn_s_barrier()
; #define PG8_SCHED __builtin_amdgcn_sched_barrier(0)
; template <class Epi, class Sched, bool ALIGN_EPI = false, bool SP2 = false>
; __device__ __forceinline__ void gemm_phase(PG8_LAS unsigned char* lds, const Gemm g, const Sched& S, const Epi& E) {
;     ...
;             PG8_WAIT_V(8); PG8_WAIT_L(0); PG8_BAR; PG8_MMA(0, 0, At, B0); PG8_MMA(0, 1, At, B1); PG8_BAR; PG8_SCHED;
;             PG8_LDA(At, 1, 1); PG8_STAGE(PG8_SB(1, 0), b3, voffB); PG8_STAGE(PG8_SB(1, 1), b3 + hstep, voffB); PG8_STAGE(PG8_SA(1, 0), a3, voffA);
;             PG8_WAIT_V(8); PG8_WAIT_L(0); PG8_BAR; PG8_MMA(1, 0, At, B0); PG8_MMA(1, 1, At, B1); PG8_BAR; PG8_SCHED;
;     ...
;         if constexpr (ALIGN_EPI) { if (wr == 0) PG8_BAR; }
	v_mfma_f32_16x16x32_bf16 v[36:39], v[174:177], v[214:217], v[36:39]
	v_mfma_f32_16x16x32_bf16 v[32:35], v[182:185], v[214:217], v[32:35]
	s_setprio 0
	s_add_i32 s44, s64, s33
	v_lshl_add_u64 v[162:163], v[162:163], 0, s[8:9]
	s_mov_b32 m0, s44
	ds_read_b128 v[186:189], v169 offset:49152
	ds_read_b128 v[190:193], v169 offset:50176
	ds_read_b128 v[194:197], v169 offset:51200
	ds_read_b128 v[198:201], v169 offset:52224
	ds_read_b128 v[202:205], v169 offset:53248
	ds_read_b128 v[206:209], v169 offset:54272
	ds_read_b128 v[210:213], v169 offset:55296
	ds_read_b128 v[214:217], v169 offset:56320
	global_load_lds_dwordx4 v[162:163], off
	s_add_i32 m0, s44, 0x2000
	s_add_u32 s42, s42, 0x200080
	v_lshl_add_u64 v[162:163], v[218:219], 0, s[8:9]
	s_addc_u32 s43, s43, 0
	s_add_i32 s44, s65, s33
	global_load_lds_dwordx4 v[162:163], off
	v_lshl_add_u64 v[162:163], s[42:43], 0, v[138:139]
	s_mov_b32 m0, s44
	s_nop 0
	global_load_lds_dwordx4 v[162:163], off
	v_lshl_add_u64 v[162:163], s[42:43], 0, v[142:143]
	s_add_i32 m0, s44, 0x2000
	s_nop 0
	global_load_lds_dwordx4 v[162:163], off
	v_lshl_add_u64 v[162:163], v[220:221], 0, s[8:9]
	s_mov_b32 m0, s52
	s_nop 0
	global_load_lds_dwordx4 v[162:163], off
	v_lshl_add_u64 v[162:163], v[222:223], 0, s[8:9]
	s_mov_b32 m0, s53
	s_nop 0
	global_load_lds_dwordx4 v[162:163], off
	s_waitcnt vmcnt(8)
	s_waitcnt lgkmcnt(0)
	s_setprio 1
	s_barrier
	v_mfma_f32_16x16x32_bf16 v[92:95], v[128:131], v[186:189], v[92:95]
	v_mfma_f32_16x16x32_bf16 v[88:91], v[154:157], v[186:189], v[88:91]
	v_mfma_f32_16x16x32_bf16 v[84:87], v[128:131], v[194:197], v[84:87]
	v_mfma_f32_16x16x32_bf16 v[80:83], v[154:157], v[194:197], v[80:83]
	v_mfma_f32_16x16x32_bf16 v[76:79], v[128:131], v[202:205], v[76:79]
	v_mfma_f32_16x16x32_bf16 v[72:75], v[154:157], v[202:205], v[72:75]
	v_mfma_f32_16x16x32_bf16 v[64:67], v[128:131], v[210:213], v[64:67]
	v_mfma_f32_16x16x32_bf16 v[56:59], v[154:157], v[210:213], v[56:59]
	v_mfma_f32_16x16x32_bf16 v[92:95], v[132:135], v[190:193], v[92:95]
	v_mfma_f32_16x16x32_bf16 v[88:91], v[158:161], v[190:193], v[88:91]
	v_mfma_f32_16x16x32_bf16 v[84:87], v[132:135], v[198:201], v[84:87]
	v_mfma_f32_16x16x32_bf16 v[80:83], v[158:161], v[198:201], v[80:83]
	v_mfma_f32_16x16x32_bf16 v[76:79], v[132:135], v[206:209], v[76:79]
	v_mfma_f32_16x16x32_bf16 v[72:75], v[158:161], v[206:209], v[72:75]
	v_mfma_f32_16x16x32_bf16 v[64:67], v[132:135], v[214:217], v[64:67]
	v_mfma_f32_16x16x32_bf16 v[56:59], v[158:161], v[214:217], v[56:59]
	s_setprio 0
	s_setprio 1
	v_mfma_f32_16x16x32_bf16 v[28:31], v[170:173], v[186:189], v[28:31]
	v_mfma_f32_16x16x32_bf16 v[24:27], v[178:181], v[186:189], v[24:27]
	v_mfma_f32_16x16x32_bf16 v[20:23], v[170:173], v[194:197], v[20:23]
	v_mfma_f32_16x16x32_bf16 v[16:19], v[178:181], v[194:197], v[16:19]
	v_mfma_f32_16x16x32_bf16 v[12:15], v[170:173], v[202:205], v[12:15]
	v_mfma_f32_16x16x32_bf16 v[8:11], v[178:181], v[202:205], v[8:11]
	v_mfma_f32_16x16x32_bf16 v[4:7], v[170:173], v[210:213], v[4:7]
	v_mfma_f32_16x16x32_bf16 v[0:3], v[178:181], v[210:213], v[0:3]
	v_mfma_f32_16x16x32_bf16 v[28:31], v[174:177], v[190:193], v[28:31]
	v_mfma_f32_16x16x32_bf16 v[24:27], v[182:185], v[190:193], v[24:27]
	v_mfma_f32_16x16x32_bf16 v[20:23], v[174:177], v[198:201], v[20:23]
	v_mfma_f32_16x16x32_bf16 v[16:19], v[182:185], v[198:201], v[16:19]
	v_mfma_f32_16x16x32_bf16 v[12:15], v[174:177], v[206:209], v[12:15]
	v_mfma_f32_16x16x32_bf16 v[8:11], v[182:185], v[206:209], v[8:11]
	s_setprio 2
	s_barrier
	v_mfma_f32_16x16x32_bf16 v[4:7], v[174:177], v[214:217], v[4:7]
	v_mfma_f32_16x16x32_bf16 v[0:3], v[182:185], v[214:217], v[0:3]
	s_setprio 0
	s_add_i32 s63, s63, 2
	s_add_u32 s40, s40, 0x100
	s_addc_u32 s41, s41, 0
	s_add_u32 s61, s61, 0x100
	s_addc_u32 s62, s62, 0
	s_cmpk_gt_u32 s63, 0x7d
	s_cbranch_scc0 .LBB0_1219
	s_and_b64 vcc, exec, s[10:11]
	s_cbranch_vccz .LBB0_1222
	s_barrier
